# GEMM K-loops: loop bookkeeping moved in front of the loop-back barrier (only the branch remains after it)
# baseline (speedup 1.0000x reference)
;     __host__ __device__ bool next(int i, Unit& u) const { const long L = (long)i * G + c; if (L >= maxL) return false; return unit_of(L, u); }
;     __device__ __forceinline__ const char* a_base(const Gemm& g, const Unit& u, size_t tstep) const { return (const char*)g.A + (size_t)u.pm * tstep; }
;     __device__ __forceinline__ const char* b_base(const Gemm& g, const Unit& u, size_t tstep) const { return (const char*)g.Bt + (size_t)u.pn * tstep; }
; #define PG8_STAGE(bufoff, gbase, voff) do { _Pragma("unroll") for (int _i = 0; _i < 2; ++_i) \
;         __builtin_amdgcn_global_load_lds((const unsigned*)((const char*)(gbase) + (voff)[_i]), (PG8_LAS unsigned*)(lds + (bufoff) + ldsw + _i * 8192), 16, 0, 0); } while (0)
; #define PG8_LDA(dst, b, h) do { _Pragma("unroll") for (int m = 0; m < 4; ++m) _Pragma("unroll") for (int k = 0; k < 2; ++k) dst[m][k] = *(const PG8_LAS bf16x8*)(lds + PG8_SA(b, h) + aoff + m * 2048 + k * 1024); } while (0)
; #define PG8_WAIT_V(n) asm volatile("s_waitcnt vmcnt(" #n ")" ::: "memory")
; #define PG8_BAR __builtin_amdgcn_s_barrier()
; template <class Epi, class Sched, bool ALIGN_EPI = false, bool SP2 = false>
; __device__ __forceinline__ void gemm_phase(PG8_LAS unsigned char* lds, const Gemm g, const Sched& S, const Epi& E, const int wave_id_in) {
;     ...
;         const bool has_next = S.next(ui + 1, nxt);
;         const char* nA = has_next ? S.a_base(g, nxt, tstep) : cA; const char* nB = has_next ? S.b_base(g, nxt, tstep) : cB;
;         for (int t = 0; t < nt; t += 2) {
;             const bool last = (t == nt - 2);
;             const char* a1 = cA + (size_t)(t + 1) * kstep;
;             const char* a2 = last ? nA : cA + (size_t)(t + 2) * kstep; const char* b2 = last ? nB : cB + (size_t)(t + 2) * kstep;
;             const char* a3 = a2 + kstep; const char* b3 = b2 + kstep;
;             if (last && has_next) S.a_ready(nxt);
;             if constexpr (SP2) {
;             PG8_LDB(B0, 0, 0); PG8_LDB(B1, 0, 1); PG8_SCHED; PG8_LDA(At, 0, 0); PG8_STAGE(PG8_SA(1, 1), a1 + hstep, voffA);
;             PG8_WAIT_V(8); PG8_WAIT_L(0); PG8_BAR; __builtin_amdgcn_s_setprio(1); PG8_MMA(0, 0, At, B0); PG8_MMA(0, 1, At, B1); __builtin_amdgcn_s_setprio(0); PG8_BAR; PG8_SCHED;
;             PG8_LDA(At, 0, 1); PG8_STAGE(PG8_SB(0, 0), b2, voffB); PG8_STAGE(PG8_SB(0, 1), b2 + hstep, voffB); PG8_STAGE(PG8_SA(0, 0), a2, voffA);
.LBB0_131:
	s_ashr_i32 s57, s56, 31
	s_lshl_b64 s[38:39], s[56:57], 20
	s_add_u32 s60, s47, s38
	s_addc_u32 s61, s49, s39
	s_and_b64 s[38:39], s[58:59], exec
	s_cselect_b32 s25, s61, s7
	s_cselect_b32 s26, s60, s6
	s_ashr_i32 s55, s54, 31
	s_lshl_b64 s[38:39], s[54:55], 20
	s_add_u32 s62, s75, s38
	s_addc_u32 s63, s78, s39
	s_and_b64 s[38:39], s[58:59], exec
	s_cselect_b32 s38, s63, s69
	s_cselect_b32 s39, s62, s68
	s_add_u32 s6, s6, 0x80080
	s_addc_u32 s7, s7, 0
	s_add_u32 s42, s68, 0x100
	s_addc_u32 s43, s69, 0
	s_mov_b32 s55, -2
	ds_read_b128 v[128:131], v221
	ds_read_b128 v[132:135], v221 offset:1024
	ds_read_b128 v[136:139], v221 offset:2048
	ds_read_b128 v[140:143], v221 offset:3072
	ds_read_b128 v[144:147], v222
	ds_read_b128 v[148:151], v222 offset:1024
	ds_read_b128 v[152:155], v222 offset:2048
	ds_read_b128 v[156:159], v222 offset:3072
	s_add_u32 s40, s6, 0xfff80080
	s_addc_u32 s41, s7, -1
	s_cmp_eq_u32 s55, 28
	s_cselect_b32 s71, s25, s41
	s_cselect_b32 s70, s26, s40
	s_cselect_b32 s69, s38, s43
	s_cselect_b32 s68, s39, s42
	v_lshl_add_u64 v[192:193], s[6:7], 0, v[206:207]
	s_add_i32 m0, s65, 0xc000
	ds_read_b128 v[160:163], v223
	ds_read_b128 v[164:167], v223 offset:1024
	ds_read_b128 v[168:171], v223 offset:2048
	ds_read_b128 v[172:175], v223 offset:3072
	ds_read_b128 v[176:179], v223 offset:4096
	ds_read_b128 v[180:183], v223 offset:5120
	ds_read_b128 v[184:187], v223 offset:6144
	ds_read_b128 v[188:191], v223 offset:7168
	global_load_lds_dwordx4 v[192:193], off
	v_lshl_add_u64 v[192:193], s[6:7], 0, v[208:209]
	s_add_i32 m0, s65, 0xe000
	s_nop 0
	global_load_lds_dwordx4 v[192:193], off
	s_waitcnt vmcnt(8)
	s_waitcnt lgkmcnt(0)
	s_barrier
	v_mfma_f32_16x16x32_bf16 v[124:127], v[128:131], v[160:163], 0
	v_mfma_f32_16x16x32_bf16 v[120:123], v[136:139], v[160:163], 0
	v_mfma_f32_16x16x32_bf16 v[108:111], v[128:131], v[168:171], 0
	v_mfma_f32_16x16x32_bf16 v[104:107], v[136:139], v[168:171], 0
	v_mfma_f32_16x16x32_bf16 v[92:95], v[128:131], v[176:179], 0
	v_mfma_f32_16x16x32_bf16 v[88:91], v[136:139], v[176:179], 0
	v_mfma_f32_16x16x32_bf16 v[76:79], v[128:131], v[184:187], 0
	v_mfma_f32_16x16x32_bf16 v[72:75], v[136:139], v[184:187], 0
	v_mfma_f32_16x16x32_bf16 v[116:119], v[144:147], v[160:163], 0
	v_mfma_f32_16x16x32_bf16 v[112:115], v[152:155], v[160:163], 0
	v_mfma_f32_16x16x32_bf16 v[100:103], v[144:147], v[168:171], 0
	v_mfma_f32_16x16x32_bf16 v[96:99], v[152:155], v[168:171], 0
	v_mfma_f32_16x16x32_bf16 v[84:87], v[144:147], v[176:179], 0
	v_mfma_f32_16x16x32_bf16 v[80:83], v[152:155], v[176:179], 0
	v_mfma_f32_16x16x32_bf16 v[68:71], v[144:147], v[184:187], 0
	v_mfma_f32_16x16x32_bf16 v[64:67], v[152:155], v[184:187], 0
	v_mfma_f32_16x16x32_bf16 v[124:127], v[132:135], v[164:167], v[124:127]
	v_mfma_f32_16x16x32_bf16 v[120:123], v[140:143], v[164:167], v[120:123]
	v_mfma_f32_16x16x32_bf16 v[108:111], v[132:135], v[172:175], v[108:111]
	v_mfma_f32_16x16x32_bf16 v[104:107], v[140:143], v[172:175], v[104:107]
	v_mfma_f32_16x16x32_bf16 v[92:95], v[132:135], v[180:183], v[92:95]
	v_mfma_f32_16x16x32_bf16 v[88:91], v[140:143], v[180:183], v[88:91]
	v_mfma_f32_16x16x32_bf16 v[76:79], v[132:135], v[188:191], v[76:79]
	v_mfma_f32_16x16x32_bf16 v[72:75], v[140:143], v[188:191], v[72:75]
	v_mfma_f32_16x16x32_bf16 v[116:119], v[148:151], v[164:167], v[116:119]
	v_mfma_f32_16x16x32_bf16 v[112:115], v[156:159], v[164:167], v[112:115]
	v_mfma_f32_16x16x32_bf16 v[100:103], v[148:151], v[172:175], v[100:103]
	v_mfma_f32_16x16x32_bf16 v[96:99], v[156:159], v[172:175], v[96:99]
	v_mfma_f32_16x16x32_bf16 v[84:87], v[148:151], v[180:183], v[84:87]
	v_mfma_f32_16x16x32_bf16 v[80:83], v[156:159], v[180:183], v[80:83]
	v_mfma_f32_16x16x32_bf16 v[68:71], v[148:151], v[188:191], v[68:71]
	v_mfma_f32_16x16x32_bf16 v[64:67], v[156:159], v[188:191], v[64:67]
	s_barrier
	s_add_i32 s40, s93, s80
	v_lshl_add_u64 v[192:193], s[68:69], 0, v[200:201]
	s_mov_b32 m0, s40
	ds_read_b128 v[160:163], v223 offset:16384
	ds_read_b128 v[164:167], v223 offset:17408
	ds_read_b128 v[168:171], v223 offset:18432
	ds_read_b128 v[172:175], v223 offset:19456
	ds_read_b128 v[176:179], v223 offset:20480
	ds_read_b128 v[180:183], v223 offset:21504
	ds_read_b128 v[184:187], v223 offset:22528
	ds_read_b128 v[188:191], v223 offset:23552
	global_load_lds_dwordx4 v[192:193], off
	s_add_i32 m0, s40, 0x2000
	s_add_u32 s72, s68, 0x80000
	v_lshl_add_u64 v[194:195], s[68:69], 0, v[202:203]
	s_addc_u32 s73, s69, 0
	s_add_i32 s40, s94, s80
	global_load_lds_dwordx4 v[194:195], off
	v_lshl_add_u64 v[196:197], s[72:73], 0, v[200:201]
	s_mov_b32 m0, s40
	v_lshl_add_u64 v[198:199], s[70:71], 0, v[202:203]
	global_load_lds_dwordx4 v[196:197], off
	v_lshl_add_u64 v[196:197], s[72:73], 0, v[202:203]
	s_add_i32 m0, s40, 0x2000
	s_nop 0
	global_load_lds_dwordx4 v[196:197], off
	v_lshl_add_u64 v[196:197], s[70:71], 0, v[200:201]
	s_mov_b32 m0, s65
	s_nop 0
	global_load_lds_dwordx4 v[196:197], off
	s_mov_b32 m0, s67
	s_nop 0
	global_load_lds_dwordx4 v[198:199], off
	s_waitcnt vmcnt(8)
	s_waitcnt lgkmcnt(0)
	s_barrier
; #define PG8_STAGE(bufoff, gbase, voff) do { _Pragma("unroll") for (int _i = 0; _i < 2; ++_i) \
;         __builtin_amdgcn_global_load_lds((const unsigned*)((const char*)(gbase) + (voff)[_i]), (PG8_LAS unsigned*)(lds + (bufoff) + ldsw + _i * 8192), 16, 0, 0); } while (0)
; #define PG8_LDA(dst, b, h) do { _Pragma("unroll") for (int m = 0; m < 4; ++m) _Pragma("unroll") for (int k = 0; k < 2; ++k) dst[m][k] = *(const PG8_LAS bf16x8*)(lds + PG8_SA(b, h) + aoff + m * 2048 + k * 1024); } while (0)
; #define PG8_LDB(dst, b, h) do { _Pragma("unroll") for (int n = 0; n < 2; ++n) _Pragma("unroll") for (int k = 0; k < 2; ++k) dst[n][k] = *(const PG8_LAS bf16x8*)(lds + PG8_SB(b, h) + boff + n * 2048 + k * 1024); } while (0)
; #define PG8_MMA(ai, bj, At, Bt) do { _Pragma("unroll") for (int m = 0; m < 4; ++m) _Pragma("unroll") for (int n = 0; n < 2; ++n) _Pragma("unroll") for (int k = 0; k < 2; ++k) \
;         acc[ai][bj][m][n] = __builtin_amdgcn_mfma_f32_16x16x32_bf16(Bt[n][k], At[m][k], acc[ai][bj][m][n], 0, 0, 0); } while (0)
; #define PG8_WAIT_V(n) asm volatile("s_waitcnt vmcnt(" #n ")" ::: "memory")
; #define PG8_WAIT_L(n) asm volatile("s_waitcnt lgkmcnt(" #n ")" ::: "memory")
; #define PG8_BAR __builtin_amdgcn_s_barrier()
; #define PG8_SCHED __builtin_amdgcn_sched_barrier(0)
; template <class Epi, class Sched, bool ALIGN_EPI = false, bool SP2 = false>
; __device__ __forceinline__ void gemm_phase(PG8_LAS unsigned char* lds, const Gemm g, const Sched& S, const Epi& E, const int wave_id_in) {
;     ...
;             PG8_WAIT_V(8); PG8_WAIT_L(0); PG8_BAR; __builtin_amdgcn_s_setprio(1); PG8_MMA(1, 0, At, B0); PG8_MMA(1, 1, At, B1); __builtin_amdgcn_s_setprio(0); PG8_BAR; PG8_SCHED;
;             PG8_LDB(B0, 1, 0); PG8_LDB(B1, 1, 1); PG8_SCHED; PG8_LDA(At, 1, 0); PG8_STAGE(PG8_SA(0, 1), a2 + hstep, voffA);
;             PG8_WAIT_V(8); PG8_WAIT_L(0); PG8_BAR; __builtin_amdgcn_s_setprio(1); PG8_MMA(0, 0, At, B0); PG8_MMA(0, 1, At, B1); __builtin_amdgcn_s_setprio(0); PG8_BAR; PG8_SCHED;
	v_mfma_f32_16x16x32_bf16 v[60:63], v[128:131], v[160:163], 0
	v_mfma_f32_16x16x32_bf16 v[56:59], v[136:139], v[160:163], 0
	v_mfma_f32_16x16x32_bf16 v[44:47], v[128:131], v[168:171], 0
	v_mfma_f32_16x16x32_bf16 v[40:43], v[136:139], v[168:171], 0
	v_mfma_f32_16x16x32_bf16 v[28:31], v[128:131], v[176:179], 0
	v_mfma_f32_16x16x32_bf16 v[24:27], v[136:139], v[176:179], 0
	v_mfma_f32_16x16x32_bf16 v[12:15], v[128:131], v[184:187], 0
	v_mfma_f32_16x16x32_bf16 v[8:11], v[136:139], v[184:187], 0
	v_mfma_f32_16x16x32_bf16 v[52:55], v[144:147], v[160:163], 0
	v_mfma_f32_16x16x32_bf16 v[48:51], v[152:155], v[160:163], 0
	v_mfma_f32_16x16x32_bf16 v[36:39], v[144:147], v[168:171], 0
	v_mfma_f32_16x16x32_bf16 v[32:35], v[152:155], v[168:171], 0
	v_mfma_f32_16x16x32_bf16 v[20:23], v[144:147], v[176:179], 0
	v_mfma_f32_16x16x32_bf16 v[16:19], v[152:155], v[176:179], 0
	v_mfma_f32_16x16x32_bf16 v[4:7], v[144:147], v[184:187], 0
	v_mfma_f32_16x16x32_bf16 v[0:3], v[152:155], v[184:187], 0
	v_mfma_f32_16x16x32_bf16 v[60:63], v[132:135], v[164:167], v[60:63]
	v_mfma_f32_16x16x32_bf16 v[56:59], v[140:143], v[164:167], v[56:59]
	v_mfma_f32_16x16x32_bf16 v[44:47], v[132:135], v[172:175], v[44:47]
	v_mfma_f32_16x16x32_bf16 v[40:43], v[140:143], v[172:175], v[40:43]
	v_mfma_f32_16x16x32_bf16 v[28:31], v[132:135], v[180:183], v[28:31]
	v_mfma_f32_16x16x32_bf16 v[24:27], v[140:143], v[180:183], v[24:27]
	v_mfma_f32_16x16x32_bf16 v[12:15], v[132:135], v[188:191], v[12:15]
	v_mfma_f32_16x16x32_bf16 v[8:11], v[140:143], v[188:191], v[8:11]
	v_mfma_f32_16x16x32_bf16 v[52:55], v[148:151], v[164:167], v[52:55]
	v_mfma_f32_16x16x32_bf16 v[48:51], v[156:159], v[164:167], v[48:51]
	v_mfma_f32_16x16x32_bf16 v[36:39], v[148:151], v[172:175], v[36:39]
	v_mfma_f32_16x16x32_bf16 v[32:35], v[156:159], v[172:175], v[32:35]
	v_mfma_f32_16x16x32_bf16 v[20:23], v[148:151], v[180:183], v[20:23]
	v_mfma_f32_16x16x32_bf16 v[16:19], v[156:159], v[180:183], v[16:19]
	v_mfma_f32_16x16x32_bf16 v[4:7], v[148:151], v[188:191], v[4:7]
	v_mfma_f32_16x16x32_bf16 v[0:3], v[156:159], v[188:191], v[0:3]
	s_barrier
	s_add_i32 s40, 0, 0x18000
	s_add_i32 s41, 0, 0x1c000
	v_add_u32_e32 v140, s40, v220
	v_add_u32_e32 v156, s41, v220
	ds_read_b128 v[128:131], v140
	ds_read_b128 v[132:135], v140 offset:1024
	ds_read_b128 v[136:139], v140 offset:2048
	ds_read_b128 v[140:143], v140 offset:3072
	ds_read_b128 v[144:147], v156
	ds_read_b128 v[148:151], v156 offset:1024
	ds_read_b128 v[152:155], v156 offset:2048
	ds_read_b128 v[156:159], v156 offset:3072
	s_add_u32 s70, s70, 0x80000
	s_addc_u32 s71, s71, 0
	s_mov_b32 m0, s81
	v_lshl_add_u64 v[214:215], s[70:71], 0, v[200:201]
	ds_read_b128 v[160:163], v223 offset:32768
	ds_read_b128 v[164:167], v223 offset:33792
	ds_read_b128 v[168:171], v223 offset:34816
	ds_read_b128 v[172:175], v223 offset:35840
	ds_read_b128 v[176:179], v223 offset:36864
	ds_read_b128 v[180:183], v223 offset:37888
	ds_read_b128 v[184:187], v223 offset:38912
	ds_read_b128 v[188:191], v223 offset:39936
	global_load_lds_dwordx4 v[214:215], off
	v_lshl_add_u64 v[214:215], s[70:71], 0, v[202:203]
	s_mov_b32 m0, s82
	s_nop 0
	global_load_lds_dwordx4 v[214:215], off
	s_waitcnt vmcnt(8)
	s_waitcnt lgkmcnt(0)
	s_barrier
	v_mfma_f32_16x16x32_bf16 v[124:127], v[128:131], v[160:163], v[124:127]
	v_mfma_f32_16x16x32_bf16 v[120:123], v[136:139], v[160:163], v[120:123]
	v_mfma_f32_16x16x32_bf16 v[108:111], v[128:131], v[168:171], v[108:111]
	v_mfma_f32_16x16x32_bf16 v[104:107], v[136:139], v[168:171], v[104:107]
	v_mfma_f32_16x16x32_bf16 v[92:95], v[128:131], v[176:179], v[92:95]
	v_mfma_f32_16x16x32_bf16 v[88:91], v[136:139], v[176:179], v[88:91]
	v_mfma_f32_16x16x32_bf16 v[76:79], v[128:131], v[184:187], v[76:79]
	v_mfma_f32_16x16x32_bf16 v[72:75], v[136:139], v[184:187], v[72:75]
	v_mfma_f32_16x16x32_bf16 v[116:119], v[144:147], v[160:163], v[116:119]
	v_mfma_f32_16x16x32_bf16 v[112:115], v[152:155], v[160:163], v[112:115]
	v_mfma_f32_16x16x32_bf16 v[100:103], v[144:147], v[168:171], v[100:103]
	v_mfma_f32_16x16x32_bf16 v[96:99], v[152:155], v[168:171], v[96:99]
	v_mfma_f32_16x16x32_bf16 v[84:87], v[144:147], v[176:179], v[84:87]
	v_mfma_f32_16x16x32_bf16 v[80:83], v[152:155], v[176:179], v[80:83]
	v_mfma_f32_16x16x32_bf16 v[68:71], v[144:147], v[184:187], v[68:71]
	v_mfma_f32_16x16x32_bf16 v[64:67], v[152:155], v[184:187], v[64:67]
	v_mfma_f32_16x16x32_bf16 v[124:127], v[132:135], v[164:167], v[124:127]
	v_mfma_f32_16x16x32_bf16 v[120:123], v[140:143], v[164:167], v[120:123]
	v_mfma_f32_16x16x32_bf16 v[108:111], v[132:135], v[172:175], v[108:111]
	v_mfma_f32_16x16x32_bf16 v[104:107], v[140:143], v[172:175], v[104:107]
	v_mfma_f32_16x16x32_bf16 v[92:95], v[132:135], v[180:183], v[92:95]
	v_mfma_f32_16x16x32_bf16 v[88:91], v[140:143], v[180:183], v[88:91]
	v_mfma_f32_16x16x32_bf16 v[76:79], v[132:135], v[188:191], v[76:79]
	v_mfma_f32_16x16x32_bf16 v[72:75], v[140:143], v[188:191], v[72:75]
	v_mfma_f32_16x16x32_bf16 v[116:119], v[148:151], v[164:167], v[116:119]
	v_mfma_f32_16x16x32_bf16 v[112:115], v[156:159], v[164:167], v[112:115]
	v_mfma_f32_16x16x32_bf16 v[100:103], v[148:151], v[172:175], v[100:103]
	v_mfma_f32_16x16x32_bf16 v[96:99], v[156:159], v[172:175], v[96:99]
	v_mfma_f32_16x16x32_bf16 v[84:87], v[148:151], v[180:183], v[84:87]
	v_mfma_f32_16x16x32_bf16 v[80:83], v[156:159], v[180:183], v[80:83]
	v_mfma_f32_16x16x32_bf16 v[68:71], v[148:151], v[188:191], v[68:71]
	v_mfma_f32_16x16x32_bf16 v[64:67], v[156:159], v[188:191], v[64:67]
	s_barrier
; #define PG8_STAGE(bufoff, gbase, voff) do { _Pragma("unroll") for (int _i = 0; _i < 2; ++_i) \
;         __builtin_amdgcn_global_load_lds((const unsigned*)((const char*)(gbase) + (voff)[_i]), (PG8_LAS unsigned*)(lds + (bufoff) + ldsw + _i * 8192), 16, 0, 0); } while (0)
; #define PG8_LDA(dst, b, h) do { _Pragma("unroll") for (int m = 0; m < 4; ++m) _Pragma("unroll") for (int k = 0; k < 2; ++k) dst[m][k] = *(const PG8_LAS bf16x8*)(lds + PG8_SA(b, h) + aoff + m * 2048 + k * 1024); } while (0)
; #define PG8_LDB(dst, b, h) do { _Pragma("unroll") for (int n = 0; n < 2; ++n) _Pragma("unroll") for (int k = 0; k < 2; ++k) dst[n][k] = *(const PG8_LAS bf16x8*)(lds + PG8_SB(b, h) + boff + n * 2048 + k * 1024); } while (0)
; #define PG8_MMA(ai, bj, At, Bt) do { _Pragma("unroll") for (int m = 0; m < 4; ++m) _Pragma("unroll") for (int n = 0; n < 2; ++n) _Pragma("unroll") for (int k = 0; k < 2; ++k) \
;         acc[ai][bj][m][n] = __builtin_amdgcn_mfma_f32_16x16x32_bf16(Bt[n][k], At[m][k], acc[ai][bj][m][n], 0, 0, 0); } while (0)
; #define PG8_WAIT_V(n) asm volatile("s_waitcnt vmcnt(" #n ")" ::: "memory")
; #define PG8_WAIT_L(n) asm volatile("s_waitcnt lgkmcnt(" #n ")" ::: "memory")
; #define PG8_BAR __builtin_amdgcn_s_barrier()
; #define PG8_SCHED __builtin_amdgcn_sched_barrier(0)
; template <class Epi, class Sched, bool ALIGN_EPI = false, bool SP2 = false>
; __device__ __forceinline__ void gemm_phase(PG8_LAS unsigned char* lds, const Gemm g, const Sched& S, const Epi& E, const int wave_id_in) {
;     ...
;             PG8_LDB(B0, 0, 0); PG8_LDB(B1, 0, 1); PG8_SCHED; PG8_LDA(At, 0, 0); PG8_STAGE(PG8_SA(1, 1), a1 + hstep, voffA);
;             PG8_WAIT_V(8); PG8_WAIT_L(0); PG8_BAR; __builtin_amdgcn_s_setprio(1); PG8_MMA(0, 0, At, B0); PG8_MMA(0, 1, At, B1); __builtin_amdgcn_s_setprio(0); PG8_BAR; PG8_SCHED;
;     ...
;             PG8_LDA(At, 1, 1); PG8_STAGE(PG8_SB(1, 0), b3, voffB); PG8_STAGE(PG8_SB(1, 1), b3 + hstep, voffB); PG8_STAGE(PG8_SA(1, 0), a3, voffA);
;             PG8_WAIT_V(8); PG8_WAIT_L(0); PG8_BAR; __builtin_amdgcn_s_setprio(1); PG8_MMA(1, 0, At, B0); PG8_MMA(1, 1, At, B1); __builtin_amdgcn_s_setprio(0); PG8_BAR; PG8_SCHED;
	s_add_i32 s40, s40, s80
	v_lshl_add_u64 v[192:193], v[192:193], 0, s[30:31]
	s_mov_b32 m0, s40
	ds_read_b128 v[160:163], v223 offset:49152
	ds_read_b128 v[164:167], v223 offset:50176
	ds_read_b128 v[168:171], v223 offset:51200
	ds_read_b128 v[172:175], v223 offset:52224
	ds_read_b128 v[176:179], v223 offset:53248
	ds_read_b128 v[180:183], v223 offset:54272
	ds_read_b128 v[184:187], v223 offset:55296
	ds_read_b128 v[188:191], v223 offset:56320
	global_load_lds_dwordx4 v[192:193], off
	s_add_i32 m0, s40, 0x2000
	s_add_u32 s68, s68, 0x80080
	v_lshl_add_u64 v[192:193], v[194:195], 0, s[30:31]
	s_addc_u32 s69, s69, 0
	s_add_i32 s40, s41, s80
	global_load_lds_dwordx4 v[192:193], off
	v_lshl_add_u64 v[192:193], s[68:69], 0, v[200:201]
	s_mov_b32 m0, s40
	s_nop 0
	global_load_lds_dwordx4 v[192:193], off
	v_lshl_add_u64 v[192:193], s[68:69], 0, v[202:203]
	s_add_i32 m0, s40, 0x2000
	s_nop 0
	global_load_lds_dwordx4 v[192:193], off
	v_lshl_add_u64 v[192:193], v[196:197], 0, s[30:31]
	s_mov_b32 m0, s86
	s_nop 0
	global_load_lds_dwordx4 v[192:193], off
	v_lshl_add_u64 v[192:193], v[198:199], 0, s[30:31]
	s_mov_b32 m0, s87
	s_nop 0
	global_load_lds_dwordx4 v[192:193], off
	s_waitcnt vmcnt(8)
	s_waitcnt lgkmcnt(0)
	s_barrier
	v_mfma_f32_16x16x32_bf16 v[60:63], v[128:131], v[160:163], v[60:63]
	v_mfma_f32_16x16x32_bf16 v[56:59], v[136:139], v[160:163], v[56:59]
	v_mfma_f32_16x16x32_bf16 v[44:47], v[128:131], v[168:171], v[44:47]
	v_mfma_f32_16x16x32_bf16 v[40:43], v[136:139], v[168:171], v[40:43]
	v_mfma_f32_16x16x32_bf16 v[28:31], v[128:131], v[176:179], v[28:31]
	v_mfma_f32_16x16x32_bf16 v[24:27], v[136:139], v[176:179], v[24:27]
	v_mfma_f32_16x16x32_bf16 v[12:15], v[128:131], v[184:187], v[12:15]
	v_mfma_f32_16x16x32_bf16 v[8:11], v[136:139], v[184:187], v[8:11]
	v_mfma_f32_16x16x32_bf16 v[52:55], v[144:147], v[160:163], v[52:55]
	v_mfma_f32_16x16x32_bf16 v[48:51], v[152:155], v[160:163], v[48:51]
	v_mfma_f32_16x16x32_bf16 v[36:39], v[144:147], v[168:171], v[36:39]
	v_mfma_f32_16x16x32_bf16 v[32:35], v[152:155], v[168:171], v[32:35]
	v_mfma_f32_16x16x32_bf16 v[20:23], v[144:147], v[176:179], v[20:23]
	v_mfma_f32_16x16x32_bf16 v[16:19], v[152:155], v[176:179], v[16:19]
	v_mfma_f32_16x16x32_bf16 v[4:7], v[144:147], v[184:187], v[4:7]
	v_mfma_f32_16x16x32_bf16 v[0:3], v[152:155], v[184:187], v[0:3]
	v_mfma_f32_16x16x32_bf16 v[60:63], v[132:135], v[164:167], v[60:63]
	v_mfma_f32_16x16x32_bf16 v[56:59], v[140:143], v[164:167], v[56:59]
	v_mfma_f32_16x16x32_bf16 v[44:47], v[132:135], v[172:175], v[44:47]
	v_mfma_f32_16x16x32_bf16 v[40:43], v[140:143], v[172:175], v[40:43]
	v_mfma_f32_16x16x32_bf16 v[28:31], v[132:135], v[180:183], v[28:31]
	v_mfma_f32_16x16x32_bf16 v[24:27], v[140:143], v[180:183], v[24:27]
	v_mfma_f32_16x16x32_bf16 v[12:15], v[132:135], v[188:191], v[12:15]
	v_mfma_f32_16x16x32_bf16 v[8:11], v[140:143], v[188:191], v[8:11]
	v_mfma_f32_16x16x32_bf16 v[52:55], v[148:151], v[164:167], v[52:55]
	v_mfma_f32_16x16x32_bf16 v[48:51], v[156:159], v[164:167], v[48:51]
	v_mfma_f32_16x16x32_bf16 v[36:39], v[148:151], v[172:175], v[36:39]
	v_mfma_f32_16x16x32_bf16 v[32:35], v[156:159], v[172:175], v[32:35]
	v_mfma_f32_16x16x32_bf16 v[20:23], v[148:151], v[180:183], v[20:23]
	v_mfma_f32_16x16x32_bf16 v[16:19], v[156:159], v[180:183], v[16:19]
	v_mfma_f32_16x16x32_bf16 v[4:7], v[148:151], v[188:191], v[4:7]
	v_mfma_f32_16x16x32_bf16 v[0:3], v[156:159], v[188:191], v[0:3]
	s_add_i32 s55, s55, 2
	s_add_u32 s6, s6, 0x100
	s_addc_u32 s7, s7, 0
	s_add_u32 s42, s42, 0x100
	s_addc_u32 s43, s43, 0
	s_cmp_gt_u32 s55, 29
	s_barrier
	s_cbranch_scc0 .LBB0_132
	s_branch .Lpeel_exit_inproj
.LBB0_132:
	ds_read_b128 v[128:131], v221
	ds_read_b128 v[132:135], v221 offset:1024
	ds_read_b128 v[136:139], v221 offset:2048
	ds_read_b128 v[140:143], v221 offset:3072
	ds_read_b128 v[144:147], v222
	ds_read_b128 v[148:151], v222 offset:1024
	ds_read_b128 v[152:155], v222 offset:2048
	ds_read_b128 v[156:159], v222 offset:3072
	s_add_u32 s40, s6, 0xfff80080
	s_addc_u32 s41, s7, -1
	s_cmp_eq_u32 s55, 28
	s_cselect_b32 s71, s25, s41
	s_cselect_b32 s70, s26, s40
	s_cselect_b32 s69, s38, s43
	s_cselect_b32 s68, s39, s42
	v_lshl_add_u64 v[192:193], s[6:7], 0, v[206:207]
	s_add_i32 m0, s65, 0xc000
	ds_read_b128 v[160:163], v223
	ds_read_b128 v[164:167], v223 offset:1024
	ds_read_b128 v[168:171], v223 offset:2048
	ds_read_b128 v[172:175], v223 offset:3072
	ds_read_b128 v[176:179], v223 offset:4096
	ds_read_b128 v[180:183], v223 offset:5120
	ds_read_b128 v[184:187], v223 offset:6144
	ds_read_b128 v[188:191], v223 offset:7168
	global_load_lds_dwordx4 v[192:193], off
	v_lshl_add_u64 v[192:193], s[6:7], 0, v[208:209]
	s_add_i32 m0, s65, 0xe000
	s_nop 0
	global_load_lds_dwordx4 v[192:193], off
	s_waitcnt vmcnt(8)
	s_waitcnt lgkmcnt(0)
	s_barrier
; #define PG8_STAGE(bufoff, gbase, voff) do { _Pragma("unroll") for (int _i = 0; _i < 2; ++_i) \
;         __builtin_amdgcn_global_load_lds((const unsigned*)((const char*)(gbase) + (voff)[_i]), (PG8_LAS unsigned*)(lds + (bufoff) + ldsw + _i * 8192), 16, 0, 0); } while (0)
; #define PG8_LDA(dst, b, h) do { _Pragma("unroll") for (int m = 0; m < 4; ++m) _Pragma("unroll") for (int k = 0; k < 2; ++k) dst[m][k] = *(const PG8_LAS bf16x8*)(lds + PG8_SA(b, h) + aoff + m * 2048 + k * 1024); } while (0)
; #define PG8_MMA(ai, bj, At, Bt) do { _Pragma("unroll") for (int m = 0; m < 4; ++m) _Pragma("unroll") for (int n = 0; n < 2; ++n) _Pragma("unroll") for (int k = 0; k < 2; ++k) \
;         acc[ai][bj][m][n] = __builtin_amdgcn_mfma_f32_16x16x32_bf16(Bt[n][k], At[m][k], acc[ai][bj][m][n], 0, 0, 0); } while (0)
; #define PG8_WAIT_V(n) asm volatile("s_waitcnt vmcnt(" #n ")" ::: "memory")
; #define PG8_WAIT_L(n) asm volatile("s_waitcnt lgkmcnt(" #n ")" ::: "memory")
; #define PG8_BAR __builtin_amdgcn_s_barrier()
; #define PG8_SCHED __builtin_amdgcn_sched_barrier(0)
; template <class Epi, class Sched, bool ALIGN_EPI = false, bool SP2 = false>
; __device__ __forceinline__ void gemm_phase(PG8_LAS unsigned char* lds, const Gemm g, const Sched& S, const Epi& E, const int wave_id_in) {
;     ...
;             PG8_WAIT_V(8); PG8_WAIT_L(0); PG8_BAR; __builtin_amdgcn_s_setprio(1); PG8_MMA(0, 0, At, B0); PG8_MMA(0, 1, At, B1); __builtin_amdgcn_s_setprio(0); PG8_BAR; PG8_SCHED;
;             PG8_LDA(At, 0, 1); PG8_STAGE(PG8_SB(0, 0), b2, voffB); PG8_STAGE(PG8_SB(0, 1), b2 + hstep, voffB); PG8_STAGE(PG8_SA(0, 0), a2, voffA);
;             PG8_WAIT_V(8); PG8_WAIT_L(0); PG8_BAR; __builtin_amdgcn_s_setprio(1); PG8_MMA(1, 0, At, B0); PG8_MMA(1, 1, At, B1); __builtin_amdgcn_s_setprio(0); PG8_BAR; PG8_SCHED;
	v_mfma_f32_16x16x32_bf16 v[124:127], v[128:131], v[160:163], v[124:127]
	v_mfma_f32_16x16x32_bf16 v[120:123], v[136:139], v[160:163], v[120:123]
	v_mfma_f32_16x16x32_bf16 v[108:111], v[128:131], v[168:171], v[108:111]
	v_mfma_f32_16x16x32_bf16 v[104:107], v[136:139], v[168:171], v[104:107]
	v_mfma_f32_16x16x32_bf16 v[92:95], v[128:131], v[176:179], v[92:95]
	v_mfma_f32_16x16x32_bf16 v[88:91], v[136:139], v[176:179], v[88:91]
	v_mfma_f32_16x16x32_bf16 v[76:79], v[128:131], v[184:187], v[76:79]
	v_mfma_f32_16x16x32_bf16 v[72:75], v[136:139], v[184:187], v[72:75]
	v_mfma_f32_16x16x32_bf16 v[116:119], v[144:147], v[160:163], v[116:119]
	v_mfma_f32_16x16x32_bf16 v[112:115], v[152:155], v[160:163], v[112:115]
	v_mfma_f32_16x16x32_bf16 v[100:103], v[144:147], v[168:171], v[100:103]
	v_mfma_f32_16x16x32_bf16 v[96:99], v[152:155], v[168:171], v[96:99]
	v_mfma_f32_16x16x32_bf16 v[84:87], v[144:147], v[176:179], v[84:87]
	v_mfma_f32_16x16x32_bf16 v[80:83], v[152:155], v[176:179], v[80:83]
	v_mfma_f32_16x16x32_bf16 v[68:71], v[144:147], v[184:187], v[68:71]
	v_mfma_f32_16x16x32_bf16 v[64:67], v[152:155], v[184:187], v[64:67]
	v_mfma_f32_16x16x32_bf16 v[124:127], v[132:135], v[164:167], v[124:127]
	v_mfma_f32_16x16x32_bf16 v[120:123], v[140:143], v[164:167], v[120:123]
	v_mfma_f32_16x16x32_bf16 v[108:111], v[132:135], v[172:175], v[108:111]
	v_mfma_f32_16x16x32_bf16 v[104:107], v[140:143], v[172:175], v[104:107]
	v_mfma_f32_16x16x32_bf16 v[92:95], v[132:135], v[180:183], v[92:95]
	v_mfma_f32_16x16x32_bf16 v[88:91], v[140:143], v[180:183], v[88:91]
	v_mfma_f32_16x16x32_bf16 v[76:79], v[132:135], v[188:191], v[76:79]
	v_mfma_f32_16x16x32_bf16 v[72:75], v[140:143], v[188:191], v[72:75]
	v_mfma_f32_16x16x32_bf16 v[116:119], v[148:151], v[164:167], v[116:119]
	v_mfma_f32_16x16x32_bf16 v[112:115], v[156:159], v[164:167], v[112:115]
	v_mfma_f32_16x16x32_bf16 v[100:103], v[148:151], v[172:175], v[100:103]
	v_mfma_f32_16x16x32_bf16 v[96:99], v[156:159], v[172:175], v[96:99]
	v_mfma_f32_16x16x32_bf16 v[84:87], v[148:151], v[180:183], v[84:87]
	v_mfma_f32_16x16x32_bf16 v[80:83], v[156:159], v[180:183], v[80:83]
	v_mfma_f32_16x16x32_bf16 v[68:71], v[148:151], v[188:191], v[68:71]
	v_mfma_f32_16x16x32_bf16 v[64:67], v[156:159], v[188:191], v[64:67]
	s_barrier
	s_add_i32 s40, s93, s80
	v_lshl_add_u64 v[192:193], s[68:69], 0, v[200:201]
	s_mov_b32 m0, s40
	ds_read_b128 v[160:163], v223 offset:16384
	ds_read_b128 v[164:167], v223 offset:17408
	ds_read_b128 v[168:171], v223 offset:18432
	ds_read_b128 v[172:175], v223 offset:19456
	ds_read_b128 v[176:179], v223 offset:20480
	ds_read_b128 v[180:183], v223 offset:21504
	ds_read_b128 v[184:187], v223 offset:22528
	ds_read_b128 v[188:191], v223 offset:23552
	global_load_lds_dwordx4 v[192:193], off
	s_add_i32 m0, s40, 0x2000
	s_add_u32 s72, s68, 0x80000
	v_lshl_add_u64 v[194:195], s[68:69], 0, v[202:203]
	s_addc_u32 s73, s69, 0
	s_add_i32 s40, s94, s80
	global_load_lds_dwordx4 v[194:195], off
	v_lshl_add_u64 v[196:197], s[72:73], 0, v[200:201]
	s_mov_b32 m0, s40
	v_lshl_add_u64 v[198:199], s[70:71], 0, v[202:203]
	global_load_lds_dwordx4 v[196:197], off
	v_lshl_add_u64 v[196:197], s[72:73], 0, v[202:203]
	s_add_i32 m0, s40, 0x2000
	s_nop 0
	global_load_lds_dwordx4 v[196:197], off
	v_lshl_add_u64 v[196:197], s[70:71], 0, v[200:201]
	s_mov_b32 m0, s65
	s_nop 0
	global_load_lds_dwordx4 v[196:197], off
	s_mov_b32 m0, s67
	s_nop 0
	global_load_lds_dwordx4 v[198:199], off
	s_waitcnt vmcnt(8)
	s_waitcnt lgkmcnt(0)
	s_barrier
	v_mfma_f32_16x16x32_bf16 v[60:63], v[128:131], v[160:163], v[60:63]
	v_mfma_f32_16x16x32_bf16 v[56:59], v[136:139], v[160:163], v[56:59]
	v_mfma_f32_16x16x32_bf16 v[44:47], v[128:131], v[168:171], v[44:47]
	v_mfma_f32_16x16x32_bf16 v[40:43], v[136:139], v[168:171], v[40:43]
	v_mfma_f32_16x16x32_bf16 v[28:31], v[128:131], v[176:179], v[28:31]
	v_mfma_f32_16x16x32_bf16 v[24:27], v[136:139], v[176:179], v[24:27]
	v_mfma_f32_16x16x32_bf16 v[12:15], v[128:131], v[184:187], v[12:15]
	v_mfma_f32_16x16x32_bf16 v[8:11], v[136:139], v[184:187], v[8:11]
	v_mfma_f32_16x16x32_bf16 v[52:55], v[144:147], v[160:163], v[52:55]
	v_mfma_f32_16x16x32_bf16 v[48:51], v[152:155], v[160:163], v[48:51]
	v_mfma_f32_16x16x32_bf16 v[36:39], v[144:147], v[168:171], v[36:39]
	v_mfma_f32_16x16x32_bf16 v[32:35], v[152:155], v[168:171], v[32:35]
	v_mfma_f32_16x16x32_bf16 v[20:23], v[144:147], v[176:179], v[20:23]
	v_mfma_f32_16x16x32_bf16 v[16:19], v[152:155], v[176:179], v[16:19]
	v_mfma_f32_16x16x32_bf16 v[4:7], v[144:147], v[184:187], v[4:7]
	v_mfma_f32_16x16x32_bf16 v[0:3], v[152:155], v[184:187], v[0:3]
	v_mfma_f32_16x16x32_bf16 v[60:63], v[132:135], v[164:167], v[60:63]
	v_mfma_f32_16x16x32_bf16 v[56:59], v[140:143], v[164:167], v[56:59]
	v_mfma_f32_16x16x32_bf16 v[44:47], v[132:135], v[172:175], v[44:47]
	v_mfma_f32_16x16x32_bf16 v[40:43], v[140:143], v[172:175], v[40:43]
	v_mfma_f32_16x16x32_bf16 v[28:31], v[132:135], v[180:183], v[28:31]
	v_mfma_f32_16x16x32_bf16 v[24:27], v[140:143], v[180:183], v[24:27]
	v_mfma_f32_16x16x32_bf16 v[12:15], v[132:135], v[188:191], v[12:15]
	v_mfma_f32_16x16x32_bf16 v[8:11], v[140:143], v[188:191], v[8:11]
	v_mfma_f32_16x16x32_bf16 v[52:55], v[148:151], v[164:167], v[52:55]
	v_mfma_f32_16x16x32_bf16 v[48:51], v[156:159], v[164:167], v[48:51]
	v_mfma_f32_16x16x32_bf16 v[36:39], v[148:151], v[172:175], v[36:39]
	v_mfma_f32_16x16x32_bf16 v[32:35], v[156:159], v[172:175], v[32:35]
	v_mfma_f32_16x16x32_bf16 v[20:23], v[148:151], v[180:183], v[20:23]
	v_mfma_f32_16x16x32_bf16 v[16:19], v[156:159], v[180:183], v[16:19]
	v_mfma_f32_16x16x32_bf16 v[4:7], v[148:151], v[188:191], v[4:7]
	v_mfma_f32_16x16x32_bf16 v[0:3], v[156:159], v[188:191], v[0:3]
	s_barrier
; #define PG8_STAGE(bufoff, gbase, voff) do { _Pragma("unroll") for (int _i = 0; _i < 2; ++_i) \
;         __builtin_amdgcn_global_load_lds((const unsigned*)((const char*)(gbase) + (voff)[_i]), (PG8_LAS unsigned*)(lds + (bufoff) + ldsw + _i * 8192), 16, 0, 0); } while (0)
; #define PG8_LDA(dst, b, h) do { _Pragma("unroll") for (int m = 0; m < 4; ++m) _Pragma("unroll") for (int k = 0; k < 2; ++k) dst[m][k] = *(const PG8_LAS bf16x8*)(lds + PG8_SA(b, h) + aoff + m * 2048 + k * 1024); } while (0)
; #define PG8_LDB(dst, b, h) do { _Pragma("unroll") for (int n = 0; n < 2; ++n) _Pragma("unroll") for (int k = 0; k < 2; ++k) dst[n][k] = *(const PG8_LAS bf16x8*)(lds + PG8_SB(b, h) + boff + n * 2048 + k * 1024); } while (0)
; #define PG8_MMA(ai, bj, At, Bt) do { _Pragma("unroll") for (int m = 0; m < 4; ++m) _Pragma("unroll") for (int n = 0; n < 2; ++n) _Pragma("unroll") for (int k = 0; k < 2; ++k) \
;         acc[ai][bj][m][n] = __builtin_amdgcn_mfma_f32_16x16x32_bf16(Bt[n][k], At[m][k], acc[ai][bj][m][n], 0, 0, 0); } while (0)
; #define PG8_WAIT_V(n) asm volatile("s_waitcnt vmcnt(" #n ")" ::: "memory")
; #define PG8_WAIT_L(n) asm volatile("s_waitcnt lgkmcnt(" #n ")" ::: "memory")
; #define PG8_BAR __builtin_amdgcn_s_barrier()
; #define PG8_SCHED __builtin_amdgcn_sched_barrier(0)
; template <class Epi, class Sched, bool ALIGN_EPI = false, bool SP2 = false>
; __device__ __forceinline__ void gemm_phase(PG8_LAS unsigned char* lds, const Gemm g, const Sched& S, const Epi& E, const int wave_id_in) {
;     ...
;             PG8_LDB(B0, 1, 0); PG8_LDB(B1, 1, 1); PG8_SCHED; PG8_LDA(At, 1, 0); PG8_STAGE(PG8_SA(0, 1), a2 + hstep, voffA);
;             PG8_WAIT_V(8); PG8_WAIT_L(0); PG8_BAR; __builtin_amdgcn_s_setprio(1); PG8_MMA(0, 0, At, B0); PG8_MMA(0, 1, At, B1); __builtin_amdgcn_s_setprio(0); PG8_BAR; PG8_SCHED;
;             PG8_LDA(At, 1, 1); PG8_STAGE(PG8_SB(1, 0), b3, voffB); PG8_STAGE(PG8_SB(1, 1), b3 + hstep, voffB); PG8_STAGE(PG8_SA(1, 0), a3, voffA);
;             PG8_WAIT_V(8); PG8_WAIT_L(0); PG8_BAR; __builtin_amdgcn_s_setprio(1); PG8_MMA(1, 0, At, B0); PG8_MMA(1, 1, At, B1); __builtin_amdgcn_s_setprio(0); PG8_BAR; PG8_SCHED;
	s_add_i32 s40, 0, 0x18000
	s_add_i32 s41, 0, 0x1c000
	v_add_u32_e32 v140, s40, v220
	v_add_u32_e32 v156, s41, v220
	ds_read_b128 v[128:131], v140
	ds_read_b128 v[132:135], v140 offset:1024
	ds_read_b128 v[136:139], v140 offset:2048
	ds_read_b128 v[140:143], v140 offset:3072
	ds_read_b128 v[144:147], v156
	ds_read_b128 v[148:151], v156 offset:1024
	ds_read_b128 v[152:155], v156 offset:2048
	ds_read_b128 v[156:159], v156 offset:3072
	s_add_u32 s70, s70, 0x80000
	s_addc_u32 s71, s71, 0
	s_mov_b32 m0, s81
	v_lshl_add_u64 v[214:215], s[70:71], 0, v[200:201]
	ds_read_b128 v[160:163], v223 offset:32768
	ds_read_b128 v[164:167], v223 offset:33792
	ds_read_b128 v[168:171], v223 offset:34816
	ds_read_b128 v[172:175], v223 offset:35840
	ds_read_b128 v[176:179], v223 offset:36864
	ds_read_b128 v[180:183], v223 offset:37888
	ds_read_b128 v[184:187], v223 offset:38912
	ds_read_b128 v[188:191], v223 offset:39936
	global_load_lds_dwordx4 v[214:215], off
	v_lshl_add_u64 v[214:215], s[70:71], 0, v[202:203]
	s_mov_b32 m0, s82
	s_nop 0
	global_load_lds_dwordx4 v[214:215], off
	s_waitcnt vmcnt(8)
	s_waitcnt lgkmcnt(0)
	s_barrier
	v_mfma_f32_16x16x32_bf16 v[124:127], v[128:131], v[160:163], v[124:127]
	v_mfma_f32_16x16x32_bf16 v[120:123], v[136:139], v[160:163], v[120:123]
	v_mfma_f32_16x16x32_bf16 v[108:111], v[128:131], v[168:171], v[108:111]
	v_mfma_f32_16x16x32_bf16 v[104:107], v[136:139], v[168:171], v[104:107]
	v_mfma_f32_16x16x32_bf16 v[92:95], v[128:131], v[176:179], v[92:95]
	v_mfma_f32_16x16x32_bf16 v[88:91], v[136:139], v[176:179], v[88:91]
	v_mfma_f32_16x16x32_bf16 v[76:79], v[128:131], v[184:187], v[76:79]
	v_mfma_f32_16x16x32_bf16 v[72:75], v[136:139], v[184:187], v[72:75]
	v_mfma_f32_16x16x32_bf16 v[116:119], v[144:147], v[160:163], v[116:119]
	v_mfma_f32_16x16x32_bf16 v[112:115], v[152:155], v[160:163], v[112:115]
	v_mfma_f32_16x16x32_bf16 v[100:103], v[144:147], v[168:171], v[100:103]
	v_mfma_f32_16x16x32_bf16 v[96:99], v[152:155], v[168:171], v[96:99]
	v_mfma_f32_16x16x32_bf16 v[84:87], v[144:147], v[176:179], v[84:87]
	v_mfma_f32_16x16x32_bf16 v[80:83], v[152:155], v[176:179], v[80:83]
	v_mfma_f32_16x16x32_bf16 v[68:71], v[144:147], v[184:187], v[68:71]
	v_mfma_f32_16x16x32_bf16 v[64:67], v[152:155], v[184:187], v[64:67]
	v_mfma_f32_16x16x32_bf16 v[124:127], v[132:135], v[164:167], v[124:127]
	v_mfma_f32_16x16x32_bf16 v[120:123], v[140:143], v[164:167], v[120:123]
	v_mfma_f32_16x16x32_bf16 v[108:111], v[132:135], v[172:175], v[108:111]
	v_mfma_f32_16x16x32_bf16 v[104:107], v[140:143], v[172:175], v[104:107]
	v_mfma_f32_16x16x32_bf16 v[92:95], v[132:135], v[180:183], v[92:95]
	v_mfma_f32_16x16x32_bf16 v[88:91], v[140:143], v[180:183], v[88:91]
	v_mfma_f32_16x16x32_bf16 v[76:79], v[132:135], v[188:191], v[76:79]
	v_mfma_f32_16x16x32_bf16 v[72:75], v[140:143], v[188:191], v[72:75]
	v_mfma_f32_16x16x32_bf16 v[116:119], v[148:151], v[164:167], v[116:119]
	v_mfma_f32_16x16x32_bf16 v[112:115], v[156:159], v[164:167], v[112:115]
	v_mfma_f32_16x16x32_bf16 v[100:103], v[148:151], v[172:175], v[100:103]
	v_mfma_f32_16x16x32_bf16 v[96:99], v[156:159], v[172:175], v[96:99]
	v_mfma_f32_16x16x32_bf16 v[84:87], v[148:151], v[180:183], v[84:87]
	v_mfma_f32_16x16x32_bf16 v[80:83], v[156:159], v[180:183], v[80:83]
	v_mfma_f32_16x16x32_bf16 v[68:71], v[148:151], v[188:191], v[68:71]
	v_mfma_f32_16x16x32_bf16 v[64:67], v[156:159], v[188:191], v[64:67]
	s_barrier
	s_add_i32 s40, s40, s80
	v_lshl_add_u64 v[192:193], v[192:193], 0, s[30:31]
	s_mov_b32 m0, s40
	ds_read_b128 v[160:163], v223 offset:49152
	ds_read_b128 v[164:167], v223 offset:50176
	ds_read_b128 v[168:171], v223 offset:51200
	ds_read_b128 v[172:175], v223 offset:52224
	ds_read_b128 v[176:179], v223 offset:53248
	ds_read_b128 v[180:183], v223 offset:54272
	ds_read_b128 v[184:187], v223 offset:55296
	ds_read_b128 v[188:191], v223 offset:56320
	global_load_lds_dwordx4 v[192:193], off
	s_add_i32 m0, s40, 0x2000
	s_add_u32 s68, s68, 0x80080
	v_lshl_add_u64 v[192:193], v[194:195], 0, s[30:31]
	s_addc_u32 s69, s69, 0
	s_add_i32 s40, s41, s80
	global_load_lds_dwordx4 v[192:193], off
	v_lshl_add_u64 v[192:193], s[68:69], 0, v[200:201]
	s_mov_b32 m0, s40
	s_nop 0
	global_load_lds_dwordx4 v[192:193], off
	v_lshl_add_u64 v[192:193], s[68:69], 0, v[202:203]
	s_add_i32 m0, s40, 0x2000
	s_nop 0
	global_load_lds_dwordx4 v[192:193], off
	v_lshl_add_u64 v[192:193], v[196:197], 0, s[30:31]
	s_mov_b32 m0, s86
	s_nop 0
	global_load_lds_dwordx4 v[192:193], off
	v_lshl_add_u64 v[192:193], v[198:199], 0, s[30:31]
	s_mov_b32 m0, s87
	s_nop 0
	global_load_lds_dwordx4 v[192:193], off
	s_waitcnt vmcnt(8)
	s_waitcnt lgkmcnt(0)
	s_barrier
	v_mfma_f32_16x16x32_bf16 v[60:63], v[128:131], v[160:163], v[60:63]
	v_mfma_f32_16x16x32_bf16 v[56:59], v[136:139], v[160:163], v[56:59]
	v_mfma_f32_16x16x32_bf16 v[44:47], v[128:131], v[168:171], v[44:47]
	v_mfma_f32_16x16x32_bf16 v[40:43], v[136:139], v[168:171], v[40:43]
	v_mfma_f32_16x16x32_bf16 v[28:31], v[128:131], v[176:179], v[28:31]
	v_mfma_f32_16x16x32_bf16 v[24:27], v[136:139], v[176:179], v[24:27]
	v_mfma_f32_16x16x32_bf16 v[12:15], v[128:131], v[184:187], v[12:15]
	v_mfma_f32_16x16x32_bf16 v[8:11], v[136:139], v[184:187], v[8:11]
	v_mfma_f32_16x16x32_bf16 v[52:55], v[144:147], v[160:163], v[52:55]
	v_mfma_f32_16x16x32_bf16 v[48:51], v[152:155], v[160:163], v[48:51]
	v_mfma_f32_16x16x32_bf16 v[36:39], v[144:147], v[168:171], v[36:39]
	v_mfma_f32_16x16x32_bf16 v[32:35], v[152:155], v[168:171], v[32:35]
	v_mfma_f32_16x16x32_bf16 v[20:23], v[144:147], v[176:179], v[20:23]
	v_mfma_f32_16x16x32_bf16 v[16:19], v[152:155], v[176:179], v[16:19]
	v_mfma_f32_16x16x32_bf16 v[4:7], v[144:147], v[184:187], v[4:7]
	v_mfma_f32_16x16x32_bf16 v[0:3], v[152:155], v[184:187], v[0:3]
	v_mfma_f32_16x16x32_bf16 v[60:63], v[132:135], v[164:167], v[60:63]
	v_mfma_f32_16x16x32_bf16 v[56:59], v[140:143], v[164:167], v[56:59]
	v_mfma_f32_16x16x32_bf16 v[44:47], v[132:135], v[172:175], v[44:47]
	v_mfma_f32_16x16x32_bf16 v[40:43], v[140:143], v[172:175], v[40:43]
	v_mfma_f32_16x16x32_bf16 v[28:31], v[132:135], v[180:183], v[28:31]
	v_mfma_f32_16x16x32_bf16 v[24:27], v[140:143], v[180:183], v[24:27]
	v_mfma_f32_16x16x32_bf16 v[12:15], v[132:135], v[188:191], v[12:15]
	v_mfma_f32_16x16x32_bf16 v[8:11], v[140:143], v[188:191], v[8:11]
	v_mfma_f32_16x16x32_bf16 v[52:55], v[148:151], v[164:167], v[52:55]
	v_mfma_f32_16x16x32_bf16 v[48:51], v[156:159], v[164:167], v[48:51]
	v_mfma_f32_16x16x32_bf16 v[36:39], v[148:151], v[172:175], v[36:39]
	v_mfma_f32_16x16x32_bf16 v[32:35], v[156:159], v[172:175], v[32:35]
	v_mfma_f32_16x16x32_bf16 v[20:23], v[148:151], v[180:183], v[20:23]
	v_mfma_f32_16x16x32_bf16 v[16:19], v[156:159], v[180:183], v[16:19]
	v_mfma_f32_16x16x32_bf16 v[4:7], v[148:151], v[188:191], v[4:7]
	v_mfma_f32_16x16x32_bf16 v[0:3], v[156:159], v[188:191], v[0:3]
	s_add_i32 s55, s55, 2
	s_add_u32 s6, s6, 0x100
	s_addc_u32 s7, s7, 0
	s_add_u32 s42, s42, 0x100
	s_addc_u32 s43, s43, 0
	s_cmp_gt_u32 s55, 29
	s_barrier
	s_cbranch_scc0 .LBB0_132

; #define PG8_STAGE(bufoff, gbase, voff) do { _Pragma("unroll") for (int _i = 0; _i < 2; ++_i) \
;         __builtin_amdgcn_global_load_lds((const unsigned*)((const char*)(gbase) + (voff)[_i]), (PG8_LAS unsigned*)(lds + (bufoff) + ldsw + _i * 8192), 16, 0, 0); } while (0)
; #define PG8_LDA(dst, b, h) do { _Pragma("unroll") for (int m = 0; m < 4; ++m) _Pragma("unroll") for (int k = 0; k < 2; ++k) dst[m][k] = *(const PG8_LAS bf16x8*)(lds + PG8_SA(b, h) + aoff + m * 2048 + k * 1024); } while (0)
; #define PG8_LDB(dst, b, h) do { _Pragma("unroll") for (int n = 0; n < 2; ++n) _Pragma("unroll") for (int k = 0; k < 2; ++k) dst[n][k] = *(const PG8_LAS bf16x8*)(lds + PG8_SB(b, h) + boff + n * 2048 + k * 1024); } while (0)
; #define PG8_MMA(ai, bj, At, Bt) do { _Pragma("unroll") for (int m = 0; m < 4; ++m) _Pragma("unroll") for (int n = 0; n < 2; ++n) _Pragma("unroll") for (int k = 0; k < 2; ++k) \
;         acc[ai][bj][m][n] = __builtin_amdgcn_mfma_f32_16x16x32_bf16(Bt[n][k], At[m][k], acc[ai][bj][m][n], 0, 0, 0); } while (0)
; #define PG8_WAIT_V(n) asm volatile("s_waitcnt vmcnt(" #n ")" ::: "memory")
; #define PG8_WAIT_L(n) asm volatile("s_waitcnt lgkmcnt(" #n ")" ::: "memory")
; #define PG8_BAR __builtin_amdgcn_s_barrier()
; #define PG8_SCHED __builtin_amdgcn_sched_barrier(0)
; template <class Epi, class Sched, bool ALIGN_EPI = false, bool SP2 = false>
; __device__ __forceinline__ void gemm_phase(PG8_LAS unsigned char* lds, const Gemm g, const Sched& S, const Epi& E, const int wave_id_in) {
;     ...
;             PG8_LDB(B0, 0, 0); PG8_LDB(B1, 0, 1); PG8_SCHED; PG8_LDA(At, 0, 0); PG8_STAGE(PG8_SA(1, 1), a1 + hstep, voffA);
;             PG8_WAIT_V(8); PG8_WAIT_L(0); PG8_BAR; __builtin_amdgcn_s_setprio(1); PG8_MMA(0, 0, At, B0); PG8_MMA(0, 1, At, B1); __builtin_amdgcn_s_setprio(0); PG8_BAR; PG8_SCHED;
;             PG8_LDA(At, 0, 1); PG8_STAGE(PG8_SB(0, 0), b2, voffB); PG8_STAGE(PG8_SB(0, 1), b2 + hstep, voffB); PG8_STAGE(PG8_SA(0, 0), a2, voffA);
;             PG8_WAIT_V(8); PG8_WAIT_L(0); PG8_BAR; __builtin_amdgcn_s_setprio(1); PG8_MMA(1, 0, At, B0); PG8_MMA(1, 1, At, B1); __builtin_amdgcn_s_setprio(0); PG8_BAR; PG8_SCHED;
.LBB0_680:
	ds_read_b128 v[128:131], v211
	ds_read_b128 v[132:135], v211 offset:1024
	ds_read_b128 v[136:139], v211 offset:2048
	ds_read_b128 v[140:143], v211 offset:3072
	ds_read_b128 v[144:147], v212
	ds_read_b128 v[148:151], v212 offset:1024
	ds_read_b128 v[152:155], v212 offset:2048
	ds_read_b128 v[156:159], v212 offset:3072
	s_add_u32 s40, s36, 0xfff80080
	s_addc_u32 s41, s37, -1
	s_cmp_eq_u32 s64, 28
	s_cselect_b32 s49, s25, s41
	s_cselect_b32 s48, s31, s40
	s_cselect_b32 s47, s23, s63
	s_cselect_b32 s46, s61, s62
	v_lshl_add_u64 v[208:209], s[36:37], 0, v[200:201]
	s_add_i32 m0, s35, 0xc000
	ds_read_b128 v[160:163], v213
	ds_read_b128 v[164:167], v213 offset:1024
	ds_read_b128 v[168:171], v213 offset:2048
	ds_read_b128 v[172:175], v213 offset:3072
	ds_read_b128 v[176:179], v213 offset:4096
	ds_read_b128 v[180:183], v213 offset:5120
	ds_read_b128 v[184:187], v213 offset:6144
	ds_read_b128 v[188:191], v213 offset:7168
	global_load_lds_dwordx4 v[208:209], off
	v_lshl_add_u64 v[208:209], s[36:37], 0, v[202:203]
	s_add_i32 m0, s35, 0xe000
	s_nop 0
	global_load_lds_dwordx4 v[208:209], off
	s_waitcnt vmcnt(8)
	s_waitcnt lgkmcnt(0)
	s_barrier
	v_mfma_f32_16x16x32_bf16 v[124:127], v[128:131], v[160:163], v[124:127]
	v_mfma_f32_16x16x32_bf16 v[120:123], v[136:139], v[160:163], v[120:123]
	v_mfma_f32_16x16x32_bf16 v[116:119], v[128:131], v[168:171], v[116:119]
	v_mfma_f32_16x16x32_bf16 v[112:115], v[136:139], v[168:171], v[112:115]
	v_mfma_f32_16x16x32_bf16 v[108:111], v[128:131], v[176:179], v[108:111]
	v_mfma_f32_16x16x32_bf16 v[104:107], v[136:139], v[176:179], v[104:107]
	v_mfma_f32_16x16x32_bf16 v[100:103], v[128:131], v[184:187], v[100:103]
	v_mfma_f32_16x16x32_bf16 v[96:99], v[136:139], v[184:187], v[96:99]
	v_mfma_f32_16x16x32_bf16 v[60:63], v[144:147], v[160:163], v[60:63]
	v_mfma_f32_16x16x32_bf16 v[56:59], v[152:155], v[160:163], v[56:59]
	v_mfma_f32_16x16x32_bf16 v[52:55], v[144:147], v[168:171], v[52:55]
	v_mfma_f32_16x16x32_bf16 v[48:51], v[152:155], v[168:171], v[48:51]
	v_mfma_f32_16x16x32_bf16 v[44:47], v[144:147], v[176:179], v[44:47]
	v_mfma_f32_16x16x32_bf16 v[40:43], v[152:155], v[176:179], v[40:43]
	v_mfma_f32_16x16x32_bf16 v[36:39], v[144:147], v[184:187], v[36:39]
	v_mfma_f32_16x16x32_bf16 v[32:35], v[152:155], v[184:187], v[32:35]
	v_mfma_f32_16x16x32_bf16 v[124:127], v[132:135], v[164:167], v[124:127]
	v_mfma_f32_16x16x32_bf16 v[120:123], v[140:143], v[164:167], v[120:123]
	v_mfma_f32_16x16x32_bf16 v[116:119], v[132:135], v[172:175], v[116:119]
	v_mfma_f32_16x16x32_bf16 v[112:115], v[140:143], v[172:175], v[112:115]
	v_mfma_f32_16x16x32_bf16 v[108:111], v[132:135], v[180:183], v[108:111]
	v_mfma_f32_16x16x32_bf16 v[104:107], v[140:143], v[180:183], v[104:107]
	v_mfma_f32_16x16x32_bf16 v[100:103], v[132:135], v[188:191], v[100:103]
	v_mfma_f32_16x16x32_bf16 v[96:99], v[140:143], v[188:191], v[96:99]
	v_mfma_f32_16x16x32_bf16 v[60:63], v[148:151], v[164:167], v[60:63]
	v_mfma_f32_16x16x32_bf16 v[56:59], v[156:159], v[164:167], v[56:59]
	v_mfma_f32_16x16x32_bf16 v[52:55], v[148:151], v[172:175], v[52:55]
	v_mfma_f32_16x16x32_bf16 v[48:51], v[156:159], v[172:175], v[48:51]
	v_mfma_f32_16x16x32_bf16 v[44:47], v[148:151], v[180:183], v[44:47]
	v_mfma_f32_16x16x32_bf16 v[40:43], v[156:159], v[180:183], v[40:43]
	v_mfma_f32_16x16x32_bf16 v[36:39], v[148:151], v[188:191], v[36:39]
	v_mfma_f32_16x16x32_bf16 v[32:35], v[156:159], v[188:191], v[32:35]
	s_barrier
	s_add_i32 s40, s59, s42
	v_lshl_add_u64 v[208:209], s[46:47], 0, v[194:195]
	s_mov_b32 m0, s40
	ds_read_b128 v[160:163], v213 offset:16384
	ds_read_b128 v[164:167], v213 offset:17408
	ds_read_b128 v[168:171], v213 offset:18432
	ds_read_b128 v[172:175], v213 offset:19456
	ds_read_b128 v[176:179], v213 offset:20480
	ds_read_b128 v[180:183], v213 offset:21504
	ds_read_b128 v[184:187], v213 offset:22528
	ds_read_b128 v[188:191], v213 offset:23552
	global_load_lds_dwordx4 v[208:209], off
	s_add_i32 m0, s40, 0x2000
	s_add_u32 s66, s46, 0x80000
	v_lshl_add_u64 v[220:221], s[46:47], 0, v[198:199]
	s_addc_u32 s67, s47, 0
	s_add_i32 s40, s60, s42
	global_load_lds_dwordx4 v[220:221], off
	v_lshl_add_u64 v[222:223], s[66:67], 0, v[194:195]
	s_mov_b32 m0, s40
	v_lshl_add_u64 v[224:225], s[48:49], 0, v[196:197]
	global_load_lds_dwordx4 v[222:223], off
	v_lshl_add_u64 v[222:223], s[66:67], 0, v[198:199]
	s_add_i32 m0, s40, 0x2000
	s_nop 0
	global_load_lds_dwordx4 v[222:223], off
	v_lshl_add_u64 v[222:223], s[48:49], 0, v[192:193]
	s_mov_b32 m0, s35
	s_nop 0
	global_load_lds_dwordx4 v[222:223], off
	s_mov_b32 m0, s43
	s_nop 0
	global_load_lds_dwordx4 v[224:225], off
	s_waitcnt vmcnt(8)
	s_waitcnt lgkmcnt(0)
	s_barrier
; #define PG8_STAGE(bufoff, gbase, voff) do { _Pragma("unroll") for (int _i = 0; _i < 2; ++_i) \
;         __builtin_amdgcn_global_load_lds((const unsigned*)((const char*)(gbase) + (voff)[_i]), (PG8_LAS unsigned*)(lds + (bufoff) + ldsw + _i * 8192), 16, 0, 0); } while (0)
; #define PG8_LDA(dst, b, h) do { _Pragma("unroll") for (int m = 0; m < 4; ++m) _Pragma("unroll") for (int k = 0; k < 2; ++k) dst[m][k] = *(const PG8_LAS bf16x8*)(lds + PG8_SA(b, h) + aoff + m * 2048 + k * 1024); } while (0)
; #define PG8_LDB(dst, b, h) do { _Pragma("unroll") for (int n = 0; n < 2; ++n) _Pragma("unroll") for (int k = 0; k < 2; ++k) dst[n][k] = *(const PG8_LAS bf16x8*)(lds + PG8_SB(b, h) + boff + n * 2048 + k * 1024); } while (0)
; #define PG8_MMA(ai, bj, At, Bt) do { _Pragma("unroll") for (int m = 0; m < 4; ++m) _Pragma("unroll") for (int n = 0; n < 2; ++n) _Pragma("unroll") for (int k = 0; k < 2; ++k) \
;         acc[ai][bj][m][n] = __builtin_amdgcn_mfma_f32_16x16x32_bf16(Bt[n][k], At[m][k], acc[ai][bj][m][n], 0, 0, 0); } while (0)
; #define PG8_WAIT_V(n) asm volatile("s_waitcnt vmcnt(" #n ")" ::: "memory")
; #define PG8_WAIT_L(n) asm volatile("s_waitcnt lgkmcnt(" #n ")" ::: "memory")
; #define PG8_BAR __builtin_amdgcn_s_barrier()
; #define PG8_SCHED __builtin_amdgcn_sched_barrier(0)
; template <class Epi, class Sched, bool ALIGN_EPI = false, bool SP2 = false>
; __device__ __forceinline__ void gemm_phase(PG8_LAS unsigned char* lds, const Gemm g, const Sched& S, const Epi& E, const int wave_id_in) {
;     ...
;             PG8_WAIT_V(8); PG8_WAIT_L(0); PG8_BAR; __builtin_amdgcn_s_setprio(1); PG8_MMA(1, 0, At, B0); PG8_MMA(1, 1, At, B1); __builtin_amdgcn_s_setprio(0); PG8_BAR; PG8_SCHED;
;             PG8_LDB(B0, 1, 0); PG8_LDB(B1, 1, 1); PG8_SCHED; PG8_LDA(At, 1, 0); PG8_STAGE(PG8_SA(0, 1), a2 + hstep, voffA);
;             PG8_WAIT_V(8); PG8_WAIT_L(0); PG8_BAR; __builtin_amdgcn_s_setprio(1); PG8_MMA(0, 0, At, B0); PG8_MMA(0, 1, At, B1); __builtin_amdgcn_s_setprio(0); PG8_BAR; PG8_SCHED;
	v_mfma_f32_16x16x32_bf16 v[92:95], v[128:131], v[160:163], v[92:95]
	v_mfma_f32_16x16x32_bf16 v[88:91], v[136:139], v[160:163], v[88:91]
	v_mfma_f32_16x16x32_bf16 v[84:87], v[128:131], v[168:171], v[84:87]
	v_mfma_f32_16x16x32_bf16 v[80:83], v[136:139], v[168:171], v[80:83]
	v_mfma_f32_16x16x32_bf16 v[76:79], v[128:131], v[176:179], v[76:79]
	v_mfma_f32_16x16x32_bf16 v[72:75], v[136:139], v[176:179], v[72:75]
	v_mfma_f32_16x16x32_bf16 v[68:71], v[128:131], v[184:187], v[68:71]
	v_mfma_f32_16x16x32_bf16 v[64:67], v[136:139], v[184:187], v[64:67]
	v_mfma_f32_16x16x32_bf16 v[28:31], v[144:147], v[160:163], v[28:31]
	v_mfma_f32_16x16x32_bf16 v[24:27], v[152:155], v[160:163], v[24:27]
	v_mfma_f32_16x16x32_bf16 v[20:23], v[144:147], v[168:171], v[20:23]
	v_mfma_f32_16x16x32_bf16 v[16:19], v[152:155], v[168:171], v[16:19]
	v_mfma_f32_16x16x32_bf16 v[12:15], v[144:147], v[176:179], v[12:15]
	v_mfma_f32_16x16x32_bf16 v[8:11], v[152:155], v[176:179], v[8:11]
	v_mfma_f32_16x16x32_bf16 v[4:7], v[144:147], v[184:187], v[4:7]
	v_mfma_f32_16x16x32_bf16 v[0:3], v[152:155], v[184:187], v[0:3]
	v_mfma_f32_16x16x32_bf16 v[92:95], v[132:135], v[164:167], v[92:95]
	v_mfma_f32_16x16x32_bf16 v[88:91], v[140:143], v[164:167], v[88:91]
	v_mfma_f32_16x16x32_bf16 v[84:87], v[132:135], v[172:175], v[84:87]
	v_mfma_f32_16x16x32_bf16 v[80:83], v[140:143], v[172:175], v[80:83]
	v_mfma_f32_16x16x32_bf16 v[76:79], v[132:135], v[180:183], v[76:79]
	v_mfma_f32_16x16x32_bf16 v[72:75], v[140:143], v[180:183], v[72:75]
	v_mfma_f32_16x16x32_bf16 v[68:71], v[132:135], v[188:191], v[68:71]
	v_mfma_f32_16x16x32_bf16 v[64:67], v[140:143], v[188:191], v[64:67]
	v_mfma_f32_16x16x32_bf16 v[28:31], v[148:151], v[164:167], v[28:31]
	v_mfma_f32_16x16x32_bf16 v[24:27], v[156:159], v[164:167], v[24:27]
	v_mfma_f32_16x16x32_bf16 v[20:23], v[148:151], v[172:175], v[20:23]
	v_mfma_f32_16x16x32_bf16 v[16:19], v[156:159], v[172:175], v[16:19]
	v_mfma_f32_16x16x32_bf16 v[12:15], v[148:151], v[180:183], v[12:15]
	v_mfma_f32_16x16x32_bf16 v[8:11], v[156:159], v[180:183], v[8:11]
	v_mfma_f32_16x16x32_bf16 v[4:7], v[148:151], v[188:191], v[4:7]
	v_mfma_f32_16x16x32_bf16 v[0:3], v[156:159], v[188:191], v[0:3]
	s_barrier
	s_add_i32 s40, 0, 0x18000
	s_add_i32 s41, 0, 0x1c000
	v_add_u32_e32 v140, s40, v210
	v_add_u32_e32 v156, s41, v210
	ds_read_b128 v[128:131], v140
	ds_read_b128 v[132:135], v140 offset:1024
	ds_read_b128 v[136:139], v140 offset:2048
	ds_read_b128 v[140:143], v140 offset:3072
	ds_read_b128 v[144:147], v156
	ds_read_b128 v[148:151], v156 offset:1024
	ds_read_b128 v[152:155], v156 offset:2048
	ds_read_b128 v[156:159], v156 offset:3072
	s_add_u32 s48, s48, 0x80000
	s_addc_u32 s49, s49, 0
	s_mov_b32 m0, s44
	v_lshl_add_u64 v[226:227], s[48:49], 0, v[192:193]
	ds_read_b128 v[160:163], v213 offset:32768
	ds_read_b128 v[164:167], v213 offset:33792
	ds_read_b128 v[168:171], v213 offset:34816
	ds_read_b128 v[172:175], v213 offset:35840
	ds_read_b128 v[176:179], v213 offset:36864
	ds_read_b128 v[180:183], v213 offset:37888
	ds_read_b128 v[184:187], v213 offset:38912
	ds_read_b128 v[188:191], v213 offset:39936
	global_load_lds_dwordx4 v[226:227], off
	v_lshl_add_u64 v[226:227], s[48:49], 0, v[196:197]
	s_mov_b32 m0, s45
	s_nop 0
	global_load_lds_dwordx4 v[226:227], off
	s_waitcnt vmcnt(8)
	s_waitcnt lgkmcnt(0)
	s_barrier
	v_mfma_f32_16x16x32_bf16 v[124:127], v[128:131], v[160:163], v[124:127]
	v_mfma_f32_16x16x32_bf16 v[120:123], v[136:139], v[160:163], v[120:123]
	v_mfma_f32_16x16x32_bf16 v[116:119], v[128:131], v[168:171], v[116:119]
	v_mfma_f32_16x16x32_bf16 v[112:115], v[136:139], v[168:171], v[112:115]
	v_mfma_f32_16x16x32_bf16 v[108:111], v[128:131], v[176:179], v[108:111]
	v_mfma_f32_16x16x32_bf16 v[104:107], v[136:139], v[176:179], v[104:107]
	v_mfma_f32_16x16x32_bf16 v[100:103], v[128:131], v[184:187], v[100:103]
	v_mfma_f32_16x16x32_bf16 v[96:99], v[136:139], v[184:187], v[96:99]
	v_mfma_f32_16x16x32_bf16 v[60:63], v[144:147], v[160:163], v[60:63]
	v_mfma_f32_16x16x32_bf16 v[56:59], v[152:155], v[160:163], v[56:59]
	v_mfma_f32_16x16x32_bf16 v[52:55], v[144:147], v[168:171], v[52:55]
	v_mfma_f32_16x16x32_bf16 v[48:51], v[152:155], v[168:171], v[48:51]
	v_mfma_f32_16x16x32_bf16 v[44:47], v[144:147], v[176:179], v[44:47]
	v_mfma_f32_16x16x32_bf16 v[40:43], v[152:155], v[176:179], v[40:43]
	v_mfma_f32_16x16x32_bf16 v[36:39], v[144:147], v[184:187], v[36:39]
	v_mfma_f32_16x16x32_bf16 v[32:35], v[152:155], v[184:187], v[32:35]
	v_mfma_f32_16x16x32_bf16 v[124:127], v[132:135], v[164:167], v[124:127]
	v_mfma_f32_16x16x32_bf16 v[120:123], v[140:143], v[164:167], v[120:123]
	v_mfma_f32_16x16x32_bf16 v[116:119], v[132:135], v[172:175], v[116:119]
	v_mfma_f32_16x16x32_bf16 v[112:115], v[140:143], v[172:175], v[112:115]
	v_mfma_f32_16x16x32_bf16 v[108:111], v[132:135], v[180:183], v[108:111]
	v_mfma_f32_16x16x32_bf16 v[104:107], v[140:143], v[180:183], v[104:107]
	v_mfma_f32_16x16x32_bf16 v[100:103], v[132:135], v[188:191], v[100:103]
	v_mfma_f32_16x16x32_bf16 v[96:99], v[140:143], v[188:191], v[96:99]
	v_mfma_f32_16x16x32_bf16 v[60:63], v[148:151], v[164:167], v[60:63]
	v_mfma_f32_16x16x32_bf16 v[56:59], v[156:159], v[164:167], v[56:59]
	v_mfma_f32_16x16x32_bf16 v[52:55], v[148:151], v[172:175], v[52:55]
	v_mfma_f32_16x16x32_bf16 v[48:51], v[156:159], v[172:175], v[48:51]
	v_mfma_f32_16x16x32_bf16 v[44:47], v[148:151], v[180:183], v[44:47]
	v_mfma_f32_16x16x32_bf16 v[40:43], v[156:159], v[180:183], v[40:43]
	v_mfma_f32_16x16x32_bf16 v[36:39], v[148:151], v[188:191], v[36:39]
	v_mfma_f32_16x16x32_bf16 v[32:35], v[156:159], v[188:191], v[32:35]
	s_barrier
; #define PG8_STAGE(bufoff, gbase, voff) do { _Pragma("unroll") for (int _i = 0; _i < 2; ++_i) \
;         __builtin_amdgcn_global_load_lds((const unsigned*)((const char*)(gbase) + (voff)[_i]), (PG8_LAS unsigned*)(lds + (bufoff) + ldsw + _i * 8192), 16, 0, 0); } while (0)
; #define PG8_LDA(dst, b, h) do { _Pragma("unroll") for (int m = 0; m < 4; ++m) _Pragma("unroll") for (int k = 0; k < 2; ++k) dst[m][k] = *(const PG8_LAS bf16x8*)(lds + PG8_SA(b, h) + aoff + m * 2048 + k * 1024); } while (0)
; #define PG8_MMA(ai, bj, At, Bt) do { _Pragma("unroll") for (int m = 0; m < 4; ++m) _Pragma("unroll") for (int n = 0; n < 2; ++n) _Pragma("unroll") for (int k = 0; k < 2; ++k) \
;         acc[ai][bj][m][n] = __builtin_amdgcn_mfma_f32_16x16x32_bf16(Bt[n][k], At[m][k], acc[ai][bj][m][n], 0, 0, 0); } while (0)
; #define PG8_WAIT_V(n) asm volatile("s_waitcnt vmcnt(" #n ")" ::: "memory")
; #define PG8_WAIT_L(n) asm volatile("s_waitcnt lgkmcnt(" #n ")" ::: "memory")
; #define PG8_BAR __builtin_amdgcn_s_barrier()
; #define PG8_SCHED __builtin_amdgcn_sched_barrier(0)
; template <class Epi, class Sched, bool ALIGN_EPI = false, bool SP2 = false>
; __device__ __forceinline__ void gemm_phase(PG8_LAS unsigned char* lds, const Gemm g, const Sched& S, const Epi& E, const int wave_id_in) {
;     ...
;             PG8_LDA(At, 1, 1); PG8_STAGE(PG8_SB(1, 0), b3, voffB); PG8_STAGE(PG8_SB(1, 1), b3 + hstep, voffB); PG8_STAGE(PG8_SA(1, 0), a3, voffA);
;             PG8_WAIT_V(8); PG8_WAIT_L(0); PG8_BAR; __builtin_amdgcn_s_setprio(1); PG8_MMA(1, 0, At, B0); PG8_MMA(1, 1, At, B1); __builtin_amdgcn_s_setprio(0); PG8_BAR; PG8_SCHED;
;     ...
;         if constexpr (ALIGN_EPI) { if (wr == 0) PG8_BAR; }
	s_add_i32 s40, s40, s42
	v_lshl_add_u64 v[208:209], v[208:209], 0, s[12:13]
	s_mov_b32 m0, s40
	ds_read_b128 v[160:163], v213 offset:49152
	ds_read_b128 v[164:167], v213 offset:50176
	ds_read_b128 v[168:171], v213 offset:51200
	ds_read_b128 v[172:175], v213 offset:52224
	ds_read_b128 v[176:179], v213 offset:53248
	ds_read_b128 v[180:183], v213 offset:54272
	ds_read_b128 v[184:187], v213 offset:55296
	ds_read_b128 v[188:191], v213 offset:56320
	global_load_lds_dwordx4 v[208:209], off
	s_add_i32 m0, s40, 0x2000
	s_add_u32 s46, s46, 0x80080
	v_lshl_add_u64 v[208:209], v[220:221], 0, s[12:13]
	s_addc_u32 s47, s47, 0
	s_add_i32 s40, s41, s42
	global_load_lds_dwordx4 v[208:209], off
	v_lshl_add_u64 v[208:209], s[46:47], 0, v[194:195]
	s_mov_b32 m0, s40
	s_nop 0
	global_load_lds_dwordx4 v[208:209], off
	v_lshl_add_u64 v[208:209], s[46:47], 0, v[198:199]
	s_add_i32 m0, s40, 0x2000
	s_nop 0
	global_load_lds_dwordx4 v[208:209], off
	v_lshl_add_u64 v[208:209], v[222:223], 0, s[12:13]
	s_mov_b32 m0, s53
	s_nop 0
	global_load_lds_dwordx4 v[208:209], off
	v_lshl_add_u64 v[208:209], v[224:225], 0, s[12:13]
	s_mov_b32 m0, s54
	s_nop 0
	global_load_lds_dwordx4 v[208:209], off
	s_waitcnt vmcnt(8)
	s_waitcnt lgkmcnt(0)
	s_barrier
	v_mfma_f32_16x16x32_bf16 v[92:95], v[128:131], v[160:163], v[92:95]
	v_mfma_f32_16x16x32_bf16 v[88:91], v[136:139], v[160:163], v[88:91]
	v_mfma_f32_16x16x32_bf16 v[84:87], v[128:131], v[168:171], v[84:87]
	v_mfma_f32_16x16x32_bf16 v[80:83], v[136:139], v[168:171], v[80:83]
	v_mfma_f32_16x16x32_bf16 v[76:79], v[128:131], v[176:179], v[76:79]
	v_mfma_f32_16x16x32_bf16 v[72:75], v[136:139], v[176:179], v[72:75]
	v_mfma_f32_16x16x32_bf16 v[68:71], v[128:131], v[184:187], v[68:71]
	v_mfma_f32_16x16x32_bf16 v[64:67], v[136:139], v[184:187], v[64:67]
	v_mfma_f32_16x16x32_bf16 v[28:31], v[144:147], v[160:163], v[28:31]
	v_mfma_f32_16x16x32_bf16 v[24:27], v[152:155], v[160:163], v[24:27]
	v_mfma_f32_16x16x32_bf16 v[20:23], v[144:147], v[168:171], v[20:23]
	v_mfma_f32_16x16x32_bf16 v[16:19], v[152:155], v[168:171], v[16:19]
	v_mfma_f32_16x16x32_bf16 v[12:15], v[144:147], v[176:179], v[12:15]
	v_mfma_f32_16x16x32_bf16 v[8:11], v[152:155], v[176:179], v[8:11]
	v_mfma_f32_16x16x32_bf16 v[4:7], v[144:147], v[184:187], v[4:7]
	v_mfma_f32_16x16x32_bf16 v[0:3], v[152:155], v[184:187], v[0:3]
	v_mfma_f32_16x16x32_bf16 v[92:95], v[132:135], v[164:167], v[92:95]
	v_mfma_f32_16x16x32_bf16 v[88:91], v[140:143], v[164:167], v[88:91]
	v_mfma_f32_16x16x32_bf16 v[84:87], v[132:135], v[172:175], v[84:87]
	v_mfma_f32_16x16x32_bf16 v[80:83], v[140:143], v[172:175], v[80:83]
	v_mfma_f32_16x16x32_bf16 v[76:79], v[132:135], v[180:183], v[76:79]
	v_mfma_f32_16x16x32_bf16 v[72:75], v[140:143], v[180:183], v[72:75]
	v_mfma_f32_16x16x32_bf16 v[68:71], v[132:135], v[188:191], v[68:71]
	v_mfma_f32_16x16x32_bf16 v[64:67], v[140:143], v[188:191], v[64:67]
	v_mfma_f32_16x16x32_bf16 v[28:31], v[148:151], v[164:167], v[28:31]
	v_mfma_f32_16x16x32_bf16 v[24:27], v[156:159], v[164:167], v[24:27]
	v_mfma_f32_16x16x32_bf16 v[20:23], v[148:151], v[172:175], v[20:23]
	v_mfma_f32_16x16x32_bf16 v[16:19], v[156:159], v[172:175], v[16:19]
	v_mfma_f32_16x16x32_bf16 v[12:15], v[148:151], v[180:183], v[12:15]
	v_mfma_f32_16x16x32_bf16 v[8:11], v[156:159], v[180:183], v[8:11]
	v_mfma_f32_16x16x32_bf16 v[4:7], v[148:151], v[188:191], v[4:7]
	v_mfma_f32_16x16x32_bf16 v[0:3], v[156:159], v[188:191], v[0:3]
	s_add_i32 s64, s64, 2
	s_add_u32 s36, s36, 0x100
	s_addc_u32 s37, s37, 0
	s_add_u32 s62, s62, 0x100
	s_addc_u32 s63, s63, 0
	s_cmp_gt_u32 s64, 29
	s_barrier
	s_cbranch_scc0 .LBB0_680
	s_and_b64 vcc, exec, s[14:15]
	s_cbranch_vccz .LBB0_683
	s_barrier

; #define PG8_STAGE(bufoff, gbase, voff) do { _Pragma("unroll") for (int _i = 0; _i < 2; ++_i) \
;         __builtin_amdgcn_global_load_lds((const unsigned*)((const char*)(gbase) + (voff)[_i]), (PG8_LAS unsigned*)(lds + (bufoff) + ldsw + _i * 8192), 16, 0, 0); } while (0)
; #define PG8_LDA(dst, b, h) do { _Pragma("unroll") for (int m = 0; m < 4; ++m) _Pragma("unroll") for (int k = 0; k < 2; ++k) dst[m][k] = *(const PG8_LAS bf16x8*)(lds + PG8_SA(b, h) + aoff + m * 2048 + k * 1024); } while (0)
; #define PG8_LDB(dst, b, h) do { _Pragma("unroll") for (int n = 0; n < 2; ++n) _Pragma("unroll") for (int k = 0; k < 2; ++k) dst[n][k] = *(const PG8_LAS bf16x8*)(lds + PG8_SB(b, h) + boff + n * 2048 + k * 1024); } while (0)
; #define PG8_MMA(ai, bj, At, Bt) do { _Pragma("unroll") for (int m = 0; m < 4; ++m) _Pragma("unroll") for (int n = 0; n < 2; ++n) _Pragma("unroll") for (int k = 0; k < 2; ++k) \
;         acc[ai][bj][m][n] = __builtin_amdgcn_mfma_f32_16x16x32_bf16(Bt[n][k], At[m][k], acc[ai][bj][m][n], 0, 0, 0); } while (0)
; #define PG8_WAIT_V(n) asm volatile("s_waitcnt vmcnt(" #n ")" ::: "memory")
; #define PG8_WAIT_L(n) asm volatile("s_waitcnt lgkmcnt(" #n ")" ::: "memory")
; #define PG8_BAR __builtin_amdgcn_s_barrier()
; #define PG8_SCHED __builtin_amdgcn_sched_barrier(0)
; template <class Epi>
; __device__ __forceinline__ void gemm_half_phase(PG8_LAS unsigned char* lds, const Gemm g, const Unit cur, const Epi& E, const int wave_id_in) {
;     ...
;     for (int t = 0; t < nt; t += 2) {
;         const bool last = (t == nt - 2);
;         const char* a2 = last ? cA : cA + (size_t)(t + 2) * kstep; const char* b2 = last ? cB : cB + (size_t)(t + 2) * kstep;
;         const char* a3 = a2 + kstep; const char* b3 = b2 + kstep;
;         PG8_LDB(B0, 0, 0); PG8_LDB(B1, 0, 1); PG8_SCHED; PG8_LDA(At, 0, 0);
;         PG8_WAIT_V(6); PG8_WAIT_L(0); PG8_BAR; __builtin_amdgcn_s_setprio(1); PG8_MMA(0, 0, At, B0); __builtin_amdgcn_s_setprio(0); PG8_BAR; PG8_SCHED;
;         PG8_STAGE(PG8_SB(0, 0), b2, voffB); PG8_STAGE(PG8_SB(0, 1), b2 + hstep, voffB); PG8_STAGE(PG8_SA(0, 0), a2, voffA);
;         PG8_WAIT_V(6); PG8_BAR; __builtin_amdgcn_s_setprio(1); PG8_MMA(0, 1, At, B1); __builtin_amdgcn_s_setprio(0); PG8_BAR; PG8_SCHED;
.LBB0_769:
	ds_read_b128 v[44:47], v32
	ds_read_b128 v[52:55], v32 offset:1024
	ds_read_b128 v[56:59], v32 offset:2048
	ds_read_b128 v[64:67], v32 offset:3072
	ds_read_b128 v[88:91], v33
	ds_read_b128 v[92:95], v33 offset:1024
	ds_read_b128 v[104:107], v33 offset:2048
	ds_read_b128 v[108:111], v33 offset:3072
	s_cmp_eq_u32 s43, 28
	s_cselect_b32 s55, s7, s42
	s_cselect_b32 s54, s6, s39
	s_cselect_b32 s29, s9, s31
	s_cselect_b32 s28, s8, s30
	ds_read_b128 v[112:115], v34
	ds_read_b128 v[116:119], v34 offset:1024
	ds_read_b128 v[120:123], v34 offset:2048
	ds_read_b128 v[124:127], v34 offset:3072
	ds_read_b128 v[128:131], v34 offset:4096
	ds_read_b128 v[132:135], v34 offset:5120
	ds_read_b128 v[136:139], v34 offset:6144
	ds_read_b128 v[140:143], v34 offset:7168
	s_waitcnt vmcnt(6)
	s_waitcnt lgkmcnt(0)
	s_barrier
	v_mfma_f32_16x16x32_bf16 v[20:23], v[44:47], v[112:115], v[20:23]
	v_mfma_f32_16x16x32_bf16 v[16:19], v[56:59], v[112:115], v[16:19]
	v_mfma_f32_16x16x32_bf16 v[100:103], v[44:47], v[120:123], v[100:103]
	v_mfma_f32_16x16x32_bf16 v[96:99], v[56:59], v[120:123], v[96:99]
	v_mfma_f32_16x16x32_bf16 v[84:87], v[44:47], v[128:131], v[84:87]
	v_mfma_f32_16x16x32_bf16 v[80:83], v[56:59], v[128:131], v[80:83]
	v_mfma_f32_16x16x32_bf16 v[12:15], v[44:47], v[136:139], v[12:15]
	v_mfma_f32_16x16x32_bf16 v[8:11], v[56:59], v[136:139], v[8:11]
	v_mfma_f32_16x16x32_bf16 v[20:23], v[52:55], v[116:119], v[20:23]
	v_mfma_f32_16x16x32_bf16 v[16:19], v[64:67], v[116:119], v[16:19]
	v_mfma_f32_16x16x32_bf16 v[100:103], v[52:55], v[124:127], v[100:103]
	v_mfma_f32_16x16x32_bf16 v[96:99], v[64:67], v[124:127], v[96:99]
	v_mfma_f32_16x16x32_bf16 v[84:87], v[52:55], v[132:135], v[84:87]
	v_mfma_f32_16x16x32_bf16 v[80:83], v[64:67], v[132:135], v[80:83]
	v_mfma_f32_16x16x32_bf16 v[12:15], v[52:55], v[140:143], v[12:15]
	v_mfma_f32_16x16x32_bf16 v[8:11], v[64:67], v[140:143], v[8:11]
	s_barrier
	s_mov_b32 m0, s46
	v_lshl_add_u64 v[144:145], s[28:29], 0, v[26:27]
	s_add_u32 s56, s28, 0x80000
	global_load_lds_dwordx4 v[144:145], off
	v_lshl_add_u64 v[146:147], s[28:29], 0, v[30:31]
	s_mov_b32 m0, s47
	s_addc_u32 s57, s29, 0
	global_load_lds_dwordx4 v[146:147], off
	v_lshl_add_u64 v[38:39], s[56:57], 0, v[26:27]
	s_mov_b32 m0, s48
	v_lshl_add_u64 v[148:149], s[54:55], 0, v[24:25]
	global_load_lds_dwordx4 v[38:39], off
	v_lshl_add_u64 v[38:39], s[56:57], 0, v[30:31]
	s_mov_b32 m0, s49
	v_lshl_add_u64 v[150:151], s[54:55], 0, v[28:29]
	global_load_lds_dwordx4 v[38:39], off
	s_mov_b32 m0, s35
	s_nop 0
	global_load_lds_dwordx4 v[148:149], off
	s_mov_b32 m0, s36
	s_nop 0
	global_load_lds_dwordx4 v[150:151], off
	s_waitcnt vmcnt(6)
	s_barrier
	v_mfma_f32_16x16x32_bf16 v[38:41], v[88:91], v[112:115], v[40:43]
	v_mfma_f32_16x16x32_bf16 v[42:45], v[104:107], v[112:115], v[48:51]
	v_mfma_f32_16x16x32_bf16 v[48:51], v[88:91], v[120:123], v[76:79]
	v_mfma_f32_16x16x32_bf16 v[52:55], v[92:95], v[124:127], v[48:51]
	v_mfma_f32_16x16x32_bf16 v[48:51], v[104:107], v[120:123], v[72:75]
	v_mfma_f32_16x16x32_bf16 v[56:59], v[108:111], v[124:127], v[48:51]
	v_mfma_f32_16x16x32_bf16 v[48:51], v[88:91], v[128:131], v[68:71]
	v_mfma_f32_16x16x32_bf16 v[64:67], v[92:95], v[132:135], v[48:51]
	v_mfma_f32_16x16x32_bf16 v[48:51], v[104:107], v[128:131], v[60:63]
	v_mfma_f32_16x16x32_bf16 v[4:7], v[88:91], v[136:139], v[4:7]
	v_mfma_f32_16x16x32_bf16 v[0:3], v[104:107], v[136:139], v[0:3]
	v_mfma_f32_16x16x32_bf16 v[38:41], v[92:95], v[116:119], v[38:41]
	v_mfma_f32_16x16x32_bf16 v[60:63], v[108:111], v[132:135], v[48:51]
	v_mfma_f32_16x16x32_bf16 v[4:7], v[92:95], v[140:143], v[4:7]
	v_mfma_f32_16x16x32_bf16 v[0:3], v[108:111], v[140:143], v[0:3]
	v_mfma_f32_16x16x32_bf16 v[44:47], v[108:111], v[116:119], v[42:45]
	s_barrier
; #define PG8_STAGE(bufoff, gbase, voff) do { _Pragma("unroll") for (int _i = 0; _i < 2; ++_i) \
;         __builtin_amdgcn_global_load_lds((const unsigned*)((const char*)(gbase) + (voff)[_i]), (PG8_LAS unsigned*)(lds + (bufoff) + ldsw + _i * 8192), 16, 0, 0); } while (0)
; #define PG8_LDA(dst, b, h) do { _Pragma("unroll") for (int m = 0; m < 4; ++m) _Pragma("unroll") for (int k = 0; k < 2; ++k) dst[m][k] = *(const PG8_LAS bf16x8*)(lds + PG8_SA(b, h) + aoff + m * 2048 + k * 1024); } while (0)
; #define PG8_LDB(dst, b, h) do { _Pragma("unroll") for (int n = 0; n < 2; ++n) _Pragma("unroll") for (int k = 0; k < 2; ++k) dst[n][k] = *(const PG8_LAS bf16x8*)(lds + PG8_SB(b, h) + boff + n * 2048 + k * 1024); } while (0)
; #define PG8_MMA(ai, bj, At, Bt) do { _Pragma("unroll") for (int m = 0; m < 4; ++m) _Pragma("unroll") for (int n = 0; n < 2; ++n) _Pragma("unroll") for (int k = 0; k < 2; ++k) \
;         acc[ai][bj][m][n] = __builtin_amdgcn_mfma_f32_16x16x32_bf16(Bt[n][k], At[m][k], acc[ai][bj][m][n], 0, 0, 0); } while (0)
; #define PG8_WAIT_V(n) asm volatile("s_waitcnt vmcnt(" #n ")" ::: "memory")
; #define PG8_WAIT_L(n) asm volatile("s_waitcnt lgkmcnt(" #n ")" ::: "memory")
; #define PG8_BAR __builtin_amdgcn_s_barrier()
; #define PG8_SCHED __builtin_amdgcn_sched_barrier(0)
; template <class Epi>
; __device__ __forceinline__ void gemm_half_phase(PG8_LAS unsigned char* lds, const Gemm g, const Unit cur, const Epi& E, const int wave_id_in) {
;     ...
;         PG8_LDB(B0, 1, 0); PG8_LDB(B1, 1, 1); PG8_SCHED; PG8_LDA(At, 1, 0);
;         PG8_WAIT_V(6); PG8_WAIT_L(0); PG8_BAR; __builtin_amdgcn_s_setprio(1); PG8_MMA(0, 0, At, B0); __builtin_amdgcn_s_setprio(0); PG8_BAR; PG8_SCHED;
;         PG8_STAGE(PG8_SB(1, 0), b3, voffB); PG8_STAGE(PG8_SB(1, 1), b3 + hstep, voffB); PG8_STAGE(PG8_SA(1, 0), a3, voffA);
;         PG8_WAIT_V(6); PG8_BAR; __builtin_amdgcn_s_setprio(1); PG8_MMA(0, 1, At, B1); __builtin_amdgcn_s_setprio(0); PG8_BAR; PG8_SCHED;
;     }
;     if (wr == 0) PG8_BAR;
	ds_read_b128 v[48:51], v35
	ds_read_b128 v[68:71], v35 offset:1024
	ds_read_b128 v[72:75], v35 offset:2048
	ds_read_b128 v[76:79], v35 offset:3072
	ds_read_b128 v[88:91], v36
	ds_read_b128 v[92:95], v36 offset:1024
	ds_read_b128 v[104:107], v36 offset:2048
	ds_read_b128 v[108:111], v36 offset:3072
	ds_read_b128 v[112:115], v34 offset:32768
	ds_read_b128 v[116:119], v34 offset:33792
	ds_read_b128 v[120:123], v34 offset:34816
	ds_read_b128 v[124:127], v34 offset:35840
	ds_read_b128 v[128:131], v34 offset:36864
	ds_read_b128 v[132:135], v34 offset:37888
	ds_read_b128 v[136:139], v34 offset:38912
	ds_read_b128 v[140:143], v34 offset:39936
	s_waitcnt vmcnt(6)
	s_waitcnt lgkmcnt(0)
	s_barrier
	v_mfma_f32_16x16x32_bf16 v[20:23], v[48:51], v[112:115], v[20:23]
	v_mfma_f32_16x16x32_bf16 v[16:19], v[72:75], v[112:115], v[16:19]
	v_mfma_f32_16x16x32_bf16 v[100:103], v[48:51], v[120:123], v[100:103]
	v_mfma_f32_16x16x32_bf16 v[96:99], v[72:75], v[120:123], v[96:99]
	v_mfma_f32_16x16x32_bf16 v[84:87], v[48:51], v[128:131], v[84:87]
	v_mfma_f32_16x16x32_bf16 v[80:83], v[72:75], v[128:131], v[80:83]
	v_mfma_f32_16x16x32_bf16 v[12:15], v[48:51], v[136:139], v[12:15]
	v_mfma_f32_16x16x32_bf16 v[8:11], v[72:75], v[136:139], v[8:11]
	v_mfma_f32_16x16x32_bf16 v[20:23], v[68:71], v[116:119], v[20:23]
	v_mfma_f32_16x16x32_bf16 v[16:19], v[76:79], v[116:119], v[16:19]
	v_mfma_f32_16x16x32_bf16 v[100:103], v[68:71], v[124:127], v[100:103]
	v_mfma_f32_16x16x32_bf16 v[96:99], v[76:79], v[124:127], v[96:99]
	v_mfma_f32_16x16x32_bf16 v[84:87], v[68:71], v[132:135], v[84:87]
	v_mfma_f32_16x16x32_bf16 v[80:83], v[76:79], v[132:135], v[80:83]
	v_mfma_f32_16x16x32_bf16 v[12:15], v[68:71], v[140:143], v[12:15]
	v_mfma_f32_16x16x32_bf16 v[8:11], v[76:79], v[140:143], v[8:11]
	s_barrier
	s_mov_b32 m0, s50
	v_lshl_add_u64 v[42:43], v[144:145], 0, s[10:11]
	s_add_u32 s28, s28, 0x80080
	global_load_lds_dwordx4 v[42:43], off
	v_lshl_add_u64 v[42:43], v[146:147], 0, s[10:11]
	s_mov_b32 m0, s51
	s_addc_u32 s29, s29, 0
	global_load_lds_dwordx4 v[42:43], off
	v_lshl_add_u64 v[42:43], s[28:29], 0, v[26:27]
	s_mov_b32 m0, s52
	s_nop 0
	global_load_lds_dwordx4 v[42:43], off
	v_lshl_add_u64 v[42:43], s[28:29], 0, v[30:31]
	s_mov_b32 m0, s53
	s_nop 0
	global_load_lds_dwordx4 v[42:43], off
	v_lshl_add_u64 v[42:43], v[148:149], 0, s[10:11]
	s_mov_b32 m0, s37
	s_nop 0
	global_load_lds_dwordx4 v[42:43], off
	v_lshl_add_u64 v[42:43], v[150:151], 0, s[10:11]
	s_mov_b32 m0, s38
	s_nop 0
	global_load_lds_dwordx4 v[42:43], off
	s_waitcnt vmcnt(6)
	s_barrier
	v_mfma_f32_16x16x32_bf16 v[44:47], v[104:107], v[112:115], v[44:47]
	v_mfma_f32_16x16x32_bf16 v[48:51], v[108:111], v[116:119], v[44:47]
	v_mfma_f32_16x16x32_bf16 v[44:47], v[88:91], v[120:123], v[52:55]
	v_mfma_f32_16x16x32_bf16 v[76:79], v[92:95], v[124:127], v[44:47]
	v_mfma_f32_16x16x32_bf16 v[44:47], v[104:107], v[120:123], v[56:59]
	v_mfma_f32_16x16x32_bf16 v[72:75], v[108:111], v[124:127], v[44:47]
	v_mfma_f32_16x16x32_bf16 v[44:47], v[88:91], v[128:131], v[64:67]
	v_mfma_f32_16x16x32_bf16 v[38:41], v[88:91], v[112:115], v[38:41]
	v_mfma_f32_16x16x32_bf16 v[68:71], v[92:95], v[132:135], v[44:47]
	v_mfma_f32_16x16x32_bf16 v[44:47], v[104:107], v[128:131], v[60:63]
	v_mfma_f32_16x16x32_bf16 v[4:7], v[88:91], v[136:139], v[4:7]
	v_mfma_f32_16x16x32_bf16 v[0:3], v[104:107], v[136:139], v[0:3]
	v_mfma_f32_16x16x32_bf16 v[40:43], v[92:95], v[116:119], v[38:41]
	v_mfma_f32_16x16x32_bf16 v[60:63], v[108:111], v[132:135], v[44:47]
	v_mfma_f32_16x16x32_bf16 v[4:7], v[92:95], v[140:143], v[4:7]
	v_mfma_f32_16x16x32_bf16 v[0:3], v[108:111], v[140:143], v[0:3]
	s_add_i32 s43, s43, 2
	s_add_u32 s39, s39, 0x100
	s_addc_u32 s42, s42, 0
	s_add_u32 s30, s30, 0x100
	s_addc_u32 s31, s31, 0
	s_cmp_gt_u32 s43, 29
	s_barrier
	s_cbranch_scc0 .LBB0_769
	s_cmpk_lt_u32 s34, 0x100
	s_cselect_b64 s[28:29], -1, 0
	s_and_b64 vcc, exec, s[28:29]
	s_cbranch_vccz .LBB0_772
	s_barrier

;     __host__ __device__ bool next(int i, Unit& u) const { const long L = (long)i * G + c; if (L >= maxL) return false; return unit_of(L, u); }
;     __device__ __forceinline__ const char* a_base(const Gemm& g, const Unit& u, size_t tstep) const { return (const char*)g.A + (size_t)u.pm * tstep; }
;     __device__ __forceinline__ const char* b_base(const Gemm& g, const Unit& u, size_t tstep) const { return (const char*)g.Bt + (size_t)u.pn * tstep; }
; #define PG8_STAGE(bufoff, gbase, voff) do { _Pragma("unroll") for (int _i = 0; _i < 2; ++_i) \
;         __builtin_amdgcn_global_load_lds((const unsigned*)((const char*)(gbase) + (voff)[_i]), (PG8_LAS unsigned*)(lds + (bufoff) + ldsw + _i * 8192), 16, 0, 0); } while (0)
; #define PG8_LDA(dst, b, h) do { _Pragma("unroll") for (int m = 0; m < 4; ++m) _Pragma("unroll") for (int k = 0; k < 2; ++k) dst[m][k] = *(const PG8_LAS bf16x8*)(lds + PG8_SA(b, h) + aoff + m * 2048 + k * 1024); } while (0)
; #define PG8_WAIT_V(n) asm volatile("s_waitcnt vmcnt(" #n ")" ::: "memory")
; #define PG8_BAR __builtin_amdgcn_s_barrier()
; template <class Epi, class Sched, bool ALIGN_EPI = false, bool SP2 = false>
; __device__ __forceinline__ void gemm_phase(PG8_LAS unsigned char* lds, const Gemm g, const Sched& S, const Epi& E, const int wave_id_in) {
;     ...
;         const bool has_next = S.next(ui + 1, nxt);
;         const char* nA = has_next ? S.a_base(g, nxt, tstep) : cA; const char* nB = has_next ? S.b_base(g, nxt, tstep) : cB;
;         for (int t = 0; t < nt; t += 2) {
;             const bool last = (t == nt - 2);
;             const char* a1 = cA + (size_t)(t + 1) * kstep;
;             const char* a2 = last ? nA : cA + (size_t)(t + 2) * kstep; const char* b2 = last ? nB : cB + (size_t)(t + 2) * kstep;
;             const char* a3 = a2 + kstep; const char* b3 = b2 + kstep;
;             if (last && has_next) S.a_ready(nxt);
;             if constexpr (SP2) {
;             PG8_LDB(B0, 0, 0); PG8_LDB(B1, 0, 1); PG8_SCHED; PG8_LDA(At, 0, 0); PG8_STAGE(PG8_SA(1, 1), a1 + hstep, voffA);
;             PG8_WAIT_V(8); PG8_WAIT_L(0); PG8_BAR; __builtin_amdgcn_s_setprio(1); PG8_MMA(0, 0, At, B0); PG8_MMA(0, 1, At, B1); __builtin_amdgcn_s_setprio(0); PG8_BAR; PG8_SCHED;
;             PG8_LDA(At, 0, 1); PG8_STAGE(PG8_SB(0, 0), b2, voffB); PG8_STAGE(PG8_SB(0, 1), b2 + hstep, voffB); PG8_STAGE(PG8_SA(0, 0), a2, voffA);
.LBB0_818:
	s_ashr_i32 s67, s66, 31
	s_lshl_b64 s[68:69], s[66:67], 20
	s_add_u32 s68, s78, s68
	s_addc_u32 s69, s79, s69
	s_and_b64 s[70:71], s[6:7], exec
	s_cselect_b32 s9, s69, s11
	s_cselect_b32 s27, s68, s10
	s_ashr_i32 s65, s64, 31
	s_lshl_b64 s[70:71], s[64:65], 20
	s_add_u32 s70, s44, s70
	s_addc_u32 s71, s45, s71
	s_and_b64 s[72:73], s[6:7], exec
	s_cselect_b32 s65, s71, s13
	s_cselect_b32 s74, s70, s12
	s_add_u32 s10, s10, 0x80080
	s_addc_u32 s11, s11, 0
	s_add_u32 s75, s12, 0x100
	s_addc_u32 vcc_lo, s13, 0
	s_mov_b32 vcc_hi, -2
	s_waitcnt lgkmcnt(0)
	ds_read_b128 v[44:47], v221
	ds_read_b128 v[48:51], v221 offset:1024
	ds_read_b128 v[56:59], v221 offset:2048
	s_waitcnt lgkmcnt(0)
	ds_read_b128 v[60:63], v221 offset:3072
	ds_read_b128 v[68:71], v222
	ds_read_b128 v[72:75], v222 offset:1024
	ds_read_b128 v[76:79], v222 offset:2048
	ds_read_b128 v[84:87], v222 offset:3072
	s_add_u32 s12, s10, 0xfff80080
	s_addc_u32 s13, s11, -1
	s_cmp_eq_u32 vcc_hi, 28
	s_cselect_b32 s73, s9, s13
	s_cselect_b32 s72, s27, s12
	s_cselect_b32 s13, s65, vcc_lo
	s_cselect_b32 s12, s74, s75
	v_lshl_add_u64 v[208:209], s[10:11], 0, v[194:195]
	s_add_i32 m0, s81, 0xc000
	ds_read_b128 v[92:95], v223
	ds_read_b128 v[96:99], v223 offset:1024
	ds_read_b128 v[120:123], v223 offset:2048
	ds_read_b128 v[124:127], v223 offset:3072
	ds_read_b128 v[168:171], v223 offset:4096
	ds_read_b128 v[180:183], v223 offset:5120
	ds_read_b128 v[200:203], v223 offset:6144
	ds_read_b128 v[204:207], v223 offset:7168
	global_load_lds_dwordx4 v[208:209], off
	v_lshl_add_u64 v[208:209], s[10:11], 0, v[196:197]
	s_add_i32 m0, s81, 0xe000
	s_nop 0
	global_load_lds_dwordx4 v[208:209], off
	s_waitcnt vmcnt(8)
	s_waitcnt lgkmcnt(0)
	s_barrier
	v_mfma_f32_16x16x32_bf16 v[40:43], v[44:47], v[92:95], 0
	v_mfma_f32_16x16x32_bf16 v[36:39], v[56:59], v[92:95], 0
	v_mfma_f32_16x16x32_bf16 v[104:107], v[68:71], v[92:95], 0
	v_mfma_f32_16x16x32_bf16 v[92:95], v[76:79], v[92:95], 0
	v_mfma_f32_16x16x32_bf16 v[108:111], v[76:79], v[120:123], 0
	v_mfma_f32_16x16x32_bf16 v[40:43], v[48:51], v[96:99], v[40:43]
	v_mfma_f32_16x16x32_bf16 v[36:39], v[60:63], v[96:99], v[36:39]
	v_mfma_f32_16x16x32_bf16 v[172:175], v[44:47], v[120:123], 0
	v_mfma_f32_16x16x32_bf16 v[164:167], v[56:59], v[120:123], 0
	v_mfma_f32_16x16x32_bf16 v[104:107], v[72:75], v[96:99], v[104:107]
	v_mfma_f32_16x16x32_bf16 v[92:95], v[84:87], v[96:99], v[92:95]
	v_mfma_f32_16x16x32_bf16 v[96:99], v[68:71], v[120:123], 0
	v_mfma_f32_16x16x32_bf16 v[120:123], v[84:87], v[124:127], v[108:111]
	v_mfma_f32_16x16x32_bf16 v[108:111], v[68:71], v[168:171], 0
	v_mfma_f32_16x16x32_bf16 v[172:175], v[48:51], v[124:127], v[172:175]
	v_mfma_f32_16x16x32_bf16 v[164:167], v[60:63], v[124:127], v[164:167]
	v_mfma_f32_16x16x32_bf16 v[96:99], v[72:75], v[124:127], v[96:99]
	v_mfma_f32_16x16x32_bf16 v[124:127], v[72:75], v[180:183], v[108:111]
	v_mfma_f32_16x16x32_bf16 v[108:111], v[76:79], v[168:171], 0
	v_mfma_f32_16x16x32_bf16 v[136:139], v[84:87], v[180:183], v[108:111]
	v_mfma_f32_16x16x32_bf16 v[108:111], v[68:71], v[200:203], 0
	v_mfma_f32_16x16x32_bf16 v[156:159], v[44:47], v[168:171], 0
	v_mfma_f32_16x16x32_bf16 v[152:155], v[56:59], v[168:171], 0
	v_mfma_f32_16x16x32_bf16 v[160:163], v[44:47], v[200:203], 0
	v_mfma_f32_16x16x32_bf16 v[132:135], v[56:59], v[200:203], 0
	v_mfma_f32_16x16x32_bf16 v[116:119], v[72:75], v[204:207], v[108:111]
	v_mfma_f32_16x16x32_bf16 v[108:111], v[76:79], v[200:203], 0
	v_mfma_f32_16x16x32_bf16 v[156:159], v[48:51], v[180:183], v[156:159]
	v_mfma_f32_16x16x32_bf16 v[152:155], v[60:63], v[180:183], v[152:155]
	v_mfma_f32_16x16x32_bf16 v[160:163], v[48:51], v[204:207], v[160:163]
	v_mfma_f32_16x16x32_bf16 v[132:135], v[60:63], v[204:207], v[132:135]
	v_mfma_f32_16x16x32_bf16 v[112:115], v[84:87], v[204:207], v[108:111]
	s_barrier
	s_add_i32 s40, s5, s80
	v_lshl_add_u64 v[216:217], s[12:13], 0, v[186:187]
	s_mov_b32 m0, s40
	ds_read_b128 v[108:111], v223 offset:16384
	ds_read_b128 v[140:143], v223 offset:17408
	ds_read_b128 v[144:147], v223 offset:18432
	ds_read_b128 v[148:151], v223 offset:19456
	ds_read_b128 v[168:171], v223 offset:20480
	ds_read_b128 v[180:183], v223 offset:21504
	ds_read_b128 v[200:203], v223 offset:22528
	ds_read_b128 v[204:207], v223 offset:23552
	global_load_lds_dwordx4 v[216:217], off
	s_add_i32 m0, s40, 0x2000
	s_add_u32 s40, s12, 0x80000
	v_lshl_add_u64 v[218:219], s[12:13], 0, v[190:191]
	s_addc_u32 s41, s13, 0
	s_add_i32 s77, s28, s80
	global_load_lds_dwordx4 v[218:219], off
	v_lshl_add_u64 v[208:209], s[40:41], 0, v[186:187]
	s_mov_b32 m0, s77
	v_lshl_add_u64 v[226:227], s[72:73], 0, v[184:185]
	global_load_lds_dwordx4 v[208:209], off
	v_lshl_add_u64 v[208:209], s[40:41], 0, v[190:191]
	s_add_i32 m0, s77, 0x2000
	v_lshl_add_u64 v[228:229], s[72:73], 0, v[188:189]
	global_load_lds_dwordx4 v[208:209], off
	s_mov_b32 m0, s81
	s_nop 0
	global_load_lds_dwordx4 v[226:227], off
	s_mov_b32 m0, s82
	s_nop 0
	global_load_lds_dwordx4 v[228:229], off
	s_waitcnt vmcnt(8)
	s_waitcnt lgkmcnt(0)
	s_barrier
; #define PG8_STAGE(bufoff, gbase, voff) do { _Pragma("unroll") for (int _i = 0; _i < 2; ++_i) \
;         __builtin_amdgcn_global_load_lds((const unsigned*)((const char*)(gbase) + (voff)[_i]), (PG8_LAS unsigned*)(lds + (bufoff) + ldsw + _i * 8192), 16, 0, 0); } while (0)
; #define PG8_LDA(dst, b, h) do { _Pragma("unroll") for (int m = 0; m < 4; ++m) _Pragma("unroll") for (int k = 0; k < 2; ++k) dst[m][k] = *(const PG8_LAS bf16x8*)(lds + PG8_SA(b, h) + aoff + m * 2048 + k * 1024); } while (0)
; #define PG8_LDB(dst, b, h) do { _Pragma("unroll") for (int n = 0; n < 2; ++n) _Pragma("unroll") for (int k = 0; k < 2; ++k) dst[n][k] = *(const PG8_LAS bf16x8*)(lds + PG8_SB(b, h) + boff + n * 2048 + k * 1024); } while (0)
; #define PG8_MMA(ai, bj, At, Bt) do { _Pragma("unroll") for (int m = 0; m < 4; ++m) _Pragma("unroll") for (int n = 0; n < 2; ++n) _Pragma("unroll") for (int k = 0; k < 2; ++k) \
;         acc[ai][bj][m][n] = __builtin_amdgcn_mfma_f32_16x16x32_bf16(Bt[n][k], At[m][k], acc[ai][bj][m][n], 0, 0, 0); } while (0)
; #define PG8_WAIT_V(n) asm volatile("s_waitcnt vmcnt(" #n ")" ::: "memory")
; #define PG8_WAIT_L(n) asm volatile("s_waitcnt lgkmcnt(" #n ")" ::: "memory")
; #define PG8_BAR __builtin_amdgcn_s_barrier()
; #define PG8_SCHED __builtin_amdgcn_sched_barrier(0)
; template <class Epi, class Sched, bool ALIGN_EPI = false, bool SP2 = false>
; __device__ __forceinline__ void gemm_phase(PG8_LAS unsigned char* lds, const Gemm g, const Sched& S, const Epi& E, const int wave_id_in) {
;     ...
;             PG8_WAIT_V(8); PG8_WAIT_L(0); PG8_BAR; __builtin_amdgcn_s_setprio(1); PG8_MMA(1, 0, At, B0); PG8_MMA(1, 1, At, B1); __builtin_amdgcn_s_setprio(0); PG8_BAR; PG8_SCHED;
;             PG8_LDB(B0, 1, 0); PG8_LDB(B1, 1, 1); PG8_SCHED; PG8_LDA(At, 1, 0); PG8_STAGE(PG8_SA(0, 1), a2 + hstep, voffA);
;             PG8_WAIT_V(8); PG8_WAIT_L(0); PG8_BAR; __builtin_amdgcn_s_setprio(1); PG8_MMA(0, 0, At, B0); PG8_MMA(0, 1, At, B1); __builtin_amdgcn_s_setprio(0); PG8_BAR; PG8_SCHED;
	v_mfma_f32_16x16x32_bf16 v[128:131], v[44:47], v[108:111], 0
	v_mfma_f32_16x16x32_bf16 v[64:67], v[56:59], v[108:111], 0
	v_mfma_f32_16x16x32_bf16 v[100:103], v[44:47], v[144:147], 0
	v_mfma_f32_16x16x32_bf16 v[88:91], v[56:59], v[144:147], 0
	v_mfma_f32_16x16x32_bf16 v[28:31], v[44:47], v[168:171], 0
	v_mfma_f32_16x16x32_bf16 v[24:27], v[56:59], v[168:171], 0
	v_mfma_f32_16x16x32_bf16 v[44:47], v[44:47], v[200:203], 0
	v_mfma_f32_16x16x32_bf16 v[32:35], v[76:79], v[108:111], 0
	v_mfma_f32_16x16x32_bf16 v[20:23], v[68:71], v[144:147], 0
	v_mfma_f32_16x16x32_bf16 v[16:19], v[76:79], v[144:147], 0
	v_mfma_f32_16x16x32_bf16 v[12:15], v[68:71], v[168:171], 0
	v_mfma_f32_16x16x32_bf16 v[8:11], v[76:79], v[168:171], 0
	v_mfma_f32_16x16x32_bf16 v[4:7], v[68:71], v[200:203], 0
	v_mfma_f32_16x16x32_bf16 v[0:3], v[76:79], v[200:203], 0
	v_mfma_f32_16x16x32_bf16 v[128:131], v[48:51], v[140:143], v[128:131]
	v_mfma_f32_16x16x32_bf16 v[64:67], v[60:63], v[140:143], v[64:67]
	v_mfma_f32_16x16x32_bf16 v[100:103], v[48:51], v[148:151], v[100:103]
	v_mfma_f32_16x16x32_bf16 v[88:91], v[60:63], v[148:151], v[88:91]
	v_mfma_f32_16x16x32_bf16 v[28:31], v[48:51], v[180:183], v[28:31]
	v_mfma_f32_16x16x32_bf16 v[24:27], v[60:63], v[180:183], v[24:27]
	v_mfma_f32_16x16x32_bf16 v[44:47], v[48:51], v[204:207], v[44:47]
	v_mfma_f32_16x16x32_bf16 v[48:51], v[56:59], v[200:203], 0
	v_mfma_f32_16x16x32_bf16 v[52:55], v[68:71], v[108:111], 0
	v_mfma_f32_16x16x32_bf16 v[32:35], v[84:87], v[140:143], v[32:35]
	v_mfma_f32_16x16x32_bf16 v[20:23], v[72:75], v[148:151], v[20:23]
	v_mfma_f32_16x16x32_bf16 v[16:19], v[84:87], v[148:151], v[16:19]
	v_mfma_f32_16x16x32_bf16 v[12:15], v[72:75], v[180:183], v[12:15]
	v_mfma_f32_16x16x32_bf16 v[8:11], v[84:87], v[180:183], v[8:11]
	v_mfma_f32_16x16x32_bf16 v[4:7], v[72:75], v[204:207], v[4:7]
	v_mfma_f32_16x16x32_bf16 v[0:3], v[84:87], v[204:207], v[0:3]
	v_mfma_f32_16x16x32_bf16 v[48:51], v[60:63], v[204:207], v[48:51]
	v_mfma_f32_16x16x32_bf16 v[56:59], v[72:75], v[140:143], v[52:55]
	s_barrier
	s_add_i32 s77, 0, 0x18000
	s_add_i32 s76, 0, 0x1c000
	v_add_u32_e32 v72, s77, v220
	v_add_u32_e32 v80, s76, v220
	ds_read_b128 v[52:55], v72
	ds_read_b128 v[60:63], v72 offset:1024
	ds_read_b128 v[68:71], v72 offset:2048
	ds_read_b128 v[72:75], v72 offset:3072
	ds_read_b128 v[76:79], v80
	ds_read_b128 v[84:87], v80 offset:1024
	ds_read_b128 v[168:171], v80 offset:2048
	ds_read_b128 v[180:183], v80 offset:3072
	s_add_u32 s40, s72, 0x80000
	s_addc_u32 s41, s73, 0
	s_mov_b32 m0, s83
	v_lshl_add_u64 v[148:149], s[40:41], 0, v[184:185]
	ds_read_b128 v[80:83], v223 offset:32768
	ds_read_b128 v[108:111], v223 offset:33792
	ds_read_b128 v[140:143], v223 offset:34816
	ds_read_b128 v[144:147], v223 offset:35840
	ds_read_b128 v[176:179], v223 offset:36864
	ds_read_b128 v[200:203], v223 offset:37888
	ds_read_b128 v[204:207], v223 offset:38912
	ds_read_b128 v[208:211], v223 offset:39936
	global_load_lds_dwordx4 v[148:149], off
	v_lshl_add_u64 v[148:149], s[40:41], 0, v[188:189]
	s_mov_b32 m0, s84
	s_nop 0
	global_load_lds_dwordx4 v[148:149], off
	s_waitcnt vmcnt(8)
	s_waitcnt lgkmcnt(0)
	s_barrier
	v_mfma_f32_16x16x32_bf16 v[148:151], v[52:55], v[140:143], v[172:175]
	v_mfma_f32_16x16x32_bf16 v[172:175], v[60:63], v[144:147], v[148:151]
	v_mfma_f32_16x16x32_bf16 v[148:151], v[68:71], v[140:143], v[164:167]
	v_mfma_f32_16x16x32_bf16 v[164:167], v[72:75], v[144:147], v[148:151]
	v_mfma_f32_16x16x32_bf16 v[148:151], v[52:55], v[176:179], v[156:159]
	v_mfma_f32_16x16x32_bf16 v[40:43], v[52:55], v[80:83], v[40:43]
	v_mfma_f32_16x16x32_bf16 v[36:39], v[68:71], v[80:83], v[36:39]
	v_mfma_f32_16x16x32_bf16 v[156:159], v[60:63], v[200:203], v[148:151]
	v_mfma_f32_16x16x32_bf16 v[148:151], v[68:71], v[176:179], v[152:155]
	v_mfma_f32_16x16x32_bf16 v[104:107], v[76:79], v[80:83], v[104:107]
	v_mfma_f32_16x16x32_bf16 v[80:83], v[168:171], v[80:83], v[92:95]
	v_mfma_f32_16x16x32_bf16 v[40:43], v[60:63], v[108:111], v[40:43]
	v_mfma_f32_16x16x32_bf16 v[36:39], v[72:75], v[108:111], v[36:39]
	v_mfma_f32_16x16x32_bf16 v[152:155], v[72:75], v[200:203], v[148:151]
	v_mfma_f32_16x16x32_bf16 v[148:151], v[52:55], v[204:207], v[160:163]
	v_mfma_f32_16x16x32_bf16 v[104:107], v[84:87], v[108:111], v[104:107]
	v_mfma_f32_16x16x32_bf16 v[108:111], v[180:183], v[108:111], v[80:83]
	v_mfma_f32_16x16x32_bf16 v[80:83], v[76:79], v[140:143], v[96:99]
	v_mfma_f32_16x16x32_bf16 v[160:163], v[60:63], v[208:211], v[148:151]
	v_mfma_f32_16x16x32_bf16 v[148:151], v[84:87], v[144:147], v[80:83]
	v_mfma_f32_16x16x32_bf16 v[80:83], v[168:171], v[140:143], v[120:123]
	v_mfma_f32_16x16x32_bf16 v[144:147], v[180:183], v[144:147], v[80:83]
	v_mfma_f32_16x16x32_bf16 v[80:83], v[76:79], v[176:179], v[124:127]
	v_mfma_f32_16x16x32_bf16 v[140:143], v[84:87], v[200:203], v[80:83]
	v_mfma_f32_16x16x32_bf16 v[80:83], v[168:171], v[176:179], v[136:139]
	v_mfma_f32_16x16x32_bf16 v[136:139], v[180:183], v[200:203], v[80:83]
	v_mfma_f32_16x16x32_bf16 v[80:83], v[76:79], v[204:207], v[116:119]
	v_mfma_f32_16x16x32_bf16 v[132:135], v[68:71], v[204:207], v[132:135]
	v_mfma_f32_16x16x32_bf16 v[116:119], v[84:87], v[208:211], v[80:83]
	v_mfma_f32_16x16x32_bf16 v[80:83], v[168:171], v[204:207], v[112:115]
	v_mfma_f32_16x16x32_bf16 v[132:135], v[72:75], v[208:211], v[132:135]
	v_mfma_f32_16x16x32_bf16 v[112:115], v[180:183], v[208:211], v[80:83]
	s_barrier
; #define PG8_STAGE(bufoff, gbase, voff) do { _Pragma("unroll") for (int _i = 0; _i < 2; ++_i) \
;         __builtin_amdgcn_global_load_lds((const unsigned*)((const char*)(gbase) + (voff)[_i]), (PG8_LAS unsigned*)(lds + (bufoff) + ldsw + _i * 8192), 16, 0, 0); } while (0)
; #define PG8_LDA(dst, b, h) do { _Pragma("unroll") for (int m = 0; m < 4; ++m) _Pragma("unroll") for (int k = 0; k < 2; ++k) dst[m][k] = *(const PG8_LAS bf16x8*)(lds + PG8_SA(b, h) + aoff + m * 2048 + k * 1024); } while (0)
; #define PG8_LDB(dst, b, h) do { _Pragma("unroll") for (int n = 0; n < 2; ++n) _Pragma("unroll") for (int k = 0; k < 2; ++k) dst[n][k] = *(const PG8_LAS bf16x8*)(lds + PG8_SB(b, h) + boff + n * 2048 + k * 1024); } while (0)
; #define PG8_MMA(ai, bj, At, Bt) do { _Pragma("unroll") for (int m = 0; m < 4; ++m) _Pragma("unroll") for (int n = 0; n < 2; ++n) _Pragma("unroll") for (int k = 0; k < 2; ++k) \
;         acc[ai][bj][m][n] = __builtin_amdgcn_mfma_f32_16x16x32_bf16(Bt[n][k], At[m][k], acc[ai][bj][m][n], 0, 0, 0); } while (0)
; #define PG8_WAIT_V(n) asm volatile("s_waitcnt vmcnt(" #n ")" ::: "memory")
; #define PG8_WAIT_L(n) asm volatile("s_waitcnt lgkmcnt(" #n ")" ::: "memory")
; #define PG8_BAR __builtin_amdgcn_s_barrier()
; #define PG8_SCHED __builtin_amdgcn_sched_barrier(0)
; template <class Epi, class Sched, bool ALIGN_EPI = false, bool SP2 = false>
; __device__ __forceinline__ void gemm_phase(PG8_LAS unsigned char* lds, const Gemm g, const Sched& S, const Epi& E, const int wave_id_in) {
;     ...
;             PG8_LDB(B0, 0, 0); PG8_LDB(B1, 0, 1); PG8_SCHED; PG8_LDA(At, 0, 0); PG8_STAGE(PG8_SA(1, 1), a1 + hstep, voffA);
;             PG8_WAIT_V(8); PG8_WAIT_L(0); PG8_BAR; __builtin_amdgcn_s_setprio(1); PG8_MMA(0, 0, At, B0); PG8_MMA(0, 1, At, B1); __builtin_amdgcn_s_setprio(0); PG8_BAR; PG8_SCHED;
;     ...
;             PG8_LDA(At, 1, 1); PG8_STAGE(PG8_SB(1, 0), b3, voffB); PG8_STAGE(PG8_SB(1, 1), b3 + hstep, voffB); PG8_STAGE(PG8_SA(1, 0), a3, voffA);
;             PG8_WAIT_V(8); PG8_WAIT_L(0); PG8_BAR; __builtin_amdgcn_s_setprio(1); PG8_MMA(1, 0, At, B0); PG8_MMA(1, 1, At, B1); __builtin_amdgcn_s_setprio(0); PG8_BAR; PG8_SCHED;
	s_add_i32 s40, s77, s80
	s_nop 2
	s_nop 0
	v_lshl_add_u64 v[80:81], v[216:217], 0, s[34:35]
	s_mov_b32 m0, s40
	ds_read_b128 v[92:95], v223 offset:49152
	ds_read_b128 v[96:99], v223 offset:50176
	ds_read_b128 v[120:123], v223 offset:51200
	ds_read_b128 v[124:127], v223 offset:52224
	ds_read_b128 v[200:203], v223 offset:53248
	ds_read_b128 v[204:207], v223 offset:54272
	ds_read_b128 v[208:211], v223 offset:55296
	ds_read_b128 v[212:215], v223 offset:56320
	global_load_lds_dwordx4 v[80:81], off
	s_add_i32 m0, s40, 0x2000
	s_add_u32 s12, s12, 0x80080
	v_lshl_add_u64 v[80:81], v[218:219], 0, s[34:35]
	s_addc_u32 s13, s13, 0
	s_add_i32 s40, s76, s80
	global_load_lds_dwordx4 v[80:81], off
	v_lshl_add_u64 v[80:81], s[12:13], 0, v[186:187]
	s_mov_b32 m0, s40
	s_nop 0
	global_load_lds_dwordx4 v[80:81], off
	v_lshl_add_u64 v[80:81], s[12:13], 0, v[190:191]
	s_add_i32 m0, s40, 0x2000
	s_nop 0
	global_load_lds_dwordx4 v[80:81], off
	v_lshl_add_u64 v[80:81], v[226:227], 0, s[34:35]
	s_mov_b32 m0, s87
	s_nop 0
	global_load_lds_dwordx4 v[80:81], off
	v_lshl_add_u64 v[80:81], v[228:229], 0, s[34:35]
	s_mov_b32 m0, s88
	s_nop 0
	global_load_lds_dwordx4 v[80:81], off
	s_waitcnt vmcnt(8)
	s_waitcnt lgkmcnt(0)
	s_barrier
	v_mfma_f32_16x16x32_bf16 v[80:83], v[52:55], v[92:95], v[128:131]
	v_mfma_f32_16x16x32_bf16 v[44:47], v[52:55], v[208:211], v[44:47]
	v_mfma_f32_16x16x32_bf16 v[128:131], v[60:63], v[96:99], v[80:83]
	v_mfma_f32_16x16x32_bf16 v[80:83], v[52:55], v[120:123], v[100:103]
	v_mfma_f32_16x16x32_bf16 v[176:179], v[60:63], v[212:215], v[44:47]
	v_mfma_f32_16x16x32_bf16 v[44:47], v[68:71], v[208:211], v[48:51]
	v_mfma_f32_16x16x32_bf16 v[64:67], v[68:71], v[92:95], v[64:67]
	v_mfma_f32_16x16x32_bf16 v[100:103], v[60:63], v[124:127], v[80:83]
	v_mfma_f32_16x16x32_bf16 v[80:83], v[68:71], v[120:123], v[88:91]
	v_mfma_f32_16x16x32_bf16 v[28:31], v[52:55], v[200:203], v[28:31]
	v_mfma_f32_16x16x32_bf16 v[24:27], v[68:71], v[200:203], v[24:27]
	v_mfma_f32_16x16x32_bf16 v[52:55], v[72:75], v[212:215], v[44:47]
	v_mfma_f32_16x16x32_bf16 v[44:47], v[76:79], v[92:95], v[56:59]
	v_mfma_f32_16x16x32_bf16 v[32:35], v[168:171], v[92:95], v[32:35]
	v_mfma_f32_16x16x32_bf16 v[20:23], v[76:79], v[120:123], v[20:23]
	v_mfma_f32_16x16x32_bf16 v[16:19], v[168:171], v[120:123], v[16:19]
	v_mfma_f32_16x16x32_bf16 v[12:15], v[76:79], v[200:203], v[12:15]
	v_mfma_f32_16x16x32_bf16 v[8:11], v[168:171], v[200:203], v[8:11]
	v_mfma_f32_16x16x32_bf16 v[4:7], v[76:79], v[208:211], v[4:7]
	v_mfma_f32_16x16x32_bf16 v[0:3], v[168:171], v[208:211], v[0:3]
	v_mfma_f32_16x16x32_bf16 v[64:67], v[72:75], v[96:99], v[64:67]
	v_mfma_f32_16x16x32_bf16 v[88:91], v[72:75], v[124:127], v[80:83]
	v_mfma_f32_16x16x32_bf16 v[28:31], v[60:63], v[204:207], v[28:31]
	v_mfma_f32_16x16x32_bf16 v[24:27], v[72:75], v[204:207], v[24:27]
	v_mfma_f32_16x16x32_bf16 v[80:83], v[84:87], v[96:99], v[44:47]
	v_mfma_f32_16x16x32_bf16 v[32:35], v[180:183], v[96:99], v[32:35]
	v_mfma_f32_16x16x32_bf16 v[20:23], v[84:87], v[124:127], v[20:23]
	v_mfma_f32_16x16x32_bf16 v[16:19], v[180:183], v[124:127], v[16:19]
	v_mfma_f32_16x16x32_bf16 v[12:15], v[84:87], v[204:207], v[12:15]
	v_mfma_f32_16x16x32_bf16 v[8:11], v[180:183], v[204:207], v[8:11]
	v_mfma_f32_16x16x32_bf16 v[4:7], v[84:87], v[212:215], v[4:7]
	v_mfma_f32_16x16x32_bf16 v[0:3], v[180:183], v[212:215], v[0:3]
	s_add_i32 vcc_hi, vcc_hi, 2
	s_add_u32 s10, s10, 0x100
	s_addc_u32 s11, s11, 0
	s_add_u32 s75, s75, 0x100
	s_addc_u32 vcc_lo, vcc_lo, 0
	s_cmp_gt_u32 vcc_hi, 29
	s_barrier
	s_cbranch_scc0 .LBB0_819
	s_branch .Lpeel_exit_ffnup
.LBB0_819:
	ds_read_b128 v[44:47], v221
	ds_read_b128 v[48:51], v221 offset:1024
	ds_read_b128 v[56:59], v221 offset:2048
	s_waitcnt lgkmcnt(0)
	ds_read_b128 v[60:63], v221 offset:3072
	ds_read_b128 v[68:71], v222
	ds_read_b128 v[72:75], v222 offset:1024
	ds_read_b128 v[76:79], v222 offset:2048
	ds_read_b128 v[84:87], v222 offset:3072
	s_add_u32 s12, s10, 0xfff80080
	s_addc_u32 s13, s11, -1
	s_cmp_eq_u32 vcc_hi, 28
	s_cselect_b32 s73, s9, s13
	s_cselect_b32 s72, s27, s12
	s_cselect_b32 s13, s65, vcc_lo
	s_cselect_b32 s12, s74, s75
	v_lshl_add_u64 v[208:209], s[10:11], 0, v[194:195]
	s_add_i32 m0, s81, 0xc000
	ds_read_b128 v[92:95], v223
	ds_read_b128 v[96:99], v223 offset:1024
	ds_read_b128 v[120:123], v223 offset:2048
	ds_read_b128 v[124:127], v223 offset:3072
	ds_read_b128 v[168:171], v223 offset:4096
	ds_read_b128 v[180:183], v223 offset:5120
	ds_read_b128 v[200:203], v223 offset:6144
	ds_read_b128 v[204:207], v223 offset:7168
	global_load_lds_dwordx4 v[208:209], off
	v_lshl_add_u64 v[208:209], s[10:11], 0, v[196:197]
	s_add_i32 m0, s81, 0xe000
	s_nop 0
	global_load_lds_dwordx4 v[208:209], off
	s_waitcnt vmcnt(8)
	s_waitcnt lgkmcnt(0)
	s_barrier
; #define PG8_STAGE(bufoff, gbase, voff) do { _Pragma("unroll") for (int _i = 0; _i < 2; ++_i) \
;         __builtin_amdgcn_global_load_lds((const unsigned*)((const char*)(gbase) + (voff)[_i]), (PG8_LAS unsigned*)(lds + (bufoff) + ldsw + _i * 8192), 16, 0, 0); } while (0)
; #define PG8_LDA(dst, b, h) do { _Pragma("unroll") for (int m = 0; m < 4; ++m) _Pragma("unroll") for (int k = 0; k < 2; ++k) dst[m][k] = *(const PG8_LAS bf16x8*)(lds + PG8_SA(b, h) + aoff + m * 2048 + k * 1024); } while (0)
; #define PG8_MMA(ai, bj, At, Bt) do { _Pragma("unroll") for (int m = 0; m < 4; ++m) _Pragma("unroll") for (int n = 0; n < 2; ++n) _Pragma("unroll") for (int k = 0; k < 2; ++k) \
;         acc[ai][bj][m][n] = __builtin_amdgcn_mfma_f32_16x16x32_bf16(Bt[n][k], At[m][k], acc[ai][bj][m][n], 0, 0, 0); } while (0)
; #define PG8_WAIT_V(n) asm volatile("s_waitcnt vmcnt(" #n ")" ::: "memory")
; #define PG8_WAIT_L(n) asm volatile("s_waitcnt lgkmcnt(" #n ")" ::: "memory")
; #define PG8_BAR __builtin_amdgcn_s_barrier()
; #define PG8_SCHED __builtin_amdgcn_sched_barrier(0)
; template <class Epi, class Sched, bool ALIGN_EPI = false, bool SP2 = false>
; __device__ __forceinline__ void gemm_phase(PG8_LAS unsigned char* lds, const Gemm g, const Sched& S, const Epi& E, const int wave_id_in) {
;     ...
;             PG8_WAIT_V(8); PG8_WAIT_L(0); PG8_BAR; __builtin_amdgcn_s_setprio(1); PG8_MMA(0, 0, At, B0); PG8_MMA(0, 1, At, B1); __builtin_amdgcn_s_setprio(0); PG8_BAR; PG8_SCHED;
;             PG8_LDA(At, 0, 1); PG8_STAGE(PG8_SB(0, 0), b2, voffB); PG8_STAGE(PG8_SB(0, 1), b2 + hstep, voffB); PG8_STAGE(PG8_SA(0, 0), a2, voffA);
;             PG8_WAIT_V(8); PG8_WAIT_L(0); PG8_BAR; __builtin_amdgcn_s_setprio(1); PG8_MMA(1, 0, At, B0); PG8_MMA(1, 1, At, B1); __builtin_amdgcn_s_setprio(0); PG8_BAR; PG8_SCHED;
	v_mfma_f32_16x16x32_bf16 v[40:43], v[44:47], v[92:95], v[40:43]
	v_mfma_f32_16x16x32_bf16 v[36:39], v[56:59], v[92:95], v[36:39]
	v_mfma_f32_16x16x32_bf16 v[104:107], v[68:71], v[92:95], v[104:107]
	v_mfma_f32_16x16x32_bf16 v[92:95], v[76:79], v[92:95], v[108:111]
	v_mfma_f32_16x16x32_bf16 v[108:111], v[76:79], v[120:123], v[144:147]
	v_mfma_f32_16x16x32_bf16 v[40:43], v[48:51], v[96:99], v[40:43]
	v_mfma_f32_16x16x32_bf16 v[36:39], v[60:63], v[96:99], v[36:39]
	v_mfma_f32_16x16x32_bf16 v[172:175], v[44:47], v[120:123], v[172:175]
	v_mfma_f32_16x16x32_bf16 v[164:167], v[56:59], v[120:123], v[164:167]
	v_mfma_f32_16x16x32_bf16 v[104:107], v[72:75], v[96:99], v[104:107]
	v_mfma_f32_16x16x32_bf16 v[92:95], v[84:87], v[96:99], v[92:95]
	v_mfma_f32_16x16x32_bf16 v[96:99], v[68:71], v[120:123], v[148:151]
	v_mfma_f32_16x16x32_bf16 v[120:123], v[84:87], v[124:127], v[108:111]
	v_mfma_f32_16x16x32_bf16 v[108:111], v[68:71], v[168:171], v[140:143]
	v_mfma_f32_16x16x32_bf16 v[172:175], v[48:51], v[124:127], v[172:175]
	v_mfma_f32_16x16x32_bf16 v[164:167], v[60:63], v[124:127], v[164:167]
	v_mfma_f32_16x16x32_bf16 v[96:99], v[72:75], v[124:127], v[96:99]
	v_mfma_f32_16x16x32_bf16 v[124:127], v[72:75], v[180:183], v[108:111]
	v_mfma_f32_16x16x32_bf16 v[108:111], v[76:79], v[168:171], v[136:139]
	v_mfma_f32_16x16x32_bf16 v[136:139], v[84:87], v[180:183], v[108:111]
	v_mfma_f32_16x16x32_bf16 v[108:111], v[68:71], v[200:203], v[116:119]
	v_mfma_f32_16x16x32_bf16 v[156:159], v[44:47], v[168:171], v[156:159]
	v_mfma_f32_16x16x32_bf16 v[152:155], v[56:59], v[168:171], v[152:155]
	v_mfma_f32_16x16x32_bf16 v[160:163], v[44:47], v[200:203], v[160:163]
	v_mfma_f32_16x16x32_bf16 v[132:135], v[56:59], v[200:203], v[132:135]
	v_mfma_f32_16x16x32_bf16 v[116:119], v[72:75], v[204:207], v[108:111]
	v_mfma_f32_16x16x32_bf16 v[108:111], v[76:79], v[200:203], v[112:115]
	v_mfma_f32_16x16x32_bf16 v[156:159], v[48:51], v[180:183], v[156:159]
	v_mfma_f32_16x16x32_bf16 v[152:155], v[60:63], v[180:183], v[152:155]
	v_mfma_f32_16x16x32_bf16 v[160:163], v[48:51], v[204:207], v[160:163]
	v_mfma_f32_16x16x32_bf16 v[132:135], v[60:63], v[204:207], v[132:135]
	v_mfma_f32_16x16x32_bf16 v[112:115], v[84:87], v[204:207], v[108:111]
	s_barrier
	s_add_i32 s40, s5, s80
	v_lshl_add_u64 v[216:217], s[12:13], 0, v[186:187]
	s_mov_b32 m0, s40
	ds_read_b128 v[108:111], v223 offset:16384
	ds_read_b128 v[140:143], v223 offset:17408
	ds_read_b128 v[144:147], v223 offset:18432
	ds_read_b128 v[148:151], v223 offset:19456
	ds_read_b128 v[168:171], v223 offset:20480
	ds_read_b128 v[180:183], v223 offset:21504
	ds_read_b128 v[200:203], v223 offset:22528
	ds_read_b128 v[204:207], v223 offset:23552
	global_load_lds_dwordx4 v[216:217], off
	s_add_i32 m0, s40, 0x2000
	s_add_u32 s40, s12, 0x80000
	v_lshl_add_u64 v[218:219], s[12:13], 0, v[190:191]
	s_addc_u32 s41, s13, 0
	s_add_i32 s77, s28, s80
	global_load_lds_dwordx4 v[218:219], off
	v_lshl_add_u64 v[208:209], s[40:41], 0, v[186:187]
	s_mov_b32 m0, s77
	v_lshl_add_u64 v[226:227], s[72:73], 0, v[184:185]
	global_load_lds_dwordx4 v[208:209], off
	v_lshl_add_u64 v[208:209], s[40:41], 0, v[190:191]
	s_add_i32 m0, s77, 0x2000
	v_lshl_add_u64 v[228:229], s[72:73], 0, v[188:189]
	global_load_lds_dwordx4 v[208:209], off
	s_mov_b32 m0, s81
	s_nop 0
	global_load_lds_dwordx4 v[226:227], off
	s_mov_b32 m0, s82
	s_nop 0
	global_load_lds_dwordx4 v[228:229], off
	s_waitcnt vmcnt(8)
	s_waitcnt lgkmcnt(0)
	s_barrier
	v_mfma_f32_16x16x32_bf16 v[128:131], v[44:47], v[108:111], v[128:131]
	v_mfma_f32_16x16x32_bf16 v[64:67], v[56:59], v[108:111], v[64:67]
	v_mfma_f32_16x16x32_bf16 v[100:103], v[44:47], v[144:147], v[100:103]
	v_mfma_f32_16x16x32_bf16 v[88:91], v[56:59], v[144:147], v[88:91]
	v_mfma_f32_16x16x32_bf16 v[28:31], v[44:47], v[168:171], v[28:31]
	v_mfma_f32_16x16x32_bf16 v[24:27], v[56:59], v[168:171], v[24:27]
	v_mfma_f32_16x16x32_bf16 v[44:47], v[44:47], v[200:203], v[176:179]
	v_mfma_f32_16x16x32_bf16 v[32:35], v[76:79], v[108:111], v[32:35]
	v_mfma_f32_16x16x32_bf16 v[20:23], v[68:71], v[144:147], v[20:23]
	v_mfma_f32_16x16x32_bf16 v[16:19], v[76:79], v[144:147], v[16:19]
	v_mfma_f32_16x16x32_bf16 v[12:15], v[68:71], v[168:171], v[12:15]
	v_mfma_f32_16x16x32_bf16 v[8:11], v[76:79], v[168:171], v[8:11]
	v_mfma_f32_16x16x32_bf16 v[4:7], v[68:71], v[200:203], v[4:7]
	v_mfma_f32_16x16x32_bf16 v[0:3], v[76:79], v[200:203], v[0:3]
	v_mfma_f32_16x16x32_bf16 v[128:131], v[48:51], v[140:143], v[128:131]
	v_mfma_f32_16x16x32_bf16 v[64:67], v[60:63], v[140:143], v[64:67]
	v_mfma_f32_16x16x32_bf16 v[100:103], v[48:51], v[148:151], v[100:103]
	v_mfma_f32_16x16x32_bf16 v[88:91], v[60:63], v[148:151], v[88:91]
	v_mfma_f32_16x16x32_bf16 v[28:31], v[48:51], v[180:183], v[28:31]
	v_mfma_f32_16x16x32_bf16 v[24:27], v[60:63], v[180:183], v[24:27]
	v_mfma_f32_16x16x32_bf16 v[44:47], v[48:51], v[204:207], v[44:47]
	v_mfma_f32_16x16x32_bf16 v[48:51], v[56:59], v[200:203], v[52:55]
	v_mfma_f32_16x16x32_bf16 v[52:55], v[68:71], v[108:111], v[80:83]
	v_mfma_f32_16x16x32_bf16 v[32:35], v[84:87], v[140:143], v[32:35]
	v_mfma_f32_16x16x32_bf16 v[20:23], v[72:75], v[148:151], v[20:23]
	v_mfma_f32_16x16x32_bf16 v[16:19], v[84:87], v[148:151], v[16:19]
	v_mfma_f32_16x16x32_bf16 v[12:15], v[72:75], v[180:183], v[12:15]
	v_mfma_f32_16x16x32_bf16 v[8:11], v[84:87], v[180:183], v[8:11]
	v_mfma_f32_16x16x32_bf16 v[4:7], v[72:75], v[204:207], v[4:7]
	v_mfma_f32_16x16x32_bf16 v[0:3], v[84:87], v[204:207], v[0:3]
	v_mfma_f32_16x16x32_bf16 v[48:51], v[60:63], v[204:207], v[48:51]
	v_mfma_f32_16x16x32_bf16 v[56:59], v[72:75], v[140:143], v[52:55]
	s_barrier
; #define PG8_STAGE(bufoff, gbase, voff) do { _Pragma("unroll") for (int _i = 0; _i < 2; ++_i) \
;         __builtin_amdgcn_global_load_lds((const unsigned*)((const char*)(gbase) + (voff)[_i]), (PG8_LAS unsigned*)(lds + (bufoff) + ldsw + _i * 8192), 16, 0, 0); } while (0)
; #define PG8_LDA(dst, b, h) do { _Pragma("unroll") for (int m = 0; m < 4; ++m) _Pragma("unroll") for (int k = 0; k < 2; ++k) dst[m][k] = *(const PG8_LAS bf16x8*)(lds + PG8_SA(b, h) + aoff + m * 2048 + k * 1024); } while (0)
; #define PG8_LDB(dst, b, h) do { _Pragma("unroll") for (int n = 0; n < 2; ++n) _Pragma("unroll") for (int k = 0; k < 2; ++k) dst[n][k] = *(const PG8_LAS bf16x8*)(lds + PG8_SB(b, h) + boff + n * 2048 + k * 1024); } while (0)
; #define PG8_MMA(ai, bj, At, Bt) do { _Pragma("unroll") for (int m = 0; m < 4; ++m) _Pragma("unroll") for (int n = 0; n < 2; ++n) _Pragma("unroll") for (int k = 0; k < 2; ++k) \
;         acc[ai][bj][m][n] = __builtin_amdgcn_mfma_f32_16x16x32_bf16(Bt[n][k], At[m][k], acc[ai][bj][m][n], 0, 0, 0); } while (0)
; #define PG8_WAIT_V(n) asm volatile("s_waitcnt vmcnt(" #n ")" ::: "memory")
; #define PG8_WAIT_L(n) asm volatile("s_waitcnt lgkmcnt(" #n ")" ::: "memory")
; #define PG8_BAR __builtin_amdgcn_s_barrier()
; #define PG8_SCHED __builtin_amdgcn_sched_barrier(0)
; template <class Epi, class Sched, bool ALIGN_EPI = false, bool SP2 = false>
; __device__ __forceinline__ void gemm_phase(PG8_LAS unsigned char* lds, const Gemm g, const Sched& S, const Epi& E, const int wave_id_in) {
;     ...
;             PG8_LDB(B0, 1, 0); PG8_LDB(B1, 1, 1); PG8_SCHED; PG8_LDA(At, 1, 0); PG8_STAGE(PG8_SA(0, 1), a2 + hstep, voffA);
;             PG8_WAIT_V(8); PG8_WAIT_L(0); PG8_BAR; __builtin_amdgcn_s_setprio(1); PG8_MMA(0, 0, At, B0); PG8_MMA(0, 1, At, B1); __builtin_amdgcn_s_setprio(0); PG8_BAR; PG8_SCHED;
;             PG8_LDA(At, 1, 1); PG8_STAGE(PG8_SB(1, 0), b3, voffB); PG8_STAGE(PG8_SB(1, 1), b3 + hstep, voffB); PG8_STAGE(PG8_SA(1, 0), a3, voffA);
;             PG8_WAIT_V(8); PG8_WAIT_L(0); PG8_BAR; __builtin_amdgcn_s_setprio(1); PG8_MMA(1, 0, At, B0); PG8_MMA(1, 1, At, B1); __builtin_amdgcn_s_setprio(0); PG8_BAR; PG8_SCHED;
	s_add_i32 s77, 0, 0x18000
	s_add_i32 s76, 0, 0x1c000
	v_add_u32_e32 v72, s77, v220
	v_add_u32_e32 v80, s76, v220
	ds_read_b128 v[52:55], v72
	ds_read_b128 v[60:63], v72 offset:1024
	ds_read_b128 v[68:71], v72 offset:2048
	ds_read_b128 v[72:75], v72 offset:3072
	ds_read_b128 v[76:79], v80
	ds_read_b128 v[84:87], v80 offset:1024
	ds_read_b128 v[168:171], v80 offset:2048
	ds_read_b128 v[180:183], v80 offset:3072
	s_add_u32 s40, s72, 0x80000
	s_addc_u32 s41, s73, 0
	s_mov_b32 m0, s83
	v_lshl_add_u64 v[148:149], s[40:41], 0, v[184:185]
	ds_read_b128 v[80:83], v223 offset:32768
	ds_read_b128 v[108:111], v223 offset:33792
	ds_read_b128 v[140:143], v223 offset:34816
	ds_read_b128 v[144:147], v223 offset:35840
	ds_read_b128 v[176:179], v223 offset:36864
	ds_read_b128 v[200:203], v223 offset:37888
	ds_read_b128 v[204:207], v223 offset:38912
	ds_read_b128 v[208:211], v223 offset:39936
	global_load_lds_dwordx4 v[148:149], off
	v_lshl_add_u64 v[148:149], s[40:41], 0, v[188:189]
	s_mov_b32 m0, s84
	s_nop 0
	global_load_lds_dwordx4 v[148:149], off
	s_waitcnt vmcnt(8)
	s_waitcnt lgkmcnt(0)
	s_barrier
	v_mfma_f32_16x16x32_bf16 v[148:151], v[52:55], v[140:143], v[172:175]
	v_mfma_f32_16x16x32_bf16 v[172:175], v[60:63], v[144:147], v[148:151]
	v_mfma_f32_16x16x32_bf16 v[148:151], v[68:71], v[140:143], v[164:167]
	v_mfma_f32_16x16x32_bf16 v[164:167], v[72:75], v[144:147], v[148:151]
	v_mfma_f32_16x16x32_bf16 v[148:151], v[52:55], v[176:179], v[156:159]
	v_mfma_f32_16x16x32_bf16 v[40:43], v[52:55], v[80:83], v[40:43]
	v_mfma_f32_16x16x32_bf16 v[36:39], v[68:71], v[80:83], v[36:39]
	v_mfma_f32_16x16x32_bf16 v[156:159], v[60:63], v[200:203], v[148:151]
	v_mfma_f32_16x16x32_bf16 v[148:151], v[68:71], v[176:179], v[152:155]
	v_mfma_f32_16x16x32_bf16 v[104:107], v[76:79], v[80:83], v[104:107]
	v_mfma_f32_16x16x32_bf16 v[80:83], v[168:171], v[80:83], v[92:95]
	v_mfma_f32_16x16x32_bf16 v[40:43], v[60:63], v[108:111], v[40:43]
	v_mfma_f32_16x16x32_bf16 v[36:39], v[72:75], v[108:111], v[36:39]
	v_mfma_f32_16x16x32_bf16 v[152:155], v[72:75], v[200:203], v[148:151]
	v_mfma_f32_16x16x32_bf16 v[148:151], v[52:55], v[204:207], v[160:163]
	v_mfma_f32_16x16x32_bf16 v[104:107], v[84:87], v[108:111], v[104:107]
	v_mfma_f32_16x16x32_bf16 v[108:111], v[180:183], v[108:111], v[80:83]
	v_mfma_f32_16x16x32_bf16 v[80:83], v[76:79], v[140:143], v[96:99]
	v_mfma_f32_16x16x32_bf16 v[160:163], v[60:63], v[208:211], v[148:151]
	v_mfma_f32_16x16x32_bf16 v[148:151], v[84:87], v[144:147], v[80:83]
	v_mfma_f32_16x16x32_bf16 v[80:83], v[168:171], v[140:143], v[120:123]
	v_mfma_f32_16x16x32_bf16 v[144:147], v[180:183], v[144:147], v[80:83]
	v_mfma_f32_16x16x32_bf16 v[80:83], v[76:79], v[176:179], v[124:127]
	v_mfma_f32_16x16x32_bf16 v[140:143], v[84:87], v[200:203], v[80:83]
	v_mfma_f32_16x16x32_bf16 v[80:83], v[168:171], v[176:179], v[136:139]
	v_mfma_f32_16x16x32_bf16 v[136:139], v[180:183], v[200:203], v[80:83]
	v_mfma_f32_16x16x32_bf16 v[80:83], v[76:79], v[204:207], v[116:119]
	v_mfma_f32_16x16x32_bf16 v[132:135], v[68:71], v[204:207], v[132:135]
	v_mfma_f32_16x16x32_bf16 v[116:119], v[84:87], v[208:211], v[80:83]
	v_mfma_f32_16x16x32_bf16 v[80:83], v[168:171], v[204:207], v[112:115]
	v_mfma_f32_16x16x32_bf16 v[132:135], v[72:75], v[208:211], v[132:135]
	v_mfma_f32_16x16x32_bf16 v[112:115], v[180:183], v[208:211], v[80:83]
	s_barrier
	s_add_i32 s40, s77, s80
	s_nop 2
	s_nop 0
	v_lshl_add_u64 v[80:81], v[216:217], 0, s[34:35]
	s_mov_b32 m0, s40
	ds_read_b128 v[92:95], v223 offset:49152
	ds_read_b128 v[96:99], v223 offset:50176
	ds_read_b128 v[120:123], v223 offset:51200
	ds_read_b128 v[124:127], v223 offset:52224
	ds_read_b128 v[200:203], v223 offset:53248
	ds_read_b128 v[204:207], v223 offset:54272
	ds_read_b128 v[208:211], v223 offset:55296
	ds_read_b128 v[212:215], v223 offset:56320
	global_load_lds_dwordx4 v[80:81], off
	s_add_i32 m0, s40, 0x2000
	s_add_u32 s12, s12, 0x80080
	v_lshl_add_u64 v[80:81], v[218:219], 0, s[34:35]
	s_addc_u32 s13, s13, 0
	s_add_i32 s40, s76, s80
	global_load_lds_dwordx4 v[80:81], off
	v_lshl_add_u64 v[80:81], s[12:13], 0, v[186:187]
	s_mov_b32 m0, s40
	s_nop 0
	global_load_lds_dwordx4 v[80:81], off
	v_lshl_add_u64 v[80:81], s[12:13], 0, v[190:191]
	s_add_i32 m0, s40, 0x2000
	s_nop 0
	global_load_lds_dwordx4 v[80:81], off
	v_lshl_add_u64 v[80:81], v[226:227], 0, s[34:35]
	s_mov_b32 m0, s87
	s_nop 0
	global_load_lds_dwordx4 v[80:81], off
	v_lshl_add_u64 v[80:81], v[228:229], 0, s[34:35]
	s_mov_b32 m0, s88
	s_nop 0
	global_load_lds_dwordx4 v[80:81], off
	s_waitcnt vmcnt(8)
	s_waitcnt lgkmcnt(0)
	s_barrier
	v_mfma_f32_16x16x32_bf16 v[80:83], v[52:55], v[92:95], v[128:131]
	v_mfma_f32_16x16x32_bf16 v[44:47], v[52:55], v[208:211], v[44:47]
	v_mfma_f32_16x16x32_bf16 v[128:131], v[60:63], v[96:99], v[80:83]
	v_mfma_f32_16x16x32_bf16 v[80:83], v[52:55], v[120:123], v[100:103]
	v_mfma_f32_16x16x32_bf16 v[176:179], v[60:63], v[212:215], v[44:47]
	v_mfma_f32_16x16x32_bf16 v[44:47], v[68:71], v[208:211], v[48:51]
	v_mfma_f32_16x16x32_bf16 v[64:67], v[68:71], v[92:95], v[64:67]
	v_mfma_f32_16x16x32_bf16 v[100:103], v[60:63], v[124:127], v[80:83]
	v_mfma_f32_16x16x32_bf16 v[80:83], v[68:71], v[120:123], v[88:91]
	v_mfma_f32_16x16x32_bf16 v[28:31], v[52:55], v[200:203], v[28:31]
	v_mfma_f32_16x16x32_bf16 v[24:27], v[68:71], v[200:203], v[24:27]
	v_mfma_f32_16x16x32_bf16 v[52:55], v[72:75], v[212:215], v[44:47]
	v_mfma_f32_16x16x32_bf16 v[44:47], v[76:79], v[92:95], v[56:59]
	v_mfma_f32_16x16x32_bf16 v[32:35], v[168:171], v[92:95], v[32:35]
	v_mfma_f32_16x16x32_bf16 v[20:23], v[76:79], v[120:123], v[20:23]
	v_mfma_f32_16x16x32_bf16 v[16:19], v[168:171], v[120:123], v[16:19]
	v_mfma_f32_16x16x32_bf16 v[12:15], v[76:79], v[200:203], v[12:15]
	v_mfma_f32_16x16x32_bf16 v[8:11], v[168:171], v[200:203], v[8:11]
	v_mfma_f32_16x16x32_bf16 v[4:7], v[76:79], v[208:211], v[4:7]
	v_mfma_f32_16x16x32_bf16 v[0:3], v[168:171], v[208:211], v[0:3]
	v_mfma_f32_16x16x32_bf16 v[64:67], v[72:75], v[96:99], v[64:67]
	v_mfma_f32_16x16x32_bf16 v[88:91], v[72:75], v[124:127], v[80:83]
	v_mfma_f32_16x16x32_bf16 v[28:31], v[60:63], v[204:207], v[28:31]
	v_mfma_f32_16x16x32_bf16 v[24:27], v[72:75], v[204:207], v[24:27]
	v_mfma_f32_16x16x32_bf16 v[80:83], v[84:87], v[96:99], v[44:47]
	v_mfma_f32_16x16x32_bf16 v[32:35], v[180:183], v[96:99], v[32:35]
	v_mfma_f32_16x16x32_bf16 v[20:23], v[84:87], v[124:127], v[20:23]
	v_mfma_f32_16x16x32_bf16 v[16:19], v[180:183], v[124:127], v[16:19]
	v_mfma_f32_16x16x32_bf16 v[12:15], v[84:87], v[204:207], v[12:15]
	v_mfma_f32_16x16x32_bf16 v[8:11], v[180:183], v[204:207], v[8:11]
	v_mfma_f32_16x16x32_bf16 v[4:7], v[84:87], v[212:215], v[4:7]
	v_mfma_f32_16x16x32_bf16 v[0:3], v[180:183], v[212:215], v[0:3]
	s_add_i32 vcc_hi, vcc_hi, 2
	s_add_u32 s10, s10, 0x100
	s_addc_u32 s11, s11, 0
	s_add_u32 s75, s75, 0x100
	s_addc_u32 vcc_lo, vcc_lo, 0
	s_cmp_gt_u32 vcc_hi, 29
	s_barrier
	s_cbranch_scc0 .LBB0_819

; #define PG8_STAGE(bufoff, gbase, voff) do { _Pragma("unroll") for (int _i = 0; _i < 2; ++_i) \
;         __builtin_amdgcn_global_load_lds((const unsigned*)((const char*)(gbase) + (voff)[_i]), (PG8_LAS unsigned*)(lds + (bufoff) + ldsw + _i * 8192), 16, 0, 0); } while (0)
; #define PG8_LDA(dst, b, h) do { _Pragma("unroll") for (int m = 0; m < 4; ++m) _Pragma("unroll") for (int k = 0; k < 2; ++k) dst[m][k] = *(const PG8_LAS bf16x8*)(lds + PG8_SA(b, h) + aoff + m * 2048 + k * 1024); } while (0)
; #define PG8_LDB(dst, b, h) do { _Pragma("unroll") for (int n = 0; n < 2; ++n) _Pragma("unroll") for (int k = 0; k < 2; ++k) dst[n][k] = *(const PG8_LAS bf16x8*)(lds + PG8_SB(b, h) + boff + n * 2048 + k * 1024); } while (0)
; #define PG8_MMA(ai, bj, At, Bt) do { _Pragma("unroll") for (int m = 0; m < 4; ++m) _Pragma("unroll") for (int n = 0; n < 2; ++n) _Pragma("unroll") for (int k = 0; k < 2; ++k) \
;         acc[ai][bj][m][n] = __builtin_amdgcn_mfma_f32_16x16x32_bf16(Bt[n][k], At[m][k], acc[ai][bj][m][n], 0, 0, 0); } while (0)
; #define PG8_WAIT_V(n) asm volatile("s_waitcnt vmcnt(" #n ")" ::: "memory")
; #define PG8_WAIT_L(n) asm volatile("s_waitcnt lgkmcnt(" #n ")" ::: "memory")
; #define PG8_BAR __builtin_amdgcn_s_barrier()
; #define PG8_SCHED __builtin_amdgcn_sched_barrier(0)
; template <class Epi>
; __device__ __forceinline__ void gemm_half_phase(PG8_LAS unsigned char* lds, const Gemm g, const Unit cur, const Epi& E, const int wave_id_in) {
;     ...
;     for (int t = 0; t < nt; t += 2) {
;         const bool last = (t == nt - 2);
;         const char* a2 = last ? cA : cA + (size_t)(t + 2) * kstep; const char* b2 = last ? cB : cB + (size_t)(t + 2) * kstep;
;         const char* a3 = a2 + kstep; const char* b3 = b2 + kstep;
;         PG8_LDB(B0, 0, 0); PG8_LDB(B1, 0, 1); PG8_SCHED; PG8_LDA(At, 0, 0);
;         PG8_WAIT_V(6); PG8_WAIT_L(0); PG8_BAR; __builtin_amdgcn_s_setprio(1); PG8_MMA(0, 0, At, B0); __builtin_amdgcn_s_setprio(0); PG8_BAR; PG8_SCHED;
;         PG8_STAGE(PG8_SB(0, 0), b2, voffB); PG8_STAGE(PG8_SB(0, 1), b2 + hstep, voffB); PG8_STAGE(PG8_SA(0, 0), a2, voffA);
;         PG8_WAIT_V(6); PG8_BAR; __builtin_amdgcn_s_setprio(1); PG8_MMA(0, 1, At, B1); __builtin_amdgcn_s_setprio(0); PG8_BAR; PG8_SCHED;
.LBB0_888:
	ds_read_b128 v[44:47], v32
	ds_read_b128 v[52:55], v32 offset:1024
	ds_read_b128 v[56:59], v32 offset:2048
	ds_read_b128 v[64:67], v32 offset:3072
	ds_read_b128 v[88:91], v33
	ds_read_b128 v[92:95], v33 offset:1024
	ds_read_b128 v[104:107], v33 offset:2048
	ds_read_b128 v[108:111], v33 offset:3072
	s_cmp_eq_u32 s38, 28
	s_cselect_b32 s41, s7, s37
	s_cselect_b32 s40, s6, s36
	s_cselect_b32 s27, s9, s29
	s_cselect_b32 s26, s8, s28
	ds_read_b128 v[112:115], v34
	ds_read_b128 v[116:119], v34 offset:1024
	ds_read_b128 v[120:123], v34 offset:2048
	ds_read_b128 v[124:127], v34 offset:3072
	ds_read_b128 v[128:131], v34 offset:4096
	ds_read_b128 v[132:135], v34 offset:5120
	ds_read_b128 v[136:139], v34 offset:6144
	ds_read_b128 v[140:143], v34 offset:7168
	s_waitcnt vmcnt(6)
	s_waitcnt lgkmcnt(0)
	s_barrier
	v_mfma_f32_16x16x32_bf16 v[20:23], v[44:47], v[112:115], v[20:23]
	v_mfma_f32_16x16x32_bf16 v[16:19], v[56:59], v[112:115], v[16:19]
	v_mfma_f32_16x16x32_bf16 v[100:103], v[44:47], v[120:123], v[100:103]
	v_mfma_f32_16x16x32_bf16 v[96:99], v[56:59], v[120:123], v[96:99]
	v_mfma_f32_16x16x32_bf16 v[84:87], v[44:47], v[128:131], v[84:87]
	v_mfma_f32_16x16x32_bf16 v[80:83], v[56:59], v[128:131], v[80:83]
	v_mfma_f32_16x16x32_bf16 v[12:15], v[44:47], v[136:139], v[12:15]
	v_mfma_f32_16x16x32_bf16 v[8:11], v[56:59], v[136:139], v[8:11]
	v_mfma_f32_16x16x32_bf16 v[20:23], v[52:55], v[116:119], v[20:23]
	v_mfma_f32_16x16x32_bf16 v[16:19], v[64:67], v[116:119], v[16:19]
	v_mfma_f32_16x16x32_bf16 v[100:103], v[52:55], v[124:127], v[100:103]
	v_mfma_f32_16x16x32_bf16 v[96:99], v[64:67], v[124:127], v[96:99]
	v_mfma_f32_16x16x32_bf16 v[84:87], v[52:55], v[132:135], v[84:87]
	v_mfma_f32_16x16x32_bf16 v[80:83], v[64:67], v[132:135], v[80:83]
	v_mfma_f32_16x16x32_bf16 v[12:15], v[52:55], v[140:143], v[12:15]
	v_mfma_f32_16x16x32_bf16 v[8:11], v[64:67], v[140:143], v[8:11]
	s_barrier
	s_mov_b32 m0, s39
	v_lshl_add_u64 v[144:145], s[26:27], 0, v[26:27]
	s_add_u32 s50, s26, 0x80000
	global_load_lds_dwordx4 v[144:145], off
	v_lshl_add_u64 v[146:147], s[26:27], 0, v[30:31]
	s_mov_b32 m0, s42
	s_addc_u32 s51, s27, 0
	global_load_lds_dwordx4 v[146:147], off
	v_lshl_add_u64 v[38:39], s[50:51], 0, v[26:27]
	s_mov_b32 m0, s43
	v_lshl_add_u64 v[148:149], s[40:41], 0, v[24:25]
	global_load_lds_dwordx4 v[38:39], off
	v_lshl_add_u64 v[38:39], s[50:51], 0, v[30:31]
	s_mov_b32 m0, s44
	v_lshl_add_u64 v[150:151], s[40:41], 0, v[28:29]
	global_load_lds_dwordx4 v[38:39], off
	s_mov_b32 m0, s23
	s_nop 0
	global_load_lds_dwordx4 v[148:149], off
	s_mov_b32 m0, s31
	s_nop 0
	global_load_lds_dwordx4 v[150:151], off
	s_waitcnt vmcnt(6)
	s_barrier
	v_mfma_f32_16x16x32_bf16 v[38:41], v[88:91], v[112:115], v[40:43]
	v_mfma_f32_16x16x32_bf16 v[42:45], v[104:107], v[112:115], v[48:51]
	v_mfma_f32_16x16x32_bf16 v[48:51], v[88:91], v[120:123], v[76:79]
	v_mfma_f32_16x16x32_bf16 v[52:55], v[92:95], v[124:127], v[48:51]
	v_mfma_f32_16x16x32_bf16 v[48:51], v[104:107], v[120:123], v[72:75]
	v_mfma_f32_16x16x32_bf16 v[56:59], v[108:111], v[124:127], v[48:51]
	v_mfma_f32_16x16x32_bf16 v[48:51], v[88:91], v[128:131], v[68:71]
	v_mfma_f32_16x16x32_bf16 v[64:67], v[92:95], v[132:135], v[48:51]
	v_mfma_f32_16x16x32_bf16 v[48:51], v[104:107], v[128:131], v[60:63]
	v_mfma_f32_16x16x32_bf16 v[4:7], v[88:91], v[136:139], v[4:7]
	v_mfma_f32_16x16x32_bf16 v[0:3], v[104:107], v[136:139], v[0:3]
	v_mfma_f32_16x16x32_bf16 v[38:41], v[92:95], v[116:119], v[38:41]
	v_mfma_f32_16x16x32_bf16 v[60:63], v[108:111], v[132:135], v[48:51]
	v_mfma_f32_16x16x32_bf16 v[4:7], v[92:95], v[140:143], v[4:7]
	v_mfma_f32_16x16x32_bf16 v[0:3], v[108:111], v[140:143], v[0:3]
	v_mfma_f32_16x16x32_bf16 v[44:47], v[108:111], v[116:119], v[42:45]
	s_barrier
; #define PG8_STAGE(bufoff, gbase, voff) do { _Pragma("unroll") for (int _i = 0; _i < 2; ++_i) \
;         __builtin_amdgcn_global_load_lds((const unsigned*)((const char*)(gbase) + (voff)[_i]), (PG8_LAS unsigned*)(lds + (bufoff) + ldsw + _i * 8192), 16, 0, 0); } while (0)
; #define PG8_LDA(dst, b, h) do { _Pragma("unroll") for (int m = 0; m < 4; ++m) _Pragma("unroll") for (int k = 0; k < 2; ++k) dst[m][k] = *(const PG8_LAS bf16x8*)(lds + PG8_SA(b, h) + aoff + m * 2048 + k * 1024); } while (0)
; #define PG8_LDB(dst, b, h) do { _Pragma("unroll") for (int n = 0; n < 2; ++n) _Pragma("unroll") for (int k = 0; k < 2; ++k) dst[n][k] = *(const PG8_LAS bf16x8*)(lds + PG8_SB(b, h) + boff + n * 2048 + k * 1024); } while (0)
; #define PG8_MMA(ai, bj, At, Bt) do { _Pragma("unroll") for (int m = 0; m < 4; ++m) _Pragma("unroll") for (int n = 0; n < 2; ++n) _Pragma("unroll") for (int k = 0; k < 2; ++k) \
;         acc[ai][bj][m][n] = __builtin_amdgcn_mfma_f32_16x16x32_bf16(Bt[n][k], At[m][k], acc[ai][bj][m][n], 0, 0, 0); } while (0)
; #define PG8_WAIT_V(n) asm volatile("s_waitcnt vmcnt(" #n ")" ::: "memory")
; #define PG8_WAIT_L(n) asm volatile("s_waitcnt lgkmcnt(" #n ")" ::: "memory")
; #define PG8_BAR __builtin_amdgcn_s_barrier()
; #define PG8_SCHED __builtin_amdgcn_sched_barrier(0)
; template <class Epi>
; __device__ __forceinline__ void gemm_half_phase(PG8_LAS unsigned char* lds, const Gemm g, const Unit cur, const Epi& E, const int wave_id_in) {
;     ...
;         PG8_LDB(B0, 1, 0); PG8_LDB(B1, 1, 1); PG8_SCHED; PG8_LDA(At, 1, 0);
;         PG8_WAIT_V(6); PG8_WAIT_L(0); PG8_BAR; __builtin_amdgcn_s_setprio(1); PG8_MMA(0, 0, At, B0); __builtin_amdgcn_s_setprio(0); PG8_BAR; PG8_SCHED;
;         PG8_STAGE(PG8_SB(1, 0), b3, voffB); PG8_STAGE(PG8_SB(1, 1), b3 + hstep, voffB); PG8_STAGE(PG8_SA(1, 0), a3, voffA);
;         PG8_WAIT_V(6); PG8_BAR; __builtin_amdgcn_s_setprio(1); PG8_MMA(0, 1, At, B1); __builtin_amdgcn_s_setprio(0); PG8_BAR; PG8_SCHED;
;     }
;     if (wr == 0) PG8_BAR;
	ds_read_b128 v[48:51], v35
	ds_read_b128 v[68:71], v35 offset:1024
	ds_read_b128 v[72:75], v35 offset:2048
	ds_read_b128 v[76:79], v35 offset:3072
	ds_read_b128 v[88:91], v36
	ds_read_b128 v[92:95], v36 offset:1024
	ds_read_b128 v[104:107], v36 offset:2048
	ds_read_b128 v[108:111], v36 offset:3072
	ds_read_b128 v[112:115], v34 offset:32768
	ds_read_b128 v[116:119], v34 offset:33792
	ds_read_b128 v[120:123], v34 offset:34816
	ds_read_b128 v[124:127], v34 offset:35840
	ds_read_b128 v[128:131], v34 offset:36864
	ds_read_b128 v[132:135], v34 offset:37888
	ds_read_b128 v[136:139], v34 offset:38912
	ds_read_b128 v[140:143], v34 offset:39936
	s_waitcnt vmcnt(6)
	s_waitcnt lgkmcnt(0)
	s_barrier
	v_mfma_f32_16x16x32_bf16 v[20:23], v[48:51], v[112:115], v[20:23]
	v_mfma_f32_16x16x32_bf16 v[16:19], v[72:75], v[112:115], v[16:19]
	v_mfma_f32_16x16x32_bf16 v[100:103], v[48:51], v[120:123], v[100:103]
	v_mfma_f32_16x16x32_bf16 v[96:99], v[72:75], v[120:123], v[96:99]
	v_mfma_f32_16x16x32_bf16 v[84:87], v[48:51], v[128:131], v[84:87]
	v_mfma_f32_16x16x32_bf16 v[80:83], v[72:75], v[128:131], v[80:83]
	v_mfma_f32_16x16x32_bf16 v[12:15], v[48:51], v[136:139], v[12:15]
	v_mfma_f32_16x16x32_bf16 v[8:11], v[72:75], v[136:139], v[8:11]
	v_mfma_f32_16x16x32_bf16 v[20:23], v[68:71], v[116:119], v[20:23]
	v_mfma_f32_16x16x32_bf16 v[16:19], v[76:79], v[116:119], v[16:19]
	v_mfma_f32_16x16x32_bf16 v[100:103], v[68:71], v[124:127], v[100:103]
	v_mfma_f32_16x16x32_bf16 v[96:99], v[76:79], v[124:127], v[96:99]
	v_mfma_f32_16x16x32_bf16 v[84:87], v[68:71], v[132:135], v[84:87]
	v_mfma_f32_16x16x32_bf16 v[80:83], v[76:79], v[132:135], v[80:83]
	v_mfma_f32_16x16x32_bf16 v[12:15], v[68:71], v[140:143], v[12:15]
	v_mfma_f32_16x16x32_bf16 v[8:11], v[76:79], v[140:143], v[8:11]
	s_barrier
	s_mov_b32 m0, s45
	v_lshl_add_u64 v[42:43], v[144:145], 0, s[10:11]
	s_add_u32 s26, s26, 0x80080
	global_load_lds_dwordx4 v[42:43], off
	v_lshl_add_u64 v[42:43], v[146:147], 0, s[10:11]
	s_mov_b32 m0, s46
	s_addc_u32 s27, s27, 0
	global_load_lds_dwordx4 v[42:43], off
	v_lshl_add_u64 v[42:43], s[26:27], 0, v[26:27]
	s_mov_b32 m0, s47
	s_nop 0
	global_load_lds_dwordx4 v[42:43], off
	v_lshl_add_u64 v[42:43], s[26:27], 0, v[30:31]
	s_mov_b32 m0, s48
	s_nop 0
	global_load_lds_dwordx4 v[42:43], off
	v_lshl_add_u64 v[42:43], v[148:149], 0, s[10:11]
	s_mov_b32 m0, s34
	s_nop 0
	global_load_lds_dwordx4 v[42:43], off
	v_lshl_add_u64 v[42:43], v[150:151], 0, s[10:11]
	s_mov_b32 m0, s35
	s_nop 0
	global_load_lds_dwordx4 v[42:43], off
	s_waitcnt vmcnt(6)
	s_barrier
	v_mfma_f32_16x16x32_bf16 v[44:47], v[104:107], v[112:115], v[44:47]
	v_mfma_f32_16x16x32_bf16 v[48:51], v[108:111], v[116:119], v[44:47]
	v_mfma_f32_16x16x32_bf16 v[44:47], v[88:91], v[120:123], v[52:55]
	v_mfma_f32_16x16x32_bf16 v[76:79], v[92:95], v[124:127], v[44:47]
	v_mfma_f32_16x16x32_bf16 v[44:47], v[104:107], v[120:123], v[56:59]
	v_mfma_f32_16x16x32_bf16 v[72:75], v[108:111], v[124:127], v[44:47]
	v_mfma_f32_16x16x32_bf16 v[44:47], v[88:91], v[128:131], v[64:67]
	v_mfma_f32_16x16x32_bf16 v[38:41], v[88:91], v[112:115], v[38:41]
	v_mfma_f32_16x16x32_bf16 v[68:71], v[92:95], v[132:135], v[44:47]
	v_mfma_f32_16x16x32_bf16 v[44:47], v[104:107], v[128:131], v[60:63]
	v_mfma_f32_16x16x32_bf16 v[4:7], v[88:91], v[136:139], v[4:7]
	v_mfma_f32_16x16x32_bf16 v[0:3], v[104:107], v[136:139], v[0:3]
	v_mfma_f32_16x16x32_bf16 v[40:43], v[92:95], v[116:119], v[38:41]
	v_mfma_f32_16x16x32_bf16 v[60:63], v[108:111], v[132:135], v[44:47]
	v_mfma_f32_16x16x32_bf16 v[4:7], v[92:95], v[140:143], v[4:7]
	v_mfma_f32_16x16x32_bf16 v[0:3], v[108:111], v[140:143], v[0:3]
	s_add_i32 s38, s38, 2
	s_add_u32 s36, s36, 0x100
	s_addc_u32 s37, s37, 0
	s_add_u32 s28, s28, 0x100
	s_addc_u32 s29, s29, 0
	s_cmp_gt_u32 s38, 29
	s_barrier
	s_cbranch_scc0 .LBB0_888
	s_cmpk_lt_u32 s30, 0x100
	s_cselect_b64 s[26:27], -1, 0
	s_and_b64 vcc, exec, s[26:27]
	s_cbranch_vccz .LBB0_891
	s_barrier

;     __host__ __device__ bool next(int i, Unit& u) const { const long L = (long)i * G + c; if (L >= maxL) return false; return unit_of(L, u); }
;     __device__ __forceinline__ const char* a_base(const Gemm& g, const Unit& u, size_t tstep) const { return (const char*)g.A + (size_t)u.pm * tstep; }
;     __device__ __forceinline__ const char* b_base(const Gemm& g, const Unit& u, size_t tstep) const { return (const char*)g.Bt + (size_t)u.pn * tstep; }
; #define PG8_STAGE(bufoff, gbase, voff) do { _Pragma("unroll") for (int _i = 0; _i < 2; ++_i) \
;         __builtin_amdgcn_global_load_lds((const unsigned*)((const char*)(gbase) + (voff)[_i]), (PG8_LAS unsigned*)(lds + (bufoff) + ldsw + _i * 8192), 16, 0, 0); } while (0)
; #define PG8_LDA(dst, b, h) do { _Pragma("unroll") for (int m = 0; m < 4; ++m) _Pragma("unroll") for (int k = 0; k < 2; ++k) dst[m][k] = *(const PG8_LAS bf16x8*)(lds + PG8_SA(b, h) + aoff + m * 2048 + k * 1024); } while (0)
; #define PG8_WAIT_V(n) asm volatile("s_waitcnt vmcnt(" #n ")" ::: "memory")
; #define PG8_BAR __builtin_amdgcn_s_barrier()
; template <class Epi, class Sched, bool ALIGN_EPI = false, bool SP2 = false>
; __device__ __forceinline__ void gemm_phase(PG8_LAS unsigned char* lds, const Gemm g, const Sched& S, const Epi& E, const int wave_id_in) {
;     ...
;         const bool has_next = S.next(ui + 1, nxt);
;         const char* nA = has_next ? S.a_base(g, nxt, tstep) : cA; const char* nB = has_next ? S.b_base(g, nxt, tstep) : cB;
;         for (int t = 0; t < nt; t += 2) {
;             const bool last = (t == nt - 2);
;             const char* a1 = cA + (size_t)(t + 1) * kstep;
;             const char* a2 = last ? nA : cA + (size_t)(t + 2) * kstep; const char* b2 = last ? nB : cB + (size_t)(t + 2) * kstep;
;             const char* a3 = a2 + kstep; const char* b3 = b2 + kstep;
;             if (last && has_next) S.a_ready(nxt);
;             if constexpr (SP2) {
;             PG8_LDB(B0, 0, 0); PG8_LDB(B1, 0, 1); PG8_SCHED; PG8_LDA(At, 0, 0); PG8_STAGE(PG8_SA(1, 1), a1 + hstep, voffA);
;             PG8_WAIT_V(8); PG8_WAIT_L(0); PG8_BAR; __builtin_amdgcn_s_setprio(1); PG8_MMA(0, 0, At, B0); PG8_MMA(0, 1, At, B1); __builtin_amdgcn_s_setprio(0); PG8_BAR; PG8_SCHED;
;             PG8_LDA(At, 0, 1); PG8_STAGE(PG8_SB(0, 0), b2, voffB); PG8_STAGE(PG8_SB(0, 1), b2 + hstep, voffB); PG8_STAGE(PG8_SA(0, 0), a2, voffA);
.LBB0_1022:
	ds_read_b128 v[128:131], v201
	ds_read_b128 v[132:135], v201 offset:1024
	ds_read_b128 v[136:139], v201 offset:2048
	ds_read_b128 v[140:143], v201 offset:3072
	ds_read_b128 v[144:147], v202
	ds_read_b128 v[148:151], v202 offset:1024
	ds_read_b128 v[152:155], v202 offset:2048
	ds_read_b128 v[156:159], v202 offset:3072
	s_add_u32 s24, s22, 0x100
	s_addc_u32 s25, s23, 0
	s_cmpk_eq_i32 s55, 0x54
	s_cselect_b32 s29, s5, s25
	s_cselect_b32 s28, s4, s24
	s_cselect_b32 s27, s21, s54
	s_cselect_b32 s26, s20, s53
	v_lshl_add_u64 v[212:213], s[22:23], 0, v[192:193]
	s_add_i32 m0, s35, 0xc000
	ds_read_b128 v[160:163], v203
	ds_read_b128 v[164:167], v203 offset:1024
	ds_read_b128 v[168:171], v203 offset:2048
	ds_read_b128 v[172:175], v203 offset:3072
	ds_read_b128 v[176:179], v203 offset:4096
	ds_read_b128 v[180:183], v203 offset:5120
	ds_read_b128 v[204:207], v203 offset:6144
	ds_read_b128 v[208:211], v203 offset:7168
	global_load_lds_dwordx4 v[212:213], off
	v_lshl_add_u64 v[212:213], s[22:23], 0, v[194:195]
	s_add_i32 m0, s35, 0xe000
	s_nop 0
	global_load_lds_dwordx4 v[212:213], off
	s_waitcnt vmcnt(8)
	s_waitcnt lgkmcnt(0)
	s_barrier
	v_mfma_f32_16x16x32_bf16 v[124:127], v[128:131], v[160:163], v[124:127]
	v_mfma_f32_16x16x32_bf16 v[120:123], v[136:139], v[160:163], v[120:123]
	v_mfma_f32_16x16x32_bf16 v[112:115], v[128:131], v[168:171], v[112:115]
	v_mfma_f32_16x16x32_bf16 v[104:107], v[136:139], v[168:171], v[104:107]
	v_mfma_f32_16x16x32_bf16 v[96:99], v[128:131], v[176:179], v[96:99]
	v_mfma_f32_16x16x32_bf16 v[88:91], v[136:139], v[176:179], v[88:91]
	v_mfma_f32_16x16x32_bf16 v[80:83], v[128:131], v[204:207], v[80:83]
	v_mfma_f32_16x16x32_bf16 v[72:75], v[136:139], v[204:207], v[72:75]
	v_mfma_f32_16x16x32_bf16 v[116:119], v[144:147], v[160:163], v[116:119]
	v_mfma_f32_16x16x32_bf16 v[108:111], v[152:155], v[160:163], v[108:111]
	v_mfma_f32_16x16x32_bf16 v[100:103], v[144:147], v[168:171], v[100:103]
	v_mfma_f32_16x16x32_bf16 v[92:95], v[152:155], v[168:171], v[92:95]
	v_mfma_f32_16x16x32_bf16 v[84:87], v[144:147], v[176:179], v[84:87]
	v_mfma_f32_16x16x32_bf16 v[76:79], v[152:155], v[176:179], v[76:79]
	v_mfma_f32_16x16x32_bf16 v[68:71], v[144:147], v[204:207], v[68:71]
	v_mfma_f32_16x16x32_bf16 v[64:67], v[152:155], v[204:207], v[64:67]
	v_mfma_f32_16x16x32_bf16 v[124:127], v[132:135], v[164:167], v[124:127]
	v_mfma_f32_16x16x32_bf16 v[120:123], v[140:143], v[164:167], v[120:123]
	v_mfma_f32_16x16x32_bf16 v[112:115], v[132:135], v[172:175], v[112:115]
	v_mfma_f32_16x16x32_bf16 v[104:107], v[140:143], v[172:175], v[104:107]
	v_mfma_f32_16x16x32_bf16 v[96:99], v[132:135], v[180:183], v[96:99]
	v_mfma_f32_16x16x32_bf16 v[88:91], v[140:143], v[180:183], v[88:91]
	v_mfma_f32_16x16x32_bf16 v[80:83], v[132:135], v[208:211], v[80:83]
	v_mfma_f32_16x16x32_bf16 v[72:75], v[140:143], v[208:211], v[72:75]
	v_mfma_f32_16x16x32_bf16 v[116:119], v[148:151], v[164:167], v[116:119]
	v_mfma_f32_16x16x32_bf16 v[108:111], v[156:159], v[164:167], v[108:111]
	v_mfma_f32_16x16x32_bf16 v[100:103], v[148:151], v[172:175], v[100:103]
	v_mfma_f32_16x16x32_bf16 v[92:95], v[156:159], v[172:175], v[92:95]
	v_mfma_f32_16x16x32_bf16 v[84:87], v[148:151], v[180:183], v[84:87]
	v_mfma_f32_16x16x32_bf16 v[76:79], v[156:159], v[180:183], v[76:79]
	v_mfma_f32_16x16x32_bf16 v[68:71], v[148:151], v[208:211], v[68:71]
	v_mfma_f32_16x16x32_bf16 v[64:67], v[156:159], v[208:211], v[64:67]
	s_barrier
	s_add_i32 s22, s45, s34
	v_lshl_add_u64 v[212:213], s[26:27], 0, v[186:187]
	s_mov_b32 m0, s22
	ds_read_b128 v[160:163], v203 offset:16384
	ds_read_b128 v[164:167], v203 offset:17408
	ds_read_b128 v[168:171], v203 offset:18432
	ds_read_b128 v[172:175], v203 offset:19456
	ds_read_b128 v[176:179], v203 offset:20480
	ds_read_b128 v[180:183], v203 offset:21504
	ds_read_b128 v[204:207], v203 offset:22528
	ds_read_b128 v[208:211], v203 offset:23552
	global_load_lds_dwordx4 v[212:213], off
	s_add_i32 m0, s22, 0x2000
	s_add_u32 s22, s26, 0x160000
	v_lshl_add_u64 v[214:215], s[26:27], 0, v[190:191]
	s_addc_u32 s23, s27, 0
	s_add_i32 s59, s46, s34
	global_load_lds_dwordx4 v[214:215], off
	v_lshl_add_u64 v[216:217], s[22:23], 0, v[186:187]
	s_mov_b32 m0, s59
	v_lshl_add_u64 v[218:219], s[28:29], 0, v[188:189]
	global_load_lds_dwordx4 v[216:217], off
	v_lshl_add_u64 v[216:217], s[22:23], 0, v[190:191]
	s_add_i32 m0, s59, 0x2000
	s_nop 0
	global_load_lds_dwordx4 v[216:217], off
	v_lshl_add_u64 v[216:217], s[28:29], 0, v[184:185]
	s_mov_b32 m0, s35
	s_nop 0
	global_load_lds_dwordx4 v[216:217], off
	s_mov_b32 m0, s36
	s_nop 0
	global_load_lds_dwordx4 v[218:219], off
	s_waitcnt vmcnt(8)
	s_waitcnt lgkmcnt(0)
	s_barrier
; #define PG8_STAGE(bufoff, gbase, voff) do { _Pragma("unroll") for (int _i = 0; _i < 2; ++_i) \
;         __builtin_amdgcn_global_load_lds((const unsigned*)((const char*)(gbase) + (voff)[_i]), (PG8_LAS unsigned*)(lds + (bufoff) + ldsw + _i * 8192), 16, 0, 0); } while (0)
; #define PG8_LDA(dst, b, h) do { _Pragma("unroll") for (int m = 0; m < 4; ++m) _Pragma("unroll") for (int k = 0; k < 2; ++k) dst[m][k] = *(const PG8_LAS bf16x8*)(lds + PG8_SA(b, h) + aoff + m * 2048 + k * 1024); } while (0)
; #define PG8_LDB(dst, b, h) do { _Pragma("unroll") for (int n = 0; n < 2; ++n) _Pragma("unroll") for (int k = 0; k < 2; ++k) dst[n][k] = *(const PG8_LAS bf16x8*)(lds + PG8_SB(b, h) + boff + n * 2048 + k * 1024); } while (0)
; #define PG8_MMA(ai, bj, At, Bt) do { _Pragma("unroll") for (int m = 0; m < 4; ++m) _Pragma("unroll") for (int n = 0; n < 2; ++n) _Pragma("unroll") for (int k = 0; k < 2; ++k) \
;         acc[ai][bj][m][n] = __builtin_amdgcn_mfma_f32_16x16x32_bf16(Bt[n][k], At[m][k], acc[ai][bj][m][n], 0, 0, 0); } while (0)
; #define PG8_WAIT_V(n) asm volatile("s_waitcnt vmcnt(" #n ")" ::: "memory")
; #define PG8_WAIT_L(n) asm volatile("s_waitcnt lgkmcnt(" #n ")" ::: "memory")
; #define PG8_BAR __builtin_amdgcn_s_barrier()
; #define PG8_SCHED __builtin_amdgcn_sched_barrier(0)
; template <class Epi, class Sched, bool ALIGN_EPI = false, bool SP2 = false>
; __device__ __forceinline__ void gemm_phase(PG8_LAS unsigned char* lds, const Gemm g, const Sched& S, const Epi& E, const int wave_id_in) {
;     ...
;             PG8_WAIT_V(8); PG8_WAIT_L(0); PG8_BAR; __builtin_amdgcn_s_setprio(1); PG8_MMA(1, 0, At, B0); PG8_MMA(1, 1, At, B1); __builtin_amdgcn_s_setprio(0); PG8_BAR; PG8_SCHED;
;             PG8_LDB(B0, 1, 0); PG8_LDB(B1, 1, 1); PG8_SCHED; PG8_LDA(At, 1, 0); PG8_STAGE(PG8_SA(0, 1), a2 + hstep, voffA);
;             PG8_WAIT_V(8); PG8_WAIT_L(0); PG8_BAR; __builtin_amdgcn_s_setprio(1); PG8_MMA(0, 0, At, B0); PG8_MMA(0, 1, At, B1); __builtin_amdgcn_s_setprio(0); PG8_BAR; PG8_SCHED;
	v_mfma_f32_16x16x32_bf16 v[60:63], v[128:131], v[160:163], v[60:63]
	v_mfma_f32_16x16x32_bf16 v[56:59], v[136:139], v[160:163], v[56:59]
	v_mfma_f32_16x16x32_bf16 v[48:51], v[128:131], v[168:171], v[48:51]
	v_mfma_f32_16x16x32_bf16 v[40:43], v[136:139], v[168:171], v[40:43]
	v_mfma_f32_16x16x32_bf16 v[32:35], v[128:131], v[176:179], v[32:35]
	v_mfma_f32_16x16x32_bf16 v[24:27], v[136:139], v[176:179], v[24:27]
	v_mfma_f32_16x16x32_bf16 v[16:19], v[128:131], v[204:207], v[16:19]
	v_mfma_f32_16x16x32_bf16 v[8:11], v[136:139], v[204:207], v[8:11]
	v_mfma_f32_16x16x32_bf16 v[52:55], v[144:147], v[160:163], v[52:55]
	v_mfma_f32_16x16x32_bf16 v[44:47], v[152:155], v[160:163], v[44:47]
	v_mfma_f32_16x16x32_bf16 v[36:39], v[144:147], v[168:171], v[36:39]
	v_mfma_f32_16x16x32_bf16 v[28:31], v[152:155], v[168:171], v[28:31]
	v_mfma_f32_16x16x32_bf16 v[20:23], v[144:147], v[176:179], v[20:23]
	v_mfma_f32_16x16x32_bf16 v[12:15], v[152:155], v[176:179], v[12:15]
	v_mfma_f32_16x16x32_bf16 v[4:7], v[144:147], v[204:207], v[4:7]
	v_mfma_f32_16x16x32_bf16 v[0:3], v[152:155], v[204:207], v[0:3]
	v_mfma_f32_16x16x32_bf16 v[60:63], v[132:135], v[164:167], v[60:63]
	v_mfma_f32_16x16x32_bf16 v[56:59], v[140:143], v[164:167], v[56:59]
	v_mfma_f32_16x16x32_bf16 v[48:51], v[132:135], v[172:175], v[48:51]
	v_mfma_f32_16x16x32_bf16 v[40:43], v[140:143], v[172:175], v[40:43]
	v_mfma_f32_16x16x32_bf16 v[32:35], v[132:135], v[180:183], v[32:35]
	v_mfma_f32_16x16x32_bf16 v[24:27], v[140:143], v[180:183], v[24:27]
	v_mfma_f32_16x16x32_bf16 v[16:19], v[132:135], v[208:211], v[16:19]
	v_mfma_f32_16x16x32_bf16 v[8:11], v[140:143], v[208:211], v[8:11]
	v_mfma_f32_16x16x32_bf16 v[52:55], v[148:151], v[164:167], v[52:55]
	v_mfma_f32_16x16x32_bf16 v[44:47], v[156:159], v[164:167], v[44:47]
	v_mfma_f32_16x16x32_bf16 v[36:39], v[148:151], v[172:175], v[36:39]
	v_mfma_f32_16x16x32_bf16 v[28:31], v[156:159], v[172:175], v[28:31]
	v_mfma_f32_16x16x32_bf16 v[20:23], v[148:151], v[180:183], v[20:23]
	v_mfma_f32_16x16x32_bf16 v[12:15], v[156:159], v[180:183], v[12:15]
	v_mfma_f32_16x16x32_bf16 v[4:7], v[148:151], v[208:211], v[4:7]
	v_mfma_f32_16x16x32_bf16 v[0:3], v[156:159], v[208:211], v[0:3]
	s_barrier
	s_add_i32 s59, 0, 0x18000
	s_add_i32 s60, 0, 0x1c000
	v_add_u32_e32 v140, s59, v200
	v_add_u32_e32 v156, s60, v200
	ds_read_b128 v[128:131], v140
	ds_read_b128 v[132:135], v140 offset:1024
	ds_read_b128 v[136:139], v140 offset:2048
	ds_read_b128 v[140:143], v140 offset:3072
	ds_read_b128 v[144:147], v156
	ds_read_b128 v[148:151], v156 offset:1024
	ds_read_b128 v[152:155], v156 offset:2048
	ds_read_b128 v[156:159], v156 offset:3072
	s_add_u32 s22, s28, 0x160000
	s_addc_u32 s23, s29, 0
	s_mov_b32 m0, s37
	v_lshl_add_u64 v[220:221], s[22:23], 0, v[184:185]
	ds_read_b128 v[160:163], v203 offset:32768
	ds_read_b128 v[164:167], v203 offset:33792
	ds_read_b128 v[168:171], v203 offset:34816
	ds_read_b128 v[172:175], v203 offset:35840
	ds_read_b128 v[176:179], v203 offset:36864
	ds_read_b128 v[180:183], v203 offset:37888
	ds_read_b128 v[204:207], v203 offset:38912
	ds_read_b128 v[208:211], v203 offset:39936
	global_load_lds_dwordx4 v[220:221], off
	v_lshl_add_u64 v[220:221], s[22:23], 0, v[188:189]
	s_mov_b32 m0, s38
	s_nop 0
	global_load_lds_dwordx4 v[220:221], off
	s_waitcnt vmcnt(8)
	s_waitcnt lgkmcnt(0)
	s_barrier
	v_mfma_f32_16x16x32_bf16 v[124:127], v[128:131], v[160:163], v[124:127]
	v_mfma_f32_16x16x32_bf16 v[120:123], v[136:139], v[160:163], v[120:123]
	v_mfma_f32_16x16x32_bf16 v[112:115], v[128:131], v[168:171], v[112:115]
	v_mfma_f32_16x16x32_bf16 v[104:107], v[136:139], v[168:171], v[104:107]
	v_mfma_f32_16x16x32_bf16 v[96:99], v[128:131], v[176:179], v[96:99]
	v_mfma_f32_16x16x32_bf16 v[88:91], v[136:139], v[176:179], v[88:91]
	v_mfma_f32_16x16x32_bf16 v[80:83], v[128:131], v[204:207], v[80:83]
	v_mfma_f32_16x16x32_bf16 v[72:75], v[136:139], v[204:207], v[72:75]
	v_mfma_f32_16x16x32_bf16 v[116:119], v[144:147], v[160:163], v[116:119]
	v_mfma_f32_16x16x32_bf16 v[108:111], v[152:155], v[160:163], v[108:111]
	v_mfma_f32_16x16x32_bf16 v[100:103], v[144:147], v[168:171], v[100:103]
	v_mfma_f32_16x16x32_bf16 v[92:95], v[152:155], v[168:171], v[92:95]
	v_mfma_f32_16x16x32_bf16 v[84:87], v[144:147], v[176:179], v[84:87]
	v_mfma_f32_16x16x32_bf16 v[76:79], v[152:155], v[176:179], v[76:79]
	v_mfma_f32_16x16x32_bf16 v[68:71], v[144:147], v[204:207], v[68:71]
	v_mfma_f32_16x16x32_bf16 v[64:67], v[152:155], v[204:207], v[64:67]
	v_mfma_f32_16x16x32_bf16 v[124:127], v[132:135], v[164:167], v[124:127]
	v_mfma_f32_16x16x32_bf16 v[120:123], v[140:143], v[164:167], v[120:123]
	v_mfma_f32_16x16x32_bf16 v[112:115], v[132:135], v[172:175], v[112:115]
	v_mfma_f32_16x16x32_bf16 v[104:107], v[140:143], v[172:175], v[104:107]
	v_mfma_f32_16x16x32_bf16 v[96:99], v[132:135], v[180:183], v[96:99]
	v_mfma_f32_16x16x32_bf16 v[88:91], v[140:143], v[180:183], v[88:91]
	v_mfma_f32_16x16x32_bf16 v[80:83], v[132:135], v[208:211], v[80:83]
	v_mfma_f32_16x16x32_bf16 v[72:75], v[140:143], v[208:211], v[72:75]
	v_mfma_f32_16x16x32_bf16 v[116:119], v[148:151], v[164:167], v[116:119]
	v_mfma_f32_16x16x32_bf16 v[108:111], v[156:159], v[164:167], v[108:111]
	v_mfma_f32_16x16x32_bf16 v[100:103], v[148:151], v[172:175], v[100:103]
	v_mfma_f32_16x16x32_bf16 v[92:95], v[156:159], v[172:175], v[92:95]
	v_mfma_f32_16x16x32_bf16 v[84:87], v[148:151], v[180:183], v[84:87]
	v_mfma_f32_16x16x32_bf16 v[76:79], v[156:159], v[180:183], v[76:79]
	v_mfma_f32_16x16x32_bf16 v[68:71], v[148:151], v[208:211], v[68:71]
	v_mfma_f32_16x16x32_bf16 v[64:67], v[156:159], v[208:211], v[64:67]
	s_barrier
; #define PG8_STAGE(bufoff, gbase, voff) do { _Pragma("unroll") for (int _i = 0; _i < 2; ++_i) \
;         __builtin_amdgcn_global_load_lds((const unsigned*)((const char*)(gbase) + (voff)[_i]), (PG8_LAS unsigned*)(lds + (bufoff) + ldsw + _i * 8192), 16, 0, 0); } while (0)
; #define PG8_LDA(dst, b, h) do { _Pragma("unroll") for (int m = 0; m < 4; ++m) _Pragma("unroll") for (int k = 0; k < 2; ++k) dst[m][k] = *(const PG8_LAS bf16x8*)(lds + PG8_SA(b, h) + aoff + m * 2048 + k * 1024); } while (0)
; #define PG8_MMA(ai, bj, At, Bt) do { _Pragma("unroll") for (int m = 0; m < 4; ++m) _Pragma("unroll") for (int n = 0; n < 2; ++n) _Pragma("unroll") for (int k = 0; k < 2; ++k) \
;         acc[ai][bj][m][n] = __builtin_amdgcn_mfma_f32_16x16x32_bf16(Bt[n][k], At[m][k], acc[ai][bj][m][n], 0, 0, 0); } while (0)
; #define PG8_WAIT_V(n) asm volatile("s_waitcnt vmcnt(" #n ")" ::: "memory")
; #define PG8_WAIT_L(n) asm volatile("s_waitcnt lgkmcnt(" #n ")" ::: "memory")
; #define PG8_BAR __builtin_amdgcn_s_barrier()
; #define PG8_SCHED __builtin_amdgcn_sched_barrier(0)
; template <class Epi, class Sched, bool ALIGN_EPI = false, bool SP2 = false>
; __device__ __forceinline__ void gemm_phase(PG8_LAS unsigned char* lds, const Gemm g, const Sched& S, const Epi& E, const int wave_id_in) {
;     ...
;             PG8_LDA(At, 1, 1); PG8_STAGE(PG8_SB(1, 0), b3, voffB); PG8_STAGE(PG8_SB(1, 1), b3 + hstep, voffB); PG8_STAGE(PG8_SA(1, 0), a3, voffA);
;             PG8_WAIT_V(8); PG8_WAIT_L(0); PG8_BAR; __builtin_amdgcn_s_setprio(1); PG8_MMA(1, 0, At, B0); PG8_MMA(1, 1, At, B1); __builtin_amdgcn_s_setprio(0); PG8_BAR; PG8_SCHED;
;     ...
;         if constexpr (ALIGN_EPI) { if (wr == 0) PG8_BAR; }
	s_add_i32 s22, s59, s34
	v_lshl_add_u64 v[212:213], v[212:213], 0, s[8:9]
	s_mov_b32 m0, s22
	ds_read_b128 v[160:163], v203 offset:49152
	ds_read_b128 v[164:167], v203 offset:50176
	ds_read_b128 v[168:171], v203 offset:51200
	ds_read_b128 v[172:175], v203 offset:52224
	ds_read_b128 v[176:179], v203 offset:53248
	ds_read_b128 v[180:183], v203 offset:54272
	ds_read_b128 v[204:207], v203 offset:55296
	ds_read_b128 v[208:211], v203 offset:56320
	global_load_lds_dwordx4 v[212:213], off
	s_add_i32 m0, s22, 0x2000
	s_add_u32 s22, s26, 0x160080
	v_lshl_add_u64 v[212:213], v[214:215], 0, s[8:9]
	s_addc_u32 s23, s27, 0
	s_add_i32 s26, s60, s34
	global_load_lds_dwordx4 v[212:213], off
	v_lshl_add_u64 v[212:213], s[22:23], 0, v[186:187]
	s_mov_b32 m0, s26
	s_nop 0
	global_load_lds_dwordx4 v[212:213], off
	v_lshl_add_u64 v[212:213], s[22:23], 0, v[190:191]
	s_add_i32 m0, s26, 0x2000
	s_nop 0
	global_load_lds_dwordx4 v[212:213], off
	v_lshl_add_u64 v[212:213], v[216:217], 0, s[8:9]
	s_mov_b32 m0, s41
	s_nop 0
	global_load_lds_dwordx4 v[212:213], off
	v_lshl_add_u64 v[212:213], v[218:219], 0, s[8:9]
	s_mov_b32 m0, s42
	s_nop 0
	global_load_lds_dwordx4 v[212:213], off
	s_waitcnt vmcnt(8)
	s_waitcnt lgkmcnt(0)
	s_barrier
	v_mfma_f32_16x16x32_bf16 v[60:63], v[128:131], v[160:163], v[60:63]
	v_mfma_f32_16x16x32_bf16 v[56:59], v[136:139], v[160:163], v[56:59]
	v_mfma_f32_16x16x32_bf16 v[48:51], v[128:131], v[168:171], v[48:51]
	v_mfma_f32_16x16x32_bf16 v[40:43], v[136:139], v[168:171], v[40:43]
	v_mfma_f32_16x16x32_bf16 v[32:35], v[128:131], v[176:179], v[32:35]
	v_mfma_f32_16x16x32_bf16 v[24:27], v[136:139], v[176:179], v[24:27]
	v_mfma_f32_16x16x32_bf16 v[16:19], v[128:131], v[204:207], v[16:19]
	v_mfma_f32_16x16x32_bf16 v[8:11], v[136:139], v[204:207], v[8:11]
	v_mfma_f32_16x16x32_bf16 v[52:55], v[144:147], v[160:163], v[52:55]
	v_mfma_f32_16x16x32_bf16 v[44:47], v[152:155], v[160:163], v[44:47]
	v_mfma_f32_16x16x32_bf16 v[36:39], v[144:147], v[168:171], v[36:39]
	v_mfma_f32_16x16x32_bf16 v[28:31], v[152:155], v[168:171], v[28:31]
	v_mfma_f32_16x16x32_bf16 v[20:23], v[144:147], v[176:179], v[20:23]
	v_mfma_f32_16x16x32_bf16 v[12:15], v[152:155], v[176:179], v[12:15]
	v_mfma_f32_16x16x32_bf16 v[4:7], v[144:147], v[204:207], v[4:7]
	v_mfma_f32_16x16x32_bf16 v[0:3], v[152:155], v[204:207], v[0:3]
	v_mfma_f32_16x16x32_bf16 v[60:63], v[132:135], v[164:167], v[60:63]
	v_mfma_f32_16x16x32_bf16 v[56:59], v[140:143], v[164:167], v[56:59]
	v_mfma_f32_16x16x32_bf16 v[48:51], v[132:135], v[172:175], v[48:51]
	v_mfma_f32_16x16x32_bf16 v[40:43], v[140:143], v[172:175], v[40:43]
	v_mfma_f32_16x16x32_bf16 v[32:35], v[132:135], v[180:183], v[32:35]
	v_mfma_f32_16x16x32_bf16 v[24:27], v[140:143], v[180:183], v[24:27]
	v_mfma_f32_16x16x32_bf16 v[16:19], v[132:135], v[208:211], v[16:19]
	v_mfma_f32_16x16x32_bf16 v[8:11], v[140:143], v[208:211], v[8:11]
	v_mfma_f32_16x16x32_bf16 v[52:55], v[148:151], v[164:167], v[52:55]
	v_mfma_f32_16x16x32_bf16 v[44:47], v[156:159], v[164:167], v[44:47]
	v_mfma_f32_16x16x32_bf16 v[36:39], v[148:151], v[172:175], v[36:39]
	v_mfma_f32_16x16x32_bf16 v[28:31], v[156:159], v[172:175], v[28:31]
	v_mfma_f32_16x16x32_bf16 v[20:23], v[148:151], v[180:183], v[20:23]
	v_mfma_f32_16x16x32_bf16 v[12:15], v[156:159], v[180:183], v[12:15]
	v_mfma_f32_16x16x32_bf16 v[4:7], v[148:151], v[208:211], v[4:7]
	v_mfma_f32_16x16x32_bf16 v[0:3], v[156:159], v[208:211], v[0:3]
	s_add_i32 s55, s55, 2
	s_add_u32 s53, s53, 0x100
	s_addc_u32 s54, s54, 0
	s_cmpk_gt_u32 s55, 0x55
	s_mov_b64 s[22:23], s[24:25]
	s_barrier
	s_cbranch_scc0 .LBB0_1022
	s_and_b64 vcc, exec, s[10:11]
	s_cbranch_vccz .LBB0_1025
	s_barrier
